# softmax row-sum add chains split into two independent accumulators (dependency distance 2) in 11 attention blocks
# speedup vs baseline: 1.0066x; 1.0025x over previous
; __device__ __forceinline__ void finishSM(f32x16& p0, f32x16& p1, float& l_reg, bf16x8& pa0, bf16x8& pa1, bf16x8& pa2, bf16x8& pa3) {
; #pragma unroll
;   for (int r = 0; r < 16; ++r) p1[r] = __builtin_amdgcn_exp2f(p1[r]);
;   float ps = 0;
; #pragma unroll
;   for (int r = 0; r < 16; ++r) ps += p0[r];
; #pragma unroll
;   for (int r = 0; r < 16; ++r) ps += p1[r];
;   { auto rr = __builtin_amdgcn_permlane32_swap(__float_as_uint(ps), __float_as_uint(ps), false, false);
;     ps = __uint_as_float(rr[0]) + __uint_as_float(rr[1]); }
;   l_reg += ps;
;     ...
;   PK4(p0, 0, pa0); PK4(p0, 8, pa1); PK4(p1, 0, pa2); PK4(p1, 8, pa3);
;     ...
; }
; template <int DQK, int QL>
; __device__ __forceinline__ void qkt(f32x16& p0, f32x16& p1, const char* Ks, const bf16x8 (&qr)[DQK / 16 - QL], const char* qlds, const int (&kofs)[4], float negM) {
;   constexpr int QR = DQK / 16 - QL;
; #pragma unroll
;   for (int r = 0; r < 16; ++r) { p0[r] = negM; p1[r] = negM; }
; #pragma unroll
;   for (int d0 = 0; d0 < DQK / 16; ++d0) {
;     const char* kp = Ks + kofs[d0 & 3] + (d0 >> 2) * 128;
;     bf16x8 b0 = *reinterpret_cast<const bf16x8*>(kp);
;     bf16x8 b1 = *reinterpret_cast<const bf16x8*>(kp + 32 * DQK * 2);
;     bf16x8 qf;
;     if constexpr (QL > 0) { if (d0 < QR) qf = qr[d0 < QR ? d0 : 0]; else qf = *reinterpret_cast<const bf16x8*>(qlds + (d0 - QR) * 1024); }
;     else qf = qr[d0];
;     p0 = __builtin_amdgcn_mfma_f32_32x32x16_bf16(b0, qf, p0, 0, 0, 0);
;     p1 = __builtin_amdgcn_mfma_f32_32x32x16_bf16(b1, qf, p1, 0, 0, 0);
;   }
; }
; template <int NCB> __device__ __forceinline__ int v_st(int k, int c) {
;   const int kk = (k & ~0xC) | ((k & 4) << 1) | ((k & 8) >> 1);
;   return ((kk >> 3) * NCB + (c >> 5)) * 512 + ((kk & 7) * 32 + (c & 31)) * 2;
; }
; __device__ __forceinline__ int v_rd_base(int lane) { return ((lane & 3) << 3) | (((lane >> 2) & 3) << 6) | (((lane >> 4) & 1) << 5) | (((lane >> 5) & 1) << 8); }
; template <int OFF> __device__ __forceinline__ s16x4 tr_read(int vb) {
;   s16x4 r; asm volatile("ds_read_b64_tr_b16 %0, %1 offset:%2" : "=&v"(r) : "v"(vb), "i"(OFF) : "memory"); return r;
; }
; template <int NCB, int D0> __device__ __forceinline__ void pv_one(f32x16& od, int vb, bf16x8 pa0, bf16x8 pa1, bf16x8 pa2, bf16x8 pa3) {
;   constexpr int KSTEP = NCB * 1024, HALF = NCB * 512, B0 = D0 * 512;
.LBB0_323:
	ds_read_b128 v[96:99], v174 offset:40960
	ds_read_b128 v[182:185], v174 offset:45056
	v_exp_f32_e32 v100, v68
	v_exp_f32_e32 v101, v69
	s_waitcnt lgkmcnt(1)
	v_mfma_f32_32x32x16_bf16 v[80:95], v[96:99], v[142:145], v[238:253]
	ds_read_b128 v[96:99], v175 offset:40960
	ds_read_b128 v[186:189], v175 offset:45056
	v_exp_f32_e32 v102, v70
	v_exp_f32_e32 v103, v71
	v_exp_f32_e32 v104, v72
	v_exp_f32_e32 v105, v73
	v_exp_f32_e32 v106, v74
	v_exp_f32_e32 v107, v75
	s_waitcnt lgkmcnt(1)
	v_mfma_f32_32x32x16_bf16 v[80:95], v[96:99], v[138:141], v[80:95]
	ds_read_b128 v[96:99], v173 offset:40960
	ds_read_b128 v[190:193], v173 offset:45056
	v_exp_f32_e32 v108, v76
	v_exp_f32_e32 v109, v77
	v_exp_f32_e32 v110, v78
	v_exp_f32_e32 v79, v79
	s_waitcnt lgkmcnt(1)
	v_mfma_f32_32x32x16_bf16 v[80:95], v[96:99], v[134:137], v[80:95]
	ds_read_b128 v[96:99], v176 offset:40960
	ds_read_b128 v[194:197], v176 offset:45056
	s_waitcnt lgkmcnt(1)
	v_mfma_f32_32x32x16_bf16 v[80:95], v[96:99], v[130:133], v[80:95]
	v_exp_f32_e32 v96, v64
	v_add_f32_e32 v64, 0, v165
	v_add_f32_e32 v64, v157, v64
	v_add_f32_e32 v180, v167, v166
	v_add_f32_e32 v64, v155, v64
	v_add_f32_e32 v180, v164, v180
	v_add_f32_e32 v64, v154, v64
	v_add_f32_e32 v180, v156, v180
	v_add_f32_e32 v64, v151, v64
	v_add_f32_e32 v180, v153, v180
	v_add_f32_e32 v64, v149, v64
	v_add_f32_e32 v180, v152, v180
	v_add_f32_e32 v64, v147, v64
	v_exp_f32_e32 v97, v65
	v_add_f32_e32 v180, v150, v180
	v_exp_f32_e32 v98, v66
	v_add_f32_e32 v64, v146, v64
	v_exp_f32_e32 v99, v67
	v_add_f32_e32 v180, v148, v180
	v_add_f32_e32 v64, v96, v64
	v_add_f32_e32 v180, v97, v180
	v_add_f32_e32 v64, v98, v64
	v_add_f32_e32 v180, v99, v180
	v_add_f32_e32 v64, v100, v64
	v_add_f32_e32 v180, v101, v180
	v_add_f32_e32 v64, v102, v64
	v_add_f32_e32 v180, v103, v180
	v_add_f32_e32 v64, v104, v64
	v_add_f32_e32 v180, v105, v180
	v_add_f32_e32 v64, v106, v64
	v_add_f32_e32 v180, v107, v180
	v_add_f32_e32 v64, v108, v64
	v_add_f32_e32 v180, v109, v180
	v_add_f32_e32 v64, v110, v64
	v_add_f32_e32 v180, v79, v180
	v_add_f32_e32 v180, v64, v180
	v_mov_b32_e32 v181, v180
	s_nop 1
	v_permlane32_swap_b32_e32 v180, v181
	v_cvt_pk_bf16_f32 v64, v165, v167
	v_cvt_pk_bf16_f32 v65, v157, v166
	v_cvt_pk_bf16_f32 v66, v155, v164
	v_cvt_pk_bf16_f32 v67, v154, v156
	v_cvt_pk_bf16_f32 v68, v151, v153
	v_cvt_pk_bf16_f32 v69, v149, v152
	v_cvt_pk_bf16_f32 v70, v147, v150
	v_cvt_pk_bf16_f32 v71, v146, v148
	v_cvt_pk_bf16_f32 v72, v96, v97
	v_cvt_pk_bf16_f32 v73, v98, v99
	v_cvt_pk_bf16_f32 v74, v100, v101
	v_cvt_pk_bf16_f32 v75, v102, v103
	v_cvt_pk_bf16_f32 v76, v104, v105
	v_cvt_pk_bf16_f32 v77, v106, v107
	v_cvt_pk_bf16_f32 v78, v108, v109
	v_cvt_pk_bf16_f32 v79, v110, v79
	s_nop 0
	v_permlane32_swap_b32_e32 v64, v66
	v_permlane32_swap_b32_e32 v65, v67
	v_permlane32_swap_b32_e32 v68, v70
	v_permlane32_swap_b32_e32 v69, v71
	v_permlane32_swap_b32_e32 v72, v74
	v_permlane32_swap_b32_e32 v73, v75
	v_permlane32_swap_b32_e32 v76, v78
	v_permlane32_swap_b32_e32 v77, v79
	v_mfma_f32_32x32x16_bf16 v[96:111], v[182:185], v[142:145], v[238:253]
	v_mfma_f32_32x32x16_bf16 v[96:111], v[186:189], v[138:141], v[96:111]
	s_add_u32 s100, s80, 0x590c000
	s_addc_u32 s101, s81, 0
	global_load_dwordx4 v[146:149], v158, s[100:101] offset:1280
	global_load_dwordx4 v[150:153], v160, s[100:101] offset:2304
	v_mfma_f32_32x32x16_bf16 v[96:111], v[190:193], v[134:137], v[96:111]
	global_load_dwordx4 v[154:157], v162, s[100:101] offset:2304
	s_waitcnt lgkmcnt(0)
	v_mfma_f32_32x32x16_bf16 v[96:111], v[194:197], v[130:133], v[96:111]
	ds_read_b64_tr_b16 v[112:113], v172 offset:0
	ds_read_b64_tr_b16 v[114:115], v172 offset:0x800
	ds_read_b64_tr_b16 v[116:117], v172 offset:0x1000
	ds_read_b64_tr_b16 v[118:119], v172 offset:0x1800
	ds_read_b64_tr_b16 v[120:121], v172 offset:0x2000
	ds_read_b64_tr_b16 v[122:123], v172 offset:0x2800
	ds_read_b64_tr_b16 v[124:125], v172 offset:0x3000
	ds_read_b64_tr_b16 v[126:127], v172 offset:0x3800
	s_nop 0
	s_waitcnt lgkmcnt(6)
	v_mfma_f32_32x32x16_bf16 v[0:15], v[64:67], v[112:115], v[0:15]
	ds_read_b64_tr_b16 v[112:113], v172 offset:0x200
	ds_read_b64_tr_b16 v[114:115], v172 offset:0xa00
	s_waitcnt lgkmcnt(6)
	v_mfma_f32_32x32x16_bf16 v[0:15], v[68:71], v[116:119], v[0:15]
	ds_read_b64_tr_b16 v[116:117], v172 offset:0x1200
	ds_read_b64_tr_b16 v[118:119], v172 offset:0x1a00
	s_waitcnt lgkmcnt(6)
	v_mfma_f32_32x32x16_bf16 v[0:15], v[72:75], v[120:123], v[0:15]
	ds_read_b64_tr_b16 v[120:121], v172 offset:0x2200
	ds_read_b64_tr_b16 v[122:123], v172 offset:0x2a00
	s_waitcnt lgkmcnt(6)
	v_mfma_f32_32x32x16_bf16 v[0:15], v[76:79], v[124:127], v[0:15]
	ds_read_b64_tr_b16 v[124:125], v172 offset:0x3200
	ds_read_b64_tr_b16 v[126:127], v172 offset:0x3a00
	s_waitcnt lgkmcnt(6)
	v_mfma_f32_32x32x16_bf16 v[16:31], v[64:67], v[112:115], v[16:31]
	ds_read_b64_tr_b16 v[112:113], v172 offset:0x400
	ds_read_b64_tr_b16 v[114:115], v172 offset:0xc00
	s_waitcnt lgkmcnt(6)
	v_mfma_f32_32x32x16_bf16 v[16:31], v[68:71], v[116:119], v[16:31]
	ds_read_b64_tr_b16 v[116:117], v172 offset:0x1400
	ds_read_b64_tr_b16 v[118:119], v172 offset:0x1c00
	s_waitcnt lgkmcnt(6)
	v_mfma_f32_32x32x16_bf16 v[16:31], v[72:75], v[120:123], v[16:31]
	ds_read_b64_tr_b16 v[120:121], v172 offset:0x2400
	ds_read_b64_tr_b16 v[122:123], v172 offset:0x2c00
	s_waitcnt lgkmcnt(6)
	v_mfma_f32_32x32x16_bf16 v[16:31], v[76:79], v[124:127], v[16:31]
	ds_read_b64_tr_b16 v[124:125], v172 offset:0x3400
	ds_read_b64_tr_b16 v[126:127], v172 offset:0x3c00
	s_waitcnt lgkmcnt(6)
	v_mfma_f32_32x32x16_bf16 v[32:47], v[64:67], v[112:115], v[32:47]
	ds_read_b64_tr_b16 v[112:113], v172 offset:0x600
	ds_read_b64_tr_b16 v[114:115], v172 offset:0xe00
	s_waitcnt lgkmcnt(6)
	v_mfma_f32_32x32x16_bf16 v[32:47], v[68:71], v[116:119], v[32:47]
	ds_read_b64_tr_b16 v[116:117], v172 offset:0x1600
	ds_read_b64_tr_b16 v[118:119], v172 offset:0x1e00
	s_waitcnt lgkmcnt(6)
	v_mfma_f32_32x32x16_bf16 v[32:47], v[72:75], v[120:123], v[32:47]
	ds_read_b64_tr_b16 v[120:121], v172 offset:0x2600
	ds_read_b64_tr_b16 v[122:123], v172 offset:0x2e00
	s_waitcnt lgkmcnt(6)
	v_mfma_f32_32x32x16_bf16 v[32:47], v[76:79], v[124:127], v[32:47]
	ds_read_b64_tr_b16 v[124:125], v172 offset:0x3600
	ds_read_b64_tr_b16 v[126:127], v172 offset:0x3e00
	s_waitcnt lgkmcnt(6)
	v_mfma_f32_32x32x16_bf16 v[48:63], v[64:67], v[112:115], v[48:63]
	s_add_i32 s20, s36, 64
	s_cmp_le_i32 s20, s59
	v_add_u32_e32 v182, s36, v171
	s_waitcnt lgkmcnt(4)
	v_mfma_f32_32x32x16_bf16 v[48:63], v[68:71], v[116:119], v[48:63]
	s_waitcnt lgkmcnt(2)
	v_mfma_f32_32x32x16_bf16 v[48:63], v[72:75], v[120:123], v[48:63]
	s_waitcnt lgkmcnt(0)
	v_mfma_f32_32x32x16_bf16 v[48:63], v[76:79], v[124:127], v[48:63]
	s_cbranch_scc1 .LBB0_325
; __device__ __forceinline__ int crow(int r, int hi) { return (r & 3) + 8 * (r >> 2) + 4 * hi; }
; template <bool GM>
; __device__ __forceinline__ void partialSM(f32x16& p0, f32x16& p1, bool mask, int kbase, int L, int qpos, int hi) {
;   if (mask) {
; #pragma unroll
;     for (int r = 0; r < 16; ++r) {
;       int k = kbase + crow(r, hi);
;       asm volatile("" : "+v"(k) : "v"(p0[r]));
;       bool ok = k < L;
;       if (GM) ok = ok && (k < 16 || abs(qpos - k) <= 128);
;       p0[r] = ok ? p0[r] : -1e30f;
;       int k2 = k + 32;
;       asm volatile("" : "+v"(k2) : "v"(p1[r]));
;       bool ok2 = k2 < L;
;       if (GM) ok2 = ok2 && (k2 < 16 || abs(qpos - k2) <= 128);
;       p1[r] = ok2 ? p1[r] : -1e30f;
;     }
;   }
	v_add_u32_e32 v64, 64, v182
	s_nop 0
	v_cmp_gt_i32_e32 vcc, s94, v64
	v_add_u32_e32 v64, 32, v64
	s_nop 0
	v_cndmask_b32_e32 v80, v233, v80, vcc
	v_cmp_gt_i32_e32 vcc, s94, v64
	v_add_u32_e32 v64, 0x41, v182
	s_nop 0
	v_cndmask_b32_e32 v96, v233, v96, vcc
	v_cmp_gt_i32_e32 vcc, s94, v64
	v_add_u32_e32 v64, 32, v64
	s_nop 0
	v_cndmask_b32_e32 v81, v233, v81, vcc
	v_cmp_gt_i32_e32 vcc, s94, v64
	v_add_u32_e32 v64, 0x42, v182
	s_nop 0
	v_cndmask_b32_e32 v97, v233, v97, vcc
	v_cmp_gt_i32_e32 vcc, s94, v64
	v_add_u32_e32 v64, 32, v64
	s_nop 0
	v_cndmask_b32_e32 v82, v233, v82, vcc
	v_cmp_gt_i32_e32 vcc, s94, v64
	v_add_u32_e32 v64, 0x43, v182
	s_nop 0
	v_cndmask_b32_e32 v98, v233, v98, vcc
	v_cmp_gt_i32_e32 vcc, s94, v64
	v_add_u32_e32 v64, 32, v64
	s_nop 0
	v_cndmask_b32_e32 v83, v233, v83, vcc
	v_cmp_gt_i32_e32 vcc, s94, v64
	v_add_u32_e32 v64, 0x48, v182
	s_nop 0
	v_cndmask_b32_e32 v99, v233, v99, vcc
	v_cmp_gt_i32_e32 vcc, s94, v64
	v_add_u32_e32 v64, 32, v64
	s_nop 0
	v_cndmask_b32_e32 v84, v233, v84, vcc
	v_cmp_gt_i32_e32 vcc, s94, v64
	v_add_u32_e32 v64, 0x49, v182
	s_nop 0
	v_cndmask_b32_e32 v100, v233, v100, vcc
	v_cmp_gt_i32_e32 vcc, s94, v64
	v_add_u32_e32 v64, 32, v64
	s_nop 0
	v_cndmask_b32_e32 v85, v233, v85, vcc
	v_cmp_gt_i32_e32 vcc, s94, v64
	v_add_u32_e32 v64, 0x4a, v182
	s_nop 0
	v_cndmask_b32_e32 v101, v233, v101, vcc
	v_cmp_gt_i32_e32 vcc, s94, v64
	v_add_u32_e32 v64, 32, v64
	s_nop 0
	v_cndmask_b32_e32 v86, v233, v86, vcc
	v_cmp_gt_i32_e32 vcc, s94, v64
	v_add_u32_e32 v64, 0x4b, v182
	s_nop 0
	v_cndmask_b32_e32 v102, v233, v102, vcc
	v_cmp_gt_i32_e32 vcc, s94, v64
	v_add_u32_e32 v64, 32, v64
	s_nop 0
	v_cndmask_b32_e32 v87, v233, v87, vcc
	v_cmp_gt_i32_e32 vcc, s94, v64
	v_add_u32_e32 v64, 0x50, v182
	s_nop 0
	v_cndmask_b32_e32 v103, v233, v103, vcc
	v_cmp_gt_i32_e32 vcc, s94, v64
	v_add_u32_e32 v64, 32, v64
	s_nop 0
	v_cndmask_b32_e32 v88, v233, v88, vcc
	v_cmp_gt_i32_e32 vcc, s94, v64
	v_add_u32_e32 v64, 0x51, v182
	s_nop 0
	v_cndmask_b32_e32 v104, v233, v104, vcc
	v_cmp_gt_i32_e32 vcc, s94, v64
	v_add_u32_e32 v64, 32, v64
	s_nop 0
	v_cndmask_b32_e32 v89, v233, v89, vcc
	v_cmp_gt_i32_e32 vcc, s94, v64
	v_add_u32_e32 v64, 0x52, v182
	s_nop 0
	v_cndmask_b32_e32 v105, v233, v105, vcc
	v_cmp_gt_i32_e32 vcc, s94, v64
	v_add_u32_e32 v64, 32, v64
	s_nop 0
	v_cndmask_b32_e32 v90, v233, v90, vcc
	v_cmp_gt_i32_e32 vcc, s94, v64
	v_add_u32_e32 v64, 0x53, v182
	s_nop 0
	v_cndmask_b32_e32 v106, v233, v106, vcc
	v_cmp_gt_i32_e32 vcc, s94, v64
	v_add_u32_e32 v64, 32, v64
	s_nop 0
	v_cndmask_b32_e32 v91, v233, v91, vcc
	v_cmp_gt_i32_e32 vcc, s94, v64
	v_add_u32_e32 v64, 0x58, v182
	s_nop 0
	v_cndmask_b32_e32 v107, v233, v107, vcc
	v_cmp_gt_i32_e32 vcc, s94, v64
	v_add_u32_e32 v64, 32, v64
	s_nop 0
	v_cndmask_b32_e32 v92, v233, v92, vcc
	v_cmp_gt_i32_e32 vcc, s94, v64
	v_add_u32_e32 v64, 0x59, v182
	s_nop 0
	v_cndmask_b32_e32 v108, v233, v108, vcc
	v_cmp_gt_i32_e32 vcc, s94, v64
	v_add_u32_e32 v64, 32, v64
	s_nop 0
	v_cndmask_b32_e32 v93, v233, v93, vcc
	v_cmp_gt_i32_e32 vcc, s94, v64
	v_add_u32_e32 v64, 0x5a, v182
	s_nop 0
	v_cndmask_b32_e32 v109, v233, v109, vcc
	v_cmp_gt_i32_e32 vcc, s94, v64
	v_add_u32_e32 v64, 32, v64
	s_nop 0
	v_cndmask_b32_e32 v94, v233, v94, vcc
	v_cmp_gt_i32_e32 vcc, s94, v64
	v_add_u32_e32 v64, 0x5b, v182
	s_nop 0
	v_cndmask_b32_e32 v110, v233, v110, vcc
	v_cmp_gt_i32_e32 vcc, s94, v64
	v_add_u32_e32 v64, 32, v64
	s_nop 0
	v_cndmask_b32_e32 v95, v233, v95, vcc
	v_cmp_gt_i32_e32 vcc, s94, v64
	s_nop 1
	v_cndmask_b32_e32 v111, v233, v111, vcc
; #define WAIT_V0() asm volatile("s_waitcnt vmcnt(0)" ::: "memory")
; #define SBAR() __builtin_amdgcn_sched_barrier(0)
; #define SWRITE(b) do { FRESH_COORDS(); \
;     if constexpr (!KDMA) { _Pragma("unroll") for (int i = 0; i < KC; ++i) *reinterpret_cast<bf16x8*>(shm + (b) * SHM_K + klo[i]) = ks[i]; } \
;     _Pragma("unroll") for (int i = 0; i < VC; ++i) *reinterpret_cast<bf16x8*>(shm + (b) * SHM_V + vlo[i]) = vs[i]; } while (0)
; #define QKT(P0, P1, BUF) qkt<DQK, QL>(P0, P1, shm + K_OFF + (BUF) * SHM_K, qr, qlds, kofs, negM)
; __device__ __forceinline__ void finishSM(f32x16& p0, f32x16& p1, float& l_reg, bf16x8& pa0, bf16x8& pa1, bf16x8& pa2, bf16x8& pa3) {
; #pragma unroll
;   for (int r = 0; r < 16; ++r) p1[r] = __builtin_amdgcn_exp2f(p1[r]);
;   float ps = 0;
; #pragma unroll
;   for (int r = 0; r < 16; ++r) ps += p0[r];
; #pragma unroll
;   for (int r = 0; r < 16; ++r) ps += p1[r];
;   { auto rr = __builtin_amdgcn_permlane32_swap(__float_as_uint(ps), __float_as_uint(ps), false, false);
;     ps = __uint_as_float(rr[0]) + __uint_as_float(rr[1]); }
;   l_reg += ps;
;     ...
;   PK4(p0, 0, pa0); PK4(p0, 8, pa1); PK4(p1, 0, pa2); PK4(p1, 8, pa3);
;     ...
; }
; template <int DQK, int QL>
; __device__ __forceinline__ void qkt(f32x16& p0, f32x16& p1, const char* Ks, const bf16x8 (&qr)[DQK / 16 - QL], const char* qlds, const int (&kofs)[4], float negM) {
;   constexpr int QR = DQK / 16 - QL;
; #pragma unroll
;   for (int r = 0; r < 16; ++r) { p0[r] = negM; p1[r] = negM; }
; #pragma unroll
;   for (int d0 = 0; d0 < DQK / 16; ++d0) {
;     const char* kp = Ks + kofs[d0 & 3] + (d0 >> 2) * 128;
;     bf16x8 b0 = *reinterpret_cast<const bf16x8*>(kp);
;     bf16x8 b1 = *reinterpret_cast<const bf16x8*>(kp + 32 * DQK * 2);
;     bf16x8 qf;
;     if constexpr (QL > 0) { if (d0 < QR) qf = qr[d0 < QR ? d0 : 0]; else qf = *reinterpret_cast<const bf16x8*>(qlds + (d0 - QR) * 1024); }
;     else qf = qr[d0];
;     p0 = __builtin_amdgcn_mfma_f32_32x32x16_bf16(b0, qf, p0, 0, 0, 0);
;     p1 = __builtin_amdgcn_mfma_f32_32x32x16_bf16(b1, qf, p1, 0, 0, 0);
;   }
;     ...
;     __syncthreads(); WAIT_V0(); SWRITE(0);
;     __syncthreads();
;     SBAR();
;     if constexpr (ONEP) { finishSM(pB0, pB1, l_reg, pa0, pa1, pa2, pa3); SBAR(); QKT(pA0, pA1, 0); }
;     else { QKT(pA0, pA1, 0); finishSM(pB0, pB1, l_reg, pa0, pa1, pa2, pa3); }
;     SBAR();
;     if (j + 2 < NT) SLOAD(TKEY(j + 2), 1);
.LBB0_325:
	s_barrier
	s_waitcnt vmcnt(0)
	s_waitcnt vmcnt(2)
	ds_write_b128 v179, v[146:149] offset:32768
	s_waitcnt vmcnt(1)
	ds_write_b128 v177, v[150:153]
	s_waitcnt vmcnt(0)
	ds_write_b128 v178, v[154:157]
	v_exp_f32_e32 v183, v80
	v_exp_f32_e32 v188, v81
	v_exp_f32_e32 v189, v82
	v_exp_f32_e32 v190, v83
	v_exp_f32_e32 v191, v84
	v_exp_f32_e32 v192, v85
	v_exp_f32_e32 v193, v86
	v_exp_f32_e32 v194, v87
	v_exp_f32_e32 v195, v88
	v_exp_f32_e32 v196, v89
	v_exp_f32_e32 v197, v90
	v_exp_f32_e32 v198, v91
	v_exp_f32_e32 v199, v92
	v_exp_f32_e32 v200, v93
	v_exp_f32_e32 v201, v94
	v_exp_f32_e32 v202, v95
	s_waitcnt lgkmcnt(0)
	s_barrier
	ds_read_b128 v[64:67], v174 offset:32768
	ds_read_b128 v[184:187], v174 offset:36864
	v_exp_f32_e32 v111, v111
	s_waitcnt lgkmcnt(1)
	v_mfma_f32_32x32x16_bf16 v[80:95], v[64:67], v[142:145], v[238:253]
	s_waitcnt lgkmcnt(0)
	v_mfma_f32_32x32x16_bf16 v[64:79], v[184:187], v[142:145], v[238:253]
	ds_read_b128 v[112:115], v175 offset:32768
	ds_read_b128 v[116:119], v175 offset:36864
	v_exp_f32_e32 v120, v102
	v_exp_f32_e32 v121, v103
	v_exp_f32_e32 v122, v104
	v_exp_f32_e32 v123, v105
	v_exp_f32_e32 v124, v106
	v_exp_f32_e32 v125, v107
	s_waitcnt lgkmcnt(1)
	v_mfma_f32_32x32x16_bf16 v[80:95], v[112:115], v[138:141], v[80:95]
	v_exp_f32_e32 v126, v108
	v_exp_f32_e32 v127, v109
	v_exp_f32_e32 v184, v110
	s_waitcnt lgkmcnt(0)
	v_mfma_f32_32x32x16_bf16 v[64:79], v[116:119], v[138:141], v[64:79]
	ds_read_b128 v[112:115], v173 offset:32768
	ds_read_b128 v[116:119], v173 offset:36864
	s_waitcnt lgkmcnt(1)
	v_mfma_f32_32x32x16_bf16 v[80:95], v[112:115], v[134:137], v[80:95]
	s_waitcnt lgkmcnt(0)
	v_mfma_f32_32x32x16_bf16 v[64:79], v[116:119], v[134:137], v[64:79]
	ds_read_b128 v[112:115], v176 offset:32768
	ds_read_b128 v[116:119], v176 offset:36864
	s_waitcnt lgkmcnt(1)
	v_mfma_f32_32x32x16_bf16 v[80:95], v[112:115], v[130:133], v[80:95]
	v_exp_f32_e32 v114, v96
	v_add_f32_e32 v96, 0, v183
	v_add_f32_e32 v96, v189, v96
	v_add_f32_e32 v112, v188, v190
	v_add_f32_e32 v96, v191, v96
	v_add_f32_e32 v112, v192, v112
	v_add_f32_e32 v96, v193, v96
	v_add_f32_e32 v112, v194, v112
	v_add_f32_e32 v96, v195, v96
	v_add_f32_e32 v112, v196, v112
	v_add_f32_e32 v96, v197, v96
	v_add_f32_e32 v112, v198, v112
	v_add_f32_e32 v96, v199, v96
	v_exp_f32_e32 v115, v97
	v_add_f32_e32 v112, v200, v112
	s_waitcnt lgkmcnt(0)
	v_mfma_f32_32x32x16_bf16 v[64:79], v[116:119], v[130:133], v[64:79]
	v_exp_f32_e32 v116, v98
	v_add_f32_e32 v96, v201, v96
	v_exp_f32_e32 v117, v99
	v_add_f32_e32 v112, v202, v112
	v_exp_f32_e32 v118, v100
	v_add_f32_e32 v96, v114, v96
	v_exp_f32_e32 v119, v101
	v_add_f32_e32 v112, v115, v112
	v_add_f32_e32 v96, v116, v96
	v_add_f32_e32 v112, v117, v112
	v_add_f32_e32 v96, v118, v96
	v_add_f32_e32 v112, v119, v112
	v_add_f32_e32 v96, v120, v96
	v_add_f32_e32 v112, v121, v112
	v_add_f32_e32 v96, v122, v96
	v_add_f32_e32 v112, v123, v112
	v_add_f32_e32 v96, v124, v96
	v_add_f32_e32 v112, v125, v112
	v_add_f32_e32 v96, v126, v96
	v_add_f32_e32 v112, v127, v112
	v_add_f32_e32 v96, v184, v96
	v_add_f32_e32 v112, v111, v112
	v_add_f32_e32 v112, v96, v112
	v_mov_b32_e32 v113, v112
	v_cvt_pk_bf16_f32 v96, v183, v188
	v_cvt_pk_bf16_f32 v97, v189, v190
	v_cvt_pk_bf16_f32 v98, v191, v192
	v_cvt_pk_bf16_f32 v99, v193, v194
	v_cvt_pk_bf16_f32 v100, v195, v196
	v_cvt_pk_bf16_f32 v101, v197, v198
	v_cvt_pk_bf16_f32 v102, v199, v200
	v_cvt_pk_bf16_f32 v103, v201, v202
	v_cvt_pk_bf16_f32 v104, v114, v115
	v_cvt_pk_bf16_f32 v105, v116, v117
	v_cvt_pk_bf16_f32 v106, v118, v119
	v_cvt_pk_bf16_f32 v107, v120, v121
	v_cvt_pk_bf16_f32 v108, v122, v123
	v_cvt_pk_bf16_f32 v109, v124, v125
	v_cvt_pk_bf16_f32 v110, v126, v127
	v_cvt_pk_bf16_f32 v111, v184, v111
	s_nop 1
	v_permlane32_swap_b32_e32 v112, v113
	v_permlane32_swap_b32_e32 v96, v98
	v_permlane32_swap_b32_e32 v97, v99
	v_permlane32_swap_b32_e32 v100, v102
	v_permlane32_swap_b32_e32 v101, v103
	v_permlane32_swap_b32_e32 v104, v106
	v_permlane32_swap_b32_e32 v105, v107
	v_permlane32_swap_b32_e32 v108, v110
	v_permlane32_swap_b32_e32 v109, v111
	s_cmp_lt_u32 s26, s58
	s_cselect_b64 s[22:23], -1, 0
	s_cmp_ge_u32 s26, s58
	s_cselect_b64 s[20:21], -1, 0
	s_and_b64 vcc, exec, s[20:21]
	s_cbranch_vccnz .LBB0_327
	s_add_u32 s100, s80, 0x593c000
	s_addc_u32 s101, s81, 0
	global_load_dwordx4 v[146:149], v158, s[100:101] offset:1280
	global_load_dwordx4 v[150:153], v160, s[100:101] offset:2304
	global_load_dwordx4 v[154:157], v162, s[100:101] offset:2304

; __device__ __forceinline__ void finishSM(f32x16& p0, f32x16& p1, float& l_reg, bf16x8& pa0, bf16x8& pa1, bf16x8& pa2, bf16x8& pa3) {
; #pragma unroll
;   for (int r = 0; r < 16; ++r) p1[r] = __builtin_amdgcn_exp2f(p1[r]);
;   float ps = 0;
; #pragma unroll
;   for (int r = 0; r < 16; ++r) ps += p0[r];
; #pragma unroll
;   for (int r = 0; r < 16; ++r) ps += p1[r];
;   { auto rr = __builtin_amdgcn_permlane32_swap(__float_as_uint(ps), __float_as_uint(ps), false, false);
;     ps = __uint_as_float(rr[0]) + __uint_as_float(rr[1]); }
;   l_reg += ps;
;     ...
;   PK4(p0, 0, pa0); PK4(p0, 8, pa1); PK4(p1, 0, pa2); PK4(p1, 8, pa3);
;     ...
; }
; template <int DQK, int QL>
; __device__ __forceinline__ void qkt(f32x16& p0, f32x16& p1, const char* Ks, const bf16x8 (&qr)[DQK / 16 - QL], const char* qlds, const int (&kofs)[4], float negM) {
;   constexpr int QR = DQK / 16 - QL;
; #pragma unroll
;   for (int r = 0; r < 16; ++r) { p0[r] = negM; p1[r] = negM; }
; #pragma unroll
;   for (int d0 = 0; d0 < DQK / 16; ++d0) {
;     const char* kp = Ks + kofs[d0 & 3] + (d0 >> 2) * 128;
;     bf16x8 b0 = *reinterpret_cast<const bf16x8*>(kp);
;     bf16x8 b1 = *reinterpret_cast<const bf16x8*>(kp + 32 * DQK * 2);
;     bf16x8 qf;
;     if constexpr (QL > 0) { if (d0 < QR) qf = qr[d0 < QR ? d0 : 0]; else qf = *reinterpret_cast<const bf16x8*>(qlds + (d0 - QR) * 1024); }
;     else qf = qr[d0];
;     p0 = __builtin_amdgcn_mfma_f32_32x32x16_bf16(b0, qf, p0, 0, 0, 0);
;     p1 = __builtin_amdgcn_mfma_f32_32x32x16_bf16(b1, qf, p1, 0, 0, 0);
;   }
; }
; template <int NCB> __device__ __forceinline__ int v_st(int k, int c) {
;   const int kk = (k & ~0xC) | ((k & 4) << 1) | ((k & 8) >> 1);
;   return ((kk >> 3) * NCB + (c >> 5)) * 512 + ((kk & 7) * 32 + (c & 31)) * 2;
; }
; __device__ __forceinline__ int v_rd_base(int lane) { return ((lane & 3) << 3) | (((lane >> 2) & 3) << 6) | (((lane >> 4) & 1) << 5) | (((lane >> 5) & 1) << 8); }
; template <int OFF> __device__ __forceinline__ s16x4 tr_read(int vb) {
;   s16x4 r; asm volatile("ds_read_b64_tr_b16 %0, %1 offset:%2" : "=&v"(r) : "v"(vb), "i"(OFF) : "memory"); return r;
; }
; template <int NCB, int D0> __device__ __forceinline__ void pv_one(f32x16& od, int vb, bf16x8 pa0, bf16x8 pa1, bf16x8 pa2, bf16x8 pa3) {
;   constexpr int KSTEP = NCB * 1024, HALF = NCB * 512, B0 = D0 * 512;
.LBB0_342:
	ds_read_b128 v[96:99], v174 offset:40960
	ds_read_b128 v[182:185], v174 offset:45056
	v_exp_f32_e32 v100, v68
	v_exp_f32_e32 v101, v69
	s_waitcnt lgkmcnt(1)
	v_mfma_f32_32x32x16_bf16 v[80:95], v[96:99], v[142:145], v[238:253]
	ds_read_b128 v[96:99], v175 offset:40960
	ds_read_b128 v[186:189], v175 offset:45056
	v_exp_f32_e32 v102, v70
	v_exp_f32_e32 v103, v71
	v_exp_f32_e32 v104, v72
	v_exp_f32_e32 v105, v73
	v_exp_f32_e32 v106, v74
	v_exp_f32_e32 v107, v75
	s_waitcnt lgkmcnt(1)
	v_mfma_f32_32x32x16_bf16 v[80:95], v[96:99], v[138:141], v[80:95]
	ds_read_b128 v[96:99], v173 offset:40960
	ds_read_b128 v[190:193], v173 offset:45056
	v_exp_f32_e32 v108, v76
	v_exp_f32_e32 v109, v77
	v_exp_f32_e32 v110, v78
	v_exp_f32_e32 v79, v79
	s_waitcnt lgkmcnt(1)
	v_mfma_f32_32x32x16_bf16 v[80:95], v[96:99], v[134:137], v[80:95]
	ds_read_b128 v[96:99], v176 offset:40960
	ds_read_b128 v[194:197], v176 offset:45056
	s_waitcnt lgkmcnt(1)
	v_mfma_f32_32x32x16_bf16 v[80:95], v[96:99], v[130:133], v[80:95]
	v_exp_f32_e32 v96, v64
	v_add_f32_e32 v64, 0, v165
	v_add_f32_e32 v64, v157, v64
	v_add_f32_e32 v180, v167, v166
	v_add_f32_e32 v64, v155, v64
	v_add_f32_e32 v180, v164, v180
	v_add_f32_e32 v64, v154, v64
	v_add_f32_e32 v180, v156, v180
	v_add_f32_e32 v64, v151, v64
	v_add_f32_e32 v180, v153, v180
	v_add_f32_e32 v64, v149, v64
	v_add_f32_e32 v180, v152, v180
	v_add_f32_e32 v64, v147, v64
	v_exp_f32_e32 v97, v65
	v_add_f32_e32 v180, v150, v180
	v_exp_f32_e32 v98, v66
	v_add_f32_e32 v64, v146, v64
	v_exp_f32_e32 v99, v67
	v_add_f32_e32 v180, v148, v180
	v_add_f32_e32 v64, v96, v64
	v_add_f32_e32 v180, v97, v180
	v_add_f32_e32 v64, v98, v64
	v_add_f32_e32 v180, v99, v180
	v_add_f32_e32 v64, v100, v64
	v_add_f32_e32 v180, v101, v180
	v_add_f32_e32 v64, v102, v64
	v_add_f32_e32 v180, v103, v180
	v_add_f32_e32 v64, v104, v64
	v_add_f32_e32 v180, v105, v180
	v_add_f32_e32 v64, v106, v64
	v_add_f32_e32 v180, v107, v180
	v_add_f32_e32 v64, v108, v64
	v_add_f32_e32 v180, v109, v180
	v_add_f32_e32 v64, v110, v64
	v_add_f32_e32 v180, v79, v180
	v_add_f32_e32 v180, v64, v180
	v_mov_b32_e32 v181, v180
	s_nop 1
	v_permlane32_swap_b32_e32 v180, v181
	v_cvt_pk_bf16_f32 v64, v165, v167
	v_cvt_pk_bf16_f32 v65, v157, v166
	v_cvt_pk_bf16_f32 v66, v155, v164
	v_cvt_pk_bf16_f32 v67, v154, v156
	v_cvt_pk_bf16_f32 v68, v151, v153
	v_cvt_pk_bf16_f32 v69, v149, v152
	v_cvt_pk_bf16_f32 v70, v147, v150
	v_cvt_pk_bf16_f32 v71, v146, v148
	v_cvt_pk_bf16_f32 v72, v96, v97
	v_cvt_pk_bf16_f32 v73, v98, v99
	v_cvt_pk_bf16_f32 v74, v100, v101
	v_cvt_pk_bf16_f32 v75, v102, v103
	v_cvt_pk_bf16_f32 v76, v104, v105
	v_cvt_pk_bf16_f32 v77, v106, v107
	v_cvt_pk_bf16_f32 v78, v108, v109
	v_cvt_pk_bf16_f32 v79, v110, v79
	s_nop 0
	v_permlane32_swap_b32_e32 v64, v66
	v_permlane32_swap_b32_e32 v65, v67
	v_permlane32_swap_b32_e32 v68, v70
	v_permlane32_swap_b32_e32 v69, v71
	v_permlane32_swap_b32_e32 v72, v74
	v_permlane32_swap_b32_e32 v73, v75
	v_permlane32_swap_b32_e32 v76, v78
	v_permlane32_swap_b32_e32 v77, v79
	v_mfma_f32_32x32x16_bf16 v[96:111], v[182:185], v[142:145], v[238:253]
	v_mfma_f32_32x32x16_bf16 v[96:111], v[186:189], v[138:141], v[96:111]
	s_add_u32 s100, s0, 0x590c000
	s_addc_u32 s101, s1, 0
	global_load_dwordx4 v[146:149], v158, s[100:101] offset:1408
	global_load_dwordx4 v[150:153], v160, s[100:101] offset:2304
	v_mfma_f32_32x32x16_bf16 v[96:111], v[190:193], v[134:137], v[96:111]
	global_load_dwordx4 v[154:157], v162, s[100:101] offset:2304
	s_waitcnt lgkmcnt(0)
	v_mfma_f32_32x32x16_bf16 v[96:111], v[194:197], v[130:133], v[96:111]
	ds_read_b64_tr_b16 v[112:113], v172 offset:0
	ds_read_b64_tr_b16 v[114:115], v172 offset:0x800
	ds_read_b64_tr_b16 v[116:117], v172 offset:0x1000
	ds_read_b64_tr_b16 v[118:119], v172 offset:0x1800
	ds_read_b64_tr_b16 v[120:121], v172 offset:0x2000
	ds_read_b64_tr_b16 v[122:123], v172 offset:0x2800
	ds_read_b64_tr_b16 v[124:125], v172 offset:0x3000
	ds_read_b64_tr_b16 v[126:127], v172 offset:0x3800
	s_nop 0
	s_waitcnt lgkmcnt(6)
	v_mfma_f32_32x32x16_bf16 v[0:15], v[64:67], v[112:115], v[0:15]
	ds_read_b64_tr_b16 v[112:113], v172 offset:0x200
	ds_read_b64_tr_b16 v[114:115], v172 offset:0xa00
	s_waitcnt lgkmcnt(6)
	v_mfma_f32_32x32x16_bf16 v[0:15], v[68:71], v[116:119], v[0:15]
	ds_read_b64_tr_b16 v[116:117], v172 offset:0x1200
	ds_read_b64_tr_b16 v[118:119], v172 offset:0x1a00
	s_waitcnt lgkmcnt(6)
	v_mfma_f32_32x32x16_bf16 v[0:15], v[72:75], v[120:123], v[0:15]
	ds_read_b64_tr_b16 v[120:121], v172 offset:0x2200
	ds_read_b64_tr_b16 v[122:123], v172 offset:0x2a00
	s_waitcnt lgkmcnt(6)
	v_mfma_f32_32x32x16_bf16 v[0:15], v[76:79], v[124:127], v[0:15]
	ds_read_b64_tr_b16 v[124:125], v172 offset:0x3200
	ds_read_b64_tr_b16 v[126:127], v172 offset:0x3a00
	s_waitcnt lgkmcnt(6)
	v_mfma_f32_32x32x16_bf16 v[16:31], v[64:67], v[112:115], v[16:31]
	ds_read_b64_tr_b16 v[112:113], v172 offset:0x400
	ds_read_b64_tr_b16 v[114:115], v172 offset:0xc00
	s_waitcnt lgkmcnt(6)
	v_mfma_f32_32x32x16_bf16 v[16:31], v[68:71], v[116:119], v[16:31]
	ds_read_b64_tr_b16 v[116:117], v172 offset:0x1400
	ds_read_b64_tr_b16 v[118:119], v172 offset:0x1c00
	s_waitcnt lgkmcnt(6)
	v_mfma_f32_32x32x16_bf16 v[16:31], v[72:75], v[120:123], v[16:31]
	ds_read_b64_tr_b16 v[120:121], v172 offset:0x2400
	ds_read_b64_tr_b16 v[122:123], v172 offset:0x2c00
	s_waitcnt lgkmcnt(6)
	v_mfma_f32_32x32x16_bf16 v[16:31], v[76:79], v[124:127], v[16:31]
	ds_read_b64_tr_b16 v[124:125], v172 offset:0x3400
	ds_read_b64_tr_b16 v[126:127], v172 offset:0x3c00
	s_waitcnt lgkmcnt(6)
	v_mfma_f32_32x32x16_bf16 v[32:47], v[64:67], v[112:115], v[32:47]
	ds_read_b64_tr_b16 v[112:113], v172 offset:0x600
	ds_read_b64_tr_b16 v[114:115], v172 offset:0xe00
	s_waitcnt lgkmcnt(6)
	v_mfma_f32_32x32x16_bf16 v[32:47], v[68:71], v[116:119], v[32:47]
	ds_read_b64_tr_b16 v[116:117], v172 offset:0x1600
	ds_read_b64_tr_b16 v[118:119], v172 offset:0x1e00
	s_waitcnt lgkmcnt(6)
	v_mfma_f32_32x32x16_bf16 v[32:47], v[72:75], v[120:123], v[32:47]
	ds_read_b64_tr_b16 v[120:121], v172 offset:0x2600
	ds_read_b64_tr_b16 v[122:123], v172 offset:0x2e00
	s_waitcnt lgkmcnt(6)
	v_mfma_f32_32x32x16_bf16 v[32:47], v[76:79], v[124:127], v[32:47]
	ds_read_b64_tr_b16 v[124:125], v172 offset:0x3600
	ds_read_b64_tr_b16 v[126:127], v172 offset:0x3e00
	s_waitcnt lgkmcnt(6)
	v_mfma_f32_32x32x16_bf16 v[48:63], v[64:67], v[112:115], v[48:63]
	s_add_i32 s20, s36, 64
	s_cmp_le_i32 s20, s59
	v_add_u32_e32 v182, s36, v171
	s_waitcnt lgkmcnt(4)
	v_mfma_f32_32x32x16_bf16 v[48:63], v[68:71], v[116:119], v[48:63]
	s_waitcnt lgkmcnt(2)
	v_mfma_f32_32x32x16_bf16 v[48:63], v[72:75], v[120:123], v[48:63]
	s_waitcnt lgkmcnt(0)
	v_mfma_f32_32x32x16_bf16 v[48:63], v[76:79], v[124:127], v[48:63]
	s_cbranch_scc1 .LBB0_344
; __device__ __forceinline__ int crow(int r, int hi) { return (r & 3) + 8 * (r >> 2) + 4 * hi; }
; template <bool GM>
; __device__ __forceinline__ void partialSM(f32x16& p0, f32x16& p1, bool mask, int kbase, int L, int qpos, int hi) {
;   if (mask) {
; #pragma unroll
;     for (int r = 0; r < 16; ++r) {
;       int k = kbase + crow(r, hi);
;       asm volatile("" : "+v"(k) : "v"(p0[r]));
;       bool ok = k < L;
;       if (GM) ok = ok && (k < 16 || abs(qpos - k) <= 128);
;       p0[r] = ok ? p0[r] : -1e30f;
;       int k2 = k + 32;
;       asm volatile("" : "+v"(k2) : "v"(p1[r]));
;       bool ok2 = k2 < L;
;       if (GM) ok2 = ok2 && (k2 < 16 || abs(qpos - k2) <= 128);
;       p1[r] = ok2 ? p1[r] : -1e30f;
;     }
;   }
	v_add_u32_e32 v64, 64, v182
	s_nop 0
	v_cmp_gt_i32_e32 vcc, s94, v64
	v_add_u32_e32 v64, 32, v64
	s_nop 0
	v_cndmask_b32_e32 v80, v233, v80, vcc
	v_cmp_gt_i32_e32 vcc, s94, v64
	v_add_u32_e32 v64, 0x41, v182
	s_nop 0
	v_cndmask_b32_e32 v96, v233, v96, vcc
	v_cmp_gt_i32_e32 vcc, s94, v64
	v_add_u32_e32 v64, 32, v64
	s_nop 0
	v_cndmask_b32_e32 v81, v233, v81, vcc
	v_cmp_gt_i32_e32 vcc, s94, v64
	v_add_u32_e32 v64, 0x42, v182
	s_nop 0
	v_cndmask_b32_e32 v97, v233, v97, vcc
	v_cmp_gt_i32_e32 vcc, s94, v64
	v_add_u32_e32 v64, 32, v64
	s_nop 0
	v_cndmask_b32_e32 v82, v233, v82, vcc
	v_cmp_gt_i32_e32 vcc, s94, v64
	v_add_u32_e32 v64, 0x43, v182
	s_nop 0
	v_cndmask_b32_e32 v98, v233, v98, vcc
	v_cmp_gt_i32_e32 vcc, s94, v64
	v_add_u32_e32 v64, 32, v64
	s_nop 0
	v_cndmask_b32_e32 v83, v233, v83, vcc
	v_cmp_gt_i32_e32 vcc, s94, v64
	v_add_u32_e32 v64, 0x48, v182
	s_nop 0
	v_cndmask_b32_e32 v99, v233, v99, vcc
	v_cmp_gt_i32_e32 vcc, s94, v64
	v_add_u32_e32 v64, 32, v64
	s_nop 0
	v_cndmask_b32_e32 v84, v233, v84, vcc
	v_cmp_gt_i32_e32 vcc, s94, v64
	v_add_u32_e32 v64, 0x49, v182
	s_nop 0
	v_cndmask_b32_e32 v100, v233, v100, vcc
	v_cmp_gt_i32_e32 vcc, s94, v64
	v_add_u32_e32 v64, 32, v64
	s_nop 0
	v_cndmask_b32_e32 v85, v233, v85, vcc
	v_cmp_gt_i32_e32 vcc, s94, v64
	v_add_u32_e32 v64, 0x4a, v182
	s_nop 0
	v_cndmask_b32_e32 v101, v233, v101, vcc
	v_cmp_gt_i32_e32 vcc, s94, v64
	v_add_u32_e32 v64, 32, v64
	s_nop 0
	v_cndmask_b32_e32 v86, v233, v86, vcc
	v_cmp_gt_i32_e32 vcc, s94, v64
	v_add_u32_e32 v64, 0x4b, v182
	s_nop 0
	v_cndmask_b32_e32 v102, v233, v102, vcc
	v_cmp_gt_i32_e32 vcc, s94, v64
	v_add_u32_e32 v64, 32, v64
	s_nop 0
	v_cndmask_b32_e32 v87, v233, v87, vcc
	v_cmp_gt_i32_e32 vcc, s94, v64
	v_add_u32_e32 v64, 0x50, v182
	s_nop 0
	v_cndmask_b32_e32 v103, v233, v103, vcc
	v_cmp_gt_i32_e32 vcc, s94, v64
	v_add_u32_e32 v64, 32, v64
	s_nop 0
	v_cndmask_b32_e32 v88, v233, v88, vcc
	v_cmp_gt_i32_e32 vcc, s94, v64
	v_add_u32_e32 v64, 0x51, v182
	s_nop 0
	v_cndmask_b32_e32 v104, v233, v104, vcc
	v_cmp_gt_i32_e32 vcc, s94, v64
	v_add_u32_e32 v64, 32, v64
	s_nop 0
	v_cndmask_b32_e32 v89, v233, v89, vcc
	v_cmp_gt_i32_e32 vcc, s94, v64
	v_add_u32_e32 v64, 0x52, v182
	s_nop 0
	v_cndmask_b32_e32 v105, v233, v105, vcc
	v_cmp_gt_i32_e32 vcc, s94, v64
	v_add_u32_e32 v64, 32, v64
	s_nop 0
	v_cndmask_b32_e32 v90, v233, v90, vcc
	v_cmp_gt_i32_e32 vcc, s94, v64
	v_add_u32_e32 v64, 0x53, v182
	s_nop 0
	v_cndmask_b32_e32 v106, v233, v106, vcc
	v_cmp_gt_i32_e32 vcc, s94, v64
	v_add_u32_e32 v64, 32, v64
	s_nop 0
	v_cndmask_b32_e32 v91, v233, v91, vcc
	v_cmp_gt_i32_e32 vcc, s94, v64
	v_add_u32_e32 v64, 0x58, v182
	s_nop 0
	v_cndmask_b32_e32 v107, v233, v107, vcc
	v_cmp_gt_i32_e32 vcc, s94, v64
	v_add_u32_e32 v64, 32, v64
	s_nop 0
	v_cndmask_b32_e32 v92, v233, v92, vcc
	v_cmp_gt_i32_e32 vcc, s94, v64
	v_add_u32_e32 v64, 0x59, v182
	s_nop 0
	v_cndmask_b32_e32 v108, v233, v108, vcc
	v_cmp_gt_i32_e32 vcc, s94, v64
	v_add_u32_e32 v64, 32, v64
	s_nop 0
	v_cndmask_b32_e32 v93, v233, v93, vcc
	v_cmp_gt_i32_e32 vcc, s94, v64
	v_add_u32_e32 v64, 0x5a, v182
	s_nop 0
	v_cndmask_b32_e32 v109, v233, v109, vcc
	v_cmp_gt_i32_e32 vcc, s94, v64
	v_add_u32_e32 v64, 32, v64
	s_nop 0
	v_cndmask_b32_e32 v94, v233, v94, vcc
	v_cmp_gt_i32_e32 vcc, s94, v64
	v_add_u32_e32 v64, 0x5b, v182
	s_nop 0
	v_cndmask_b32_e32 v110, v233, v110, vcc
	v_cmp_gt_i32_e32 vcc, s94, v64
	v_add_u32_e32 v64, 32, v64
	s_nop 0
	v_cndmask_b32_e32 v95, v233, v95, vcc
	v_cmp_gt_i32_e32 vcc, s94, v64
	s_nop 1
	v_cndmask_b32_e32 v111, v233, v111, vcc
; #define WAIT_V0() asm volatile("s_waitcnt vmcnt(0)" ::: "memory")
; #define SBAR() __builtin_amdgcn_sched_barrier(0)
; #define SWRITE(b) do { FRESH_COORDS(); \
;     if constexpr (!KDMA) { _Pragma("unroll") for (int i = 0; i < KC; ++i) *reinterpret_cast<bf16x8*>(shm + (b) * SHM_K + klo[i]) = ks[i]; } \
;     _Pragma("unroll") for (int i = 0; i < VC; ++i) *reinterpret_cast<bf16x8*>(shm + (b) * SHM_V + vlo[i]) = vs[i]; } while (0)
; #define QKT(P0, P1, BUF) qkt<DQK, QL>(P0, P1, shm + K_OFF + (BUF) * SHM_K, qr, qlds, kofs, negM)
; __device__ __forceinline__ void finishSM(f32x16& p0, f32x16& p1, float& l_reg, bf16x8& pa0, bf16x8& pa1, bf16x8& pa2, bf16x8& pa3) {
; #pragma unroll
;   for (int r = 0; r < 16; ++r) p1[r] = __builtin_amdgcn_exp2f(p1[r]);
;   float ps = 0;
; #pragma unroll
;   for (int r = 0; r < 16; ++r) ps += p0[r];
; #pragma unroll
;   for (int r = 0; r < 16; ++r) ps += p1[r];
;   { auto rr = __builtin_amdgcn_permlane32_swap(__float_as_uint(ps), __float_as_uint(ps), false, false);
;     ps = __uint_as_float(rr[0]) + __uint_as_float(rr[1]); }
;   l_reg += ps;
;     ...
;   PK4(p0, 0, pa0); PK4(p0, 8, pa1); PK4(p1, 0, pa2); PK4(p1, 8, pa3);
;     ...
; }
; template <int DQK, int QL>
; __device__ __forceinline__ void qkt(f32x16& p0, f32x16& p1, const char* Ks, const bf16x8 (&qr)[DQK / 16 - QL], const char* qlds, const int (&kofs)[4], float negM) {
;   constexpr int QR = DQK / 16 - QL;
; #pragma unroll
;   for (int r = 0; r < 16; ++r) { p0[r] = negM; p1[r] = negM; }
; #pragma unroll
;   for (int d0 = 0; d0 < DQK / 16; ++d0) {
;     const char* kp = Ks + kofs[d0 & 3] + (d0 >> 2) * 128;
;     bf16x8 b0 = *reinterpret_cast<const bf16x8*>(kp);
;     bf16x8 b1 = *reinterpret_cast<const bf16x8*>(kp + 32 * DQK * 2);
;     bf16x8 qf;
;     if constexpr (QL > 0) { if (d0 < QR) qf = qr[d0 < QR ? d0 : 0]; else qf = *reinterpret_cast<const bf16x8*>(qlds + (d0 - QR) * 1024); }
;     else qf = qr[d0];
;     p0 = __builtin_amdgcn_mfma_f32_32x32x16_bf16(b0, qf, p0, 0, 0, 0);
;     p1 = __builtin_amdgcn_mfma_f32_32x32x16_bf16(b1, qf, p1, 0, 0, 0);
;   }
;     ...
;     __syncthreads(); WAIT_V0(); SWRITE(0);
;     __syncthreads();
;     SBAR();
;     if constexpr (ONEP) { finishSM(pB0, pB1, l_reg, pa0, pa1, pa2, pa3); SBAR(); QKT(pA0, pA1, 0); }
;     else { QKT(pA0, pA1, 0); finishSM(pB0, pB1, l_reg, pa0, pa1, pa2, pa3); }
;     SBAR();
;     if (j + 2 < NT) SLOAD(TKEY(j + 2), 1);
.LBB0_344:
	s_barrier
	s_waitcnt vmcnt(0)
	s_waitcnt vmcnt(2)
	ds_write_b128 v179, v[146:149] offset:32768
	s_waitcnt vmcnt(1)
	ds_write_b128 v177, v[150:153]
	s_waitcnt vmcnt(0)
	ds_write_b128 v178, v[154:157]
	v_exp_f32_e32 v183, v80
	v_exp_f32_e32 v188, v81
	v_exp_f32_e32 v189, v82
	v_exp_f32_e32 v190, v83
	v_exp_f32_e32 v191, v84
	v_exp_f32_e32 v192, v85
	v_exp_f32_e32 v193, v86
	v_exp_f32_e32 v194, v87
	v_exp_f32_e32 v195, v88
	v_exp_f32_e32 v196, v89
	v_exp_f32_e32 v197, v90
	v_exp_f32_e32 v198, v91
	v_exp_f32_e32 v199, v92
	v_exp_f32_e32 v200, v93
	v_exp_f32_e32 v201, v94
	v_exp_f32_e32 v202, v95
	s_waitcnt lgkmcnt(0)
	s_barrier
	ds_read_b128 v[64:67], v174 offset:32768
	ds_read_b128 v[184:187], v174 offset:36864
	v_exp_f32_e32 v111, v111
	s_waitcnt lgkmcnt(1)
	v_mfma_f32_32x32x16_bf16 v[80:95], v[64:67], v[142:145], v[238:253]
	s_waitcnt lgkmcnt(0)
	v_mfma_f32_32x32x16_bf16 v[64:79], v[184:187], v[142:145], v[238:253]
	ds_read_b128 v[112:115], v175 offset:32768
	ds_read_b128 v[116:119], v175 offset:36864
	v_exp_f32_e32 v120, v102
	v_exp_f32_e32 v121, v103
	v_exp_f32_e32 v122, v104
	v_exp_f32_e32 v123, v105
	v_exp_f32_e32 v124, v106
	v_exp_f32_e32 v125, v107
	s_waitcnt lgkmcnt(1)
	v_mfma_f32_32x32x16_bf16 v[80:95], v[112:115], v[138:141], v[80:95]
	v_exp_f32_e32 v126, v108
	v_exp_f32_e32 v127, v109
	v_exp_f32_e32 v184, v110
	s_waitcnt lgkmcnt(0)
	v_mfma_f32_32x32x16_bf16 v[64:79], v[116:119], v[138:141], v[64:79]
	ds_read_b128 v[112:115], v173 offset:32768
	ds_read_b128 v[116:119], v173 offset:36864
	s_waitcnt lgkmcnt(1)
	v_mfma_f32_32x32x16_bf16 v[80:95], v[112:115], v[134:137], v[80:95]
	s_waitcnt lgkmcnt(0)
	v_mfma_f32_32x32x16_bf16 v[64:79], v[116:119], v[134:137], v[64:79]
	ds_read_b128 v[112:115], v176 offset:32768
	ds_read_b128 v[116:119], v176 offset:36864
	s_waitcnt lgkmcnt(1)
	v_mfma_f32_32x32x16_bf16 v[80:95], v[112:115], v[130:133], v[80:95]
	v_exp_f32_e32 v114, v96
	v_add_f32_e32 v96, 0, v183
	v_add_f32_e32 v96, v189, v96
	v_add_f32_e32 v112, v188, v190
	v_add_f32_e32 v96, v191, v96
	v_add_f32_e32 v112, v192, v112
	v_add_f32_e32 v96, v193, v96
	v_add_f32_e32 v112, v194, v112
	v_add_f32_e32 v96, v195, v96
	v_add_f32_e32 v112, v196, v112
	v_add_f32_e32 v96, v197, v96
	v_add_f32_e32 v112, v198, v112
	v_add_f32_e32 v96, v199, v96
	v_exp_f32_e32 v115, v97
	v_add_f32_e32 v112, v200, v112
	s_waitcnt lgkmcnt(0)
	v_mfma_f32_32x32x16_bf16 v[64:79], v[116:119], v[130:133], v[64:79]
	v_exp_f32_e32 v116, v98
	v_add_f32_e32 v96, v201, v96
	v_exp_f32_e32 v117, v99
	v_add_f32_e32 v112, v202, v112
	v_exp_f32_e32 v118, v100
	v_add_f32_e32 v96, v114, v96
	v_exp_f32_e32 v119, v101
	v_add_f32_e32 v112, v115, v112
	v_add_f32_e32 v96, v116, v96
	v_add_f32_e32 v112, v117, v112
	v_add_f32_e32 v96, v118, v96
	v_add_f32_e32 v112, v119, v112
	v_add_f32_e32 v96, v120, v96
	v_add_f32_e32 v112, v121, v112
	v_add_f32_e32 v96, v122, v96
	v_add_f32_e32 v112, v123, v112
	v_add_f32_e32 v96, v124, v96
	v_add_f32_e32 v112, v125, v112
	v_add_f32_e32 v96, v126, v96
	v_add_f32_e32 v112, v127, v112
	v_add_f32_e32 v96, v184, v96
	v_add_f32_e32 v112, v111, v112
	v_add_f32_e32 v112, v96, v112
	v_mov_b32_e32 v113, v112
	v_cvt_pk_bf16_f32 v96, v183, v188
	v_cvt_pk_bf16_f32 v97, v189, v190
	v_cvt_pk_bf16_f32 v98, v191, v192
	v_cvt_pk_bf16_f32 v99, v193, v194
	v_cvt_pk_bf16_f32 v100, v195, v196
	v_cvt_pk_bf16_f32 v101, v197, v198
	v_cvt_pk_bf16_f32 v102, v199, v200
	v_cvt_pk_bf16_f32 v103, v201, v202
	v_cvt_pk_bf16_f32 v104, v114, v115
	v_cvt_pk_bf16_f32 v105, v116, v117
	v_cvt_pk_bf16_f32 v106, v118, v119
	v_cvt_pk_bf16_f32 v107, v120, v121
	v_cvt_pk_bf16_f32 v108, v122, v123
	v_cvt_pk_bf16_f32 v109, v124, v125
	v_cvt_pk_bf16_f32 v110, v126, v127
	v_cvt_pk_bf16_f32 v111, v184, v111
	s_nop 1
	v_permlane32_swap_b32_e32 v112, v113
	v_permlane32_swap_b32_e32 v96, v98
	v_permlane32_swap_b32_e32 v97, v99
	v_permlane32_swap_b32_e32 v100, v102
	v_permlane32_swap_b32_e32 v101, v103
	v_permlane32_swap_b32_e32 v104, v106
	v_permlane32_swap_b32_e32 v105, v107
	v_permlane32_swap_b32_e32 v108, v110
	v_permlane32_swap_b32_e32 v109, v111
	s_cmp_lt_u32 s3, s58
	s_cselect_b64 s[22:23], -1, 0
	s_cmp_ge_u32 s3, s58
	s_cselect_b64 s[20:21], -1, 0
	s_and_b64 vcc, exec, s[20:21]
	s_cbranch_vccnz .LBB0_346
	s_add_u32 s100, s0, 0x593c000
	s_addc_u32 s101, s1, 0
	global_load_dwordx4 v[146:149], v158, s[100:101] offset:1408
	global_load_dwordx4 v[150:153], v160, s[100:101] offset:2304
	global_load_dwordx4 v[154:157], v162, s[100:101] offset:2304

; __device__ __forceinline__ void finishSM(f32x16& p0, f32x16& p1, float& l_reg, bf16x8& pa0, bf16x8& pa1, bf16x8& pa2, bf16x8& pa3) {
; #pragma unroll
;   for (int r = 0; r < 16; ++r) p1[r] = __builtin_amdgcn_exp2f(p1[r]);
;   float ps = 0;
; #pragma unroll
;   for (int r = 0; r < 16; ++r) ps += p0[r];
; #pragma unroll
;   for (int r = 0; r < 16; ++r) ps += p1[r];
;   { auto rr = __builtin_amdgcn_permlane32_swap(__float_as_uint(ps), __float_as_uint(ps), false, false);
;     ps = __uint_as_float(rr[0]) + __uint_as_float(rr[1]); }
;   l_reg += ps;
;     ...
;   PK4(p0, 0, pa0); PK4(p0, 8, pa1); PK4(p1, 0, pa2); PK4(p1, 8, pa3);
;     ...
; }
; template <int DQK, int QL>
; __device__ __forceinline__ void qkt(f32x16& p0, f32x16& p1, const char* Ks, const bf16x8 (&qr)[DQK / 16 - QL], const char* qlds, const int (&kofs)[4], float negM) {
;   constexpr int QR = DQK / 16 - QL;
; #pragma unroll
;   for (int r = 0; r < 16; ++r) { p0[r] = negM; p1[r] = negM; }
; #pragma unroll
;   for (int d0 = 0; d0 < DQK / 16; ++d0) {
;     const char* kp = Ks + kofs[d0 & 3] + (d0 >> 2) * 128;
;     bf16x8 b0 = *reinterpret_cast<const bf16x8*>(kp);
;     bf16x8 b1 = *reinterpret_cast<const bf16x8*>(kp + 32 * DQK * 2);
;     bf16x8 qf;
;     if constexpr (QL > 0) { if (d0 < QR) qf = qr[d0 < QR ? d0 : 0]; else qf = *reinterpret_cast<const bf16x8*>(qlds + (d0 - QR) * 1024); }
;     else qf = qr[d0];
;     p0 = __builtin_amdgcn_mfma_f32_32x32x16_bf16(b0, qf, p0, 0, 0, 0);
;     p1 = __builtin_amdgcn_mfma_f32_32x32x16_bf16(b1, qf, p1, 0, 0, 0);
;   }
.LBB0_369:
	v_add_f32_e32 v80, 0, v176
	v_add_f32_e32 v80, v174, v80
	v_add_f32_e32 v169, v178, v177
	v_add_f32_e32 v80, v172, v80
	v_add_f32_e32 v169, v175, v169
	v_add_f32_e32 v80, v171, v80
	v_add_f32_e32 v169, v173, v169
	v_add_f32_e32 v80, v147, v80
	v_add_f32_e32 v169, v149, v169
	v_add_f32_e32 v80, v145, v80
	v_add_f32_e32 v169, v148, v169
	v_exp_f32_e32 v64, v64
	v_add_f32_e32 v80, v143, v80
	v_exp_f32_e32 v65, v65
	v_add_f32_e32 v169, v146, v169
	v_exp_f32_e32 v66, v66
	v_add_f32_e32 v80, v142, v80
	v_exp_f32_e32 v67, v67
	v_add_f32_e32 v169, v144, v169
	v_exp_f32_e32 v68, v68
	v_add_f32_e32 v80, v64, v80
	v_exp_f32_e32 v69, v69
	v_add_f32_e32 v169, v65, v169
	v_exp_f32_e32 v70, v70
	v_add_f32_e32 v80, v66, v80
	v_exp_f32_e32 v71, v71
	v_add_f32_e32 v169, v67, v169
	v_exp_f32_e32 v72, v72
	v_add_f32_e32 v80, v68, v80
	v_exp_f32_e32 v73, v73
	v_add_f32_e32 v169, v69, v169
	v_exp_f32_e32 v74, v74
	v_add_f32_e32 v80, v70, v80
	v_exp_f32_e32 v75, v75
	v_add_f32_e32 v169, v71, v169
	v_exp_f32_e32 v76, v76
	v_add_f32_e32 v80, v72, v80
	v_exp_f32_e32 v77, v77
	v_add_f32_e32 v169, v73, v169
	v_exp_f32_e32 v78, v78
	v_add_f32_e32 v80, v74, v80
	v_exp_f32_e32 v79, v79
	v_add_f32_e32 v169, v75, v169
	v_add_f32_e32 v80, v76, v80
	v_add_f32_e32 v169, v77, v169
	v_add_f32_e32 v80, v78, v80
	v_add_f32_e32 v169, v79, v169
	v_add_f32_e32 v169, v80, v169
	v_mov_b32_e32 v170, v169
	s_nop 1
	v_permlane32_swap_b32_e32 v169, v170
	v_cvt_pk_bf16_f32 v120, v176, v178
	v_cvt_pk_bf16_f32 v121, v174, v177
	v_cvt_pk_bf16_f32 v122, v172, v175
	v_cvt_pk_bf16_f32 v123, v171, v173
	v_cvt_pk_bf16_f32 v124, v147, v149
	v_cvt_pk_bf16_f32 v125, v145, v148
	v_cvt_pk_bf16_f32 v126, v143, v146
	v_cvt_pk_bf16_f32 v127, v142, v144
	v_cvt_pk_bf16_f32 v142, v64, v65
	v_cvt_pk_bf16_f32 v143, v66, v67
	v_cvt_pk_bf16_f32 v144, v68, v69
	v_cvt_pk_bf16_f32 v145, v70, v71
	v_cvt_pk_bf16_f32 v146, v72, v73
	v_cvt_pk_bf16_f32 v147, v74, v75
	v_cvt_pk_bf16_f32 v148, v76, v77
	v_cvt_pk_bf16_f32 v149, v78, v79
	s_nop 0
	v_permlane32_swap_b32_e32 v120, v122
	v_permlane32_swap_b32_e32 v121, v123
	v_permlane32_swap_b32_e32 v124, v126
	v_permlane32_swap_b32_e32 v125, v127
	v_permlane32_swap_b32_e32 v142, v144
	v_permlane32_swap_b32_e32 v143, v145
	v_permlane32_swap_b32_e32 v146, v148
	v_permlane32_swap_b32_e32 v147, v149
	ds_read_b128 v[80:83], v152 offset:57344
	ds_read_b128 v[84:87], v152 offset:57472
	v_mov_b64_e32 v[110:111], s[18:19]
	v_mov_b64_e32 v[108:109], s[16:17]
	v_mov_b64_e32 v[106:107], s[14:15]
	v_mov_b64_e32 v[104:105], s[12:13]
	v_mov_b64_e32 v[102:103], s[10:11]
	v_mov_b64_e32 v[100:101], s[8:9]
	v_mov_b64_e32 v[98:99], s[6:7]
	v_mov_b64_e32 v[96:97], s[4:5]
	v_add_u32_e32 v167, v163, v162
	s_waitcnt lgkmcnt(1)
	v_mfma_f32_32x32x16_bf16 v[64:79], v[80:83], v[138:141], v[96:111]
	ds_read_b128 v[80:83], v156 offset:57344
	ds_read_b128 v[88:91], v152 offset:57600
	s_waitcnt lgkmcnt(1)
	v_mfma_f32_32x32x16_bf16 v[64:79], v[80:83], v[134:137], v[64:79]
	ds_read_b128 v[80:83], v155 offset:57344
	ds_read_b128 v[92:95], v155 offset:57472
	s_waitcnt lgkmcnt(1)
	v_mfma_f32_32x32x16_bf16 v[64:79], v[80:83], v[130:133], v[64:79]
	ds_read_b128 v[80:83], v153 offset:57344
	ds_read_b128 v[112:115], v167
	ds_read_b128 v[116:119], v155 offset:57600
	ds_read_b128 v[172:175], v167 offset:1024
	s_waitcnt lgkmcnt(2)
	v_mfma_f32_32x32x16_bf16 v[64:79], v[80:83], v[112:115], v[64:79]
	s_waitcnt lgkmcnt(0)
	v_mfma_f32_32x32x16_bf16 v[64:79], v[84:87], v[172:175], v[64:79]
	ds_read_b128 v[80:83], v156 offset:57472
	ds_read_b128 v[176:179], v167 offset:2048
	ds_read_b128 v[84:87], v156 offset:57600
	ds_read_b128 v[180:183], v167 offset:3072
	s_waitcnt lgkmcnt(2)
	v_mfma_f32_32x32x16_bf16 v[64:79], v[80:83], v[176:179], v[64:79]
	s_waitcnt lgkmcnt(0)
	v_mfma_f32_32x32x16_bf16 v[64:79], v[92:95], v[180:183], v[64:79]
	ds_read_b128 v[80:83], v153 offset:57472
	ds_read_b128 v[184:187], v167 offset:4096
	ds_read_b128 v[188:191], v167 offset:5120
	ds_read_b128 v[92:95], v153 offset:57600
	ds_read_b128 v[192:195], v167 offset:6144
	ds_read_b128 v[196:199], v167 offset:7168
	ds_read_b128 v[200:203], v160 offset:12288
	ds_read_b128 v[204:207], v160 offset:12416
	ds_read_b128 v[208:211], v158 offset:12288
	ds_read_b128 v[212:215], v158 offset:12416
	ds_read_b128 v[216:219], v159 offset:12288
	ds_read_b128 v[220:223], v160 offset:12544
	s_waitcnt lgkmcnt(10)
	v_mfma_f32_32x32x16_bf16 v[64:79], v[80:83], v[184:187], v[64:79]
	s_waitcnt lgkmcnt(9)
	v_mfma_f32_32x32x16_bf16 v[64:79], v[88:91], v[188:191], v[64:79]
	s_waitcnt lgkmcnt(7)
	v_mfma_f32_32x32x16_bf16 v[64:79], v[84:87], v[192:195], v[64:79]
	s_waitcnt lgkmcnt(6)
	v_mfma_f32_32x32x16_bf16 v[64:79], v[116:119], v[196:199], v[64:79]
	ds_read_b128 v[116:119], v159 offset:12416
	ds_read_b128 v[238:241], v159 offset:12544
	ds_read_b128 v[242:245], v167 offset:8192
	ds_read_b128 v[246:249], v157 offset:12288
	ds_read_b128 v[250:253], v158 offset:12544
	ds_read_b128 v[228:231], v157 offset:12416
	ds_read_b128 v[224:227], v157 offset:12544
	s_waitcnt lgkmcnt(4)
	v_mfma_f32_32x32x16_bf16 v[64:79], v[92:95], v[242:245], v[64:79]
	v_mfma_f32_32x32x16_bf16 v[80:95], v[200:203], v[138:141], v[96:111]
	v_mov_b32_e32 v171, v161
	s_add_u32 s72, s55, s0
	s_addc_u32 s73, s83, s1
	v_mfma_f32_32x32x16_bf16 v[80:95], v[216:219], v[134:137], v[80:95]
	v_mfma_f32_32x32x16_bf16 v[80:95], v[208:211], v[130:133], v[80:95]
	s_waitcnt lgkmcnt(3)
; #define SBAR() __builtin_amdgcn_sched_barrier(0)
; template <int DQK, int QL>
; __device__ __forceinline__ void qkt(f32x16& p0, f32x16& p1, const char* Ks, const bf16x8 (&qr)[DQK / 16 - QL], const char* qlds, const int (&kofs)[4], float negM) {
;   constexpr int QR = DQK / 16 - QL;
; #pragma unroll
;   for (int r = 0; r < 16; ++r) { p0[r] = negM; p1[r] = negM; }
; #pragma unroll
;   for (int d0 = 0; d0 < DQK / 16; ++d0) {
;     const char* kp = Ks + kofs[d0 & 3] + (d0 >> 2) * 128;
;     bf16x8 b0 = *reinterpret_cast<const bf16x8*>(kp);
;     bf16x8 b1 = *reinterpret_cast<const bf16x8*>(kp + 32 * DQK * 2);
;     bf16x8 qf;
;     if constexpr (QL > 0) { if (d0 < QR) qf = qr[d0 < QR ? d0 : 0]; else qf = *reinterpret_cast<const bf16x8*>(qlds + (d0 - QR) * 1024); }
;     else qf = qr[d0];
;     p0 = __builtin_amdgcn_mfma_f32_32x32x16_bf16(b0, qf, p0, 0, 0, 0);
;     p1 = __builtin_amdgcn_mfma_f32_32x32x16_bf16(b1, qf, p1, 0, 0, 0);
;   }
; }
; template <int NCB> __device__ __forceinline__ int v_st(int k, int c) {
;   const int kk = (k & ~0xC) | ((k & 4) << 1) | ((k & 8) >> 1);
;   return ((kk >> 3) * NCB + (c >> 5)) * 512 + ((kk & 7) * 32 + (c & 31)) * 2;
; }
; __device__ __forceinline__ int v_rd_base(int lane) { return ((lane & 3) << 3) | (((lane >> 2) & 3) << 6) | (((lane >> 4) & 1) << 5) | (((lane >> 5) & 1) << 8); }
; template <int OFF> __device__ __forceinline__ s16x4 tr_read(int vb) {
;   s16x4 r; asm volatile("ds_read_b64_tr_b16 %0, %1 offset:%2" : "=&v"(r) : "v"(vb), "i"(OFF) : "memory"); return r;
; }
; template <int NCB, int D0> __device__ __forceinline__ void pv_one(f32x16& od, int vb, bf16x8 pa0, bf16x8 pa1, bf16x8 pa2, bf16x8 pa3) {
;   constexpr int KSTEP = NCB * 1024, HALF = NCB * 512, B0 = D0 * 512;
;   const s16x4 l0 = tr_read<B0>(vb), h0 = tr_read<B0 + HALF>(vb), l1 = tr_read<B0 + KSTEP>(vb), h1 = tr_read<B0 + KSTEP + HALF>(vb);
;   const s16x4 l2 = tr_read<B0 + 2 * KSTEP>(vb), h2 = tr_read<B0 + 2 * KSTEP + HALF>(vb), l3 = tr_read<B0 + 3 * KSTEP>(vb), h3 = tr_read<B0 + 3 * KSTEP + HALF>(vb);
;   WAIT_L0(); SBAR();
;     ...
;   od = __builtin_amdgcn_mfma_f32_32x32x16_bf16(pa0, PK(l0, h0), od, 0, 0, 0);
;   od = __builtin_amdgcn_mfma_f32_32x32x16_bf16(pa1, PK(l1, h1), od, 0, 0, 0);
;   od = __builtin_amdgcn_mfma_f32_32x32x16_bf16(pa2, PK(l2, h2), od, 0, 0, 0);
;   od = __builtin_amdgcn_mfma_f32_32x32x16_bf16(pa3, PK(l3, h3), od, 0, 0, 0);
;     ...
; }
	v_mfma_f32_32x32x16_bf16 v[80:95], v[246:249], v[112:115], v[80:95]
	v_mfma_f32_32x32x16_bf16 v[80:95], v[204:207], v[172:175], v[80:95]
	s_add_u32 s74, s36, s0
	s_addc_u32 s75, s54, s1
	s_add_u32 s100, s72, s46
	s_addc_u32 s101, s73, s47
	v_readfirstlane_b32 s20, v164
	s_mov_b32 m0, s20
	s_nop 0
	global_load_lds_dwordx4 v235, s[100:101]
	v_readfirstlane_b32 s20, v165
	s_mov_b32 m0, s20
	s_nop 0
	global_load_lds_dwordx4 v236, s[100:101]
	v_readfirstlane_b32 s20, v166
	s_mov_b32 m0, s20
	s_nop 0
	global_load_lds_dwordx4 v237, s[100:101]
	v_mfma_f32_32x32x16_bf16 v[80:95], v[116:119], v[176:179], v[80:95]
	s_add_u32 s100, s74, s25
	s_addc_u32 s101, s75, 0
	global_load_dwordx4 v[112:115], v232, s[100:101] offset:256
	s_add_u32 s100, s100, 0x8000
	s_addc_u32 s101, s101, 0
	global_load_dwordx4 v[116:119], v232, s[100:101] offset:256
	v_mfma_f32_32x32x16_bf16 v[80:95], v[212:215], v[180:183], v[80:95]
	s_waitcnt lgkmcnt(0)
	v_mfma_f32_32x32x16_bf16 v[80:95], v[228:231], v[184:187], v[80:95]
	v_mfma_f32_32x32x16_bf16 v[80:95], v[220:223], v[188:191], v[80:95]
	v_mfma_f32_32x32x16_bf16 v[80:95], v[238:241], v[192:195], v[80:95]
	v_mfma_f32_32x32x16_bf16 v[80:95], v[250:253], v[196:199], v[80:95]
	v_mfma_f32_32x32x16_bf16 v[80:95], v[224:227], v[242:245], v[80:95]
	ds_read_b64_tr_b16 v[96:97], v151 offset:0
	ds_read_b64_tr_b16 v[98:99], v151 offset:0x800
	ds_read_b64_tr_b16 v[100:101], v151 offset:0x1000
	ds_read_b64_tr_b16 v[102:103], v151 offset:0x1800
	ds_read_b64_tr_b16 v[104:105], v151 offset:0x2000
	ds_read_b64_tr_b16 v[106:107], v151 offset:0x2800
	ds_read_b64_tr_b16 v[108:109], v151 offset:0x3000
	ds_read_b64_tr_b16 v[110:111], v151 offset:0x3800
	s_nop 0
	s_waitcnt lgkmcnt(6)
	v_mfma_f32_32x32x16_bf16 v[0:15], v[120:123], v[96:99], v[0:15]
	ds_read_b64_tr_b16 v[96:97], v151 offset:0x200
	ds_read_b64_tr_b16 v[98:99], v151 offset:0xa00
	s_waitcnt lgkmcnt(6)
	v_mfma_f32_32x32x16_bf16 v[0:15], v[124:127], v[100:103], v[0:15]
	ds_read_b64_tr_b16 v[100:101], v151 offset:0x1200
	ds_read_b64_tr_b16 v[102:103], v151 offset:0x1a00
	s_waitcnt lgkmcnt(6)
	v_mfma_f32_32x32x16_bf16 v[0:15], v[142:145], v[104:107], v[0:15]
	ds_read_b64_tr_b16 v[104:105], v151 offset:0x2200
	ds_read_b64_tr_b16 v[106:107], v151 offset:0x2a00
	s_waitcnt lgkmcnt(6)
	v_mfma_f32_32x32x16_bf16 v[0:15], v[146:149], v[108:111], v[0:15]
	ds_read_b64_tr_b16 v[108:109], v151 offset:0x3200
	ds_read_b64_tr_b16 v[110:111], v151 offset:0x3a00
	s_waitcnt lgkmcnt(6)
	v_mfma_f32_32x32x16_bf16 v[16:31], v[120:123], v[96:99], v[16:31]
	ds_read_b64_tr_b16 v[96:97], v151 offset:0x400
	ds_read_b64_tr_b16 v[98:99], v151 offset:0xc00
	s_waitcnt lgkmcnt(6)
	v_mfma_f32_32x32x16_bf16 v[16:31], v[124:127], v[100:103], v[16:31]
	ds_read_b64_tr_b16 v[100:101], v151 offset:0x1400
	ds_read_b64_tr_b16 v[102:103], v151 offset:0x1c00
	s_waitcnt lgkmcnt(6)
	v_mfma_f32_32x32x16_bf16 v[16:31], v[142:145], v[104:107], v[16:31]
	ds_read_b64_tr_b16 v[104:105], v151 offset:0x2400
	ds_read_b64_tr_b16 v[106:107], v151 offset:0x2c00
	s_waitcnt lgkmcnt(6)
	v_mfma_f32_32x32x16_bf16 v[16:31], v[146:149], v[108:111], v[16:31]
	ds_read_b64_tr_b16 v[108:109], v151 offset:0x3400
	ds_read_b64_tr_b16 v[110:111], v151 offset:0x3c00
	s_waitcnt lgkmcnt(6)
	v_mfma_f32_32x32x16_bf16 v[32:47], v[120:123], v[96:99], v[32:47]
	ds_read_b64_tr_b16 v[96:97], v151 offset:0x600
	ds_read_b64_tr_b16 v[98:99], v151 offset:0xe00
	s_waitcnt lgkmcnt(6)
	v_mfma_f32_32x32x16_bf16 v[32:47], v[124:127], v[100:103], v[32:47]
	ds_read_b64_tr_b16 v[100:101], v151 offset:0x1600
	ds_read_b64_tr_b16 v[102:103], v151 offset:0x1e00
	s_waitcnt lgkmcnt(6)
	v_mfma_f32_32x32x16_bf16 v[32:47], v[142:145], v[104:107], v[32:47]
	ds_read_b64_tr_b16 v[104:105], v151 offset:0x2600
	ds_read_b64_tr_b16 v[106:107], v151 offset:0x2e00
	s_waitcnt lgkmcnt(6)
	v_mfma_f32_32x32x16_bf16 v[32:47], v[146:149], v[108:111], v[32:47]
	ds_read_b64_tr_b16 v[108:109], v151 offset:0x3600
	ds_read_b64_tr_b16 v[110:111], v151 offset:0x3e00
	s_waitcnt lgkmcnt(6)
	v_mfma_f32_32x32x16_bf16 v[48:63], v[120:123], v[96:99], v[48:63]
	s_add_i32 s20, s87, 64
	s_cmp_le_i32 s20, s59
	v_add_u32_e32 v171, s87, v154
	s_waitcnt lgkmcnt(4)
	v_mfma_f32_32x32x16_bf16 v[48:63], v[124:127], v[100:103], v[48:63]
	s_waitcnt lgkmcnt(2)
	v_mfma_f32_32x32x16_bf16 v[48:63], v[142:145], v[104:107], v[48:63]
	s_waitcnt lgkmcnt(0)
	v_mfma_f32_32x32x16_bf16 v[48:63], v[146:149], v[108:111], v[48:63]
	s_cbranch_scc1 .LBB0_371
; #define WAIT_V0() asm volatile("s_waitcnt vmcnt(0)" ::: "memory")
; __device__ __forceinline__ int crow(int r, int hi) { return (r & 3) + 8 * (r >> 2) + 4 * hi; }
; #define SWRITE(b) do { FRESH_COORDS(); \
;     if constexpr (!KDMA) { _Pragma("unroll") for (int i = 0; i < KC; ++i) *reinterpret_cast<bf16x8*>(shm + (b) * SHM_K + klo[i]) = ks[i]; } \
;     _Pragma("unroll") for (int i = 0; i < VC; ++i) *reinterpret_cast<bf16x8*>(shm + (b) * SHM_V + vlo[i]) = vs[i]; } while (0)
; template <bool GM>
; __device__ __forceinline__ void partialSM(f32x16& p0, f32x16& p1, bool mask, int kbase, int L, int qpos, int hi) {
;   if (mask) {
; #pragma unroll
;     for (int r = 0; r < 16; ++r) {
;       int k = kbase + crow(r, hi);
;       asm volatile("" : "+v"(k) : "v"(p0[r]));
;       bool ok = k < L;
;       if (GM) ok = ok && (k < 16 || abs(qpos - k) <= 128);
;       p0[r] = ok ? p0[r] : -1e30f;
;       int k2 = k + 32;
;       asm volatile("" : "+v"(k2) : "v"(p1[r]));
;       bool ok2 = k2 < L;
;       if (GM) ok2 = ok2 && (k2 < 16 || abs(qpos - k2) <= 128);
;       p1[r] = ok2 ? p1[r] : -1e30f;
;     }
;   }
; #pragma unroll
;   for (int r = 0; r < 16; ++r) p0[r] = __builtin_amdgcn_exp2f(p0[r]);
; }
;     ...
;     partialSM<GM>(pB0, pB1, NEEDMASK(kb), kb, L, qpos, hi);
;     __syncthreads(); WAIT_V0(); SWRITE(0);
;     __syncthreads();
	v_add_u32_e32 v96, 64, v171
	s_nop 0
	v_cmp_gt_i32_e32 vcc, s94, v96
	v_add_u32_e32 v96, 32, v96
	s_nop 0
	v_cndmask_b32_e32 v64, v233, v64, vcc
	v_cmp_gt_i32_e32 vcc, s94, v96
	v_add_u32_e32 v96, 0x41, v171
	s_nop 0
	v_cndmask_b32_e32 v80, v233, v80, vcc
	v_cmp_gt_i32_e32 vcc, s94, v96
	v_add_u32_e32 v96, 32, v96
	s_nop 0
	v_cndmask_b32_e32 v65, v233, v65, vcc
	v_cmp_gt_i32_e32 vcc, s94, v96
	v_add_u32_e32 v96, 0x42, v171
	s_nop 0
	v_cndmask_b32_e32 v81, v233, v81, vcc
	v_cmp_gt_i32_e32 vcc, s94, v96
	v_add_u32_e32 v96, 32, v96
	s_nop 0
	v_cndmask_b32_e32 v66, v233, v66, vcc
	v_cmp_gt_i32_e32 vcc, s94, v96
	v_add_u32_e32 v96, 0x43, v171
	s_nop 0
	v_cndmask_b32_e32 v82, v233, v82, vcc
	v_cmp_gt_i32_e32 vcc, s94, v96
	v_add_u32_e32 v96, 32, v96
	s_nop 0
	v_cndmask_b32_e32 v67, v233, v67, vcc
	v_cmp_gt_i32_e32 vcc, s94, v96
	v_add_u32_e32 v96, 0x48, v171
	s_nop 0
	v_cndmask_b32_e32 v83, v233, v83, vcc
	v_cmp_gt_i32_e32 vcc, s94, v96
	v_add_u32_e32 v96, 32, v96
	s_nop 0
	v_cndmask_b32_e32 v68, v233, v68, vcc
	v_cmp_gt_i32_e32 vcc, s94, v96
	v_add_u32_e32 v96, 0x49, v171
	s_nop 0
	v_cndmask_b32_e32 v84, v233, v84, vcc
	v_cmp_gt_i32_e32 vcc, s94, v96
	v_add_u32_e32 v96, 32, v96
	s_nop 0
	v_cndmask_b32_e32 v69, v233, v69, vcc
	v_cmp_gt_i32_e32 vcc, s94, v96
	v_add_u32_e32 v96, 0x4a, v171
	s_nop 0
	v_cndmask_b32_e32 v85, v233, v85, vcc
	v_cmp_gt_i32_e32 vcc, s94, v96
	v_add_u32_e32 v96, 32, v96
	s_nop 0
	v_cndmask_b32_e32 v70, v233, v70, vcc
	v_cmp_gt_i32_e32 vcc, s94, v96
	v_add_u32_e32 v96, 0x4b, v171
	s_nop 0
	v_cndmask_b32_e32 v86, v233, v86, vcc
	v_cmp_gt_i32_e32 vcc, s94, v96
	v_add_u32_e32 v96, 32, v96
	s_nop 0
	v_cndmask_b32_e32 v71, v233, v71, vcc
	v_cmp_gt_i32_e32 vcc, s94, v96
	v_add_u32_e32 v96, 0x50, v171
	s_nop 0
	v_cndmask_b32_e32 v87, v233, v87, vcc
	v_cmp_gt_i32_e32 vcc, s94, v96
	v_add_u32_e32 v96, 32, v96
	s_nop 0
	v_cndmask_b32_e32 v72, v233, v72, vcc
	v_cmp_gt_i32_e32 vcc, s94, v96
	v_add_u32_e32 v96, 0x51, v171
	s_nop 0
	v_cndmask_b32_e32 v88, v233, v88, vcc
	v_cmp_gt_i32_e32 vcc, s94, v96
	v_add_u32_e32 v96, 32, v96
	s_nop 0
	v_cndmask_b32_e32 v73, v233, v73, vcc
	v_cmp_gt_i32_e32 vcc, s94, v96
	v_add_u32_e32 v96, 0x52, v171
	s_nop 0
	v_cndmask_b32_e32 v89, v233, v89, vcc
	v_cmp_gt_i32_e32 vcc, s94, v96
	v_add_u32_e32 v96, 32, v96
	s_nop 0
	v_cndmask_b32_e32 v74, v233, v74, vcc
	v_cmp_gt_i32_e32 vcc, s94, v96
	v_add_u32_e32 v96, 0x53, v171
	s_nop 0
	v_cndmask_b32_e32 v90, v233, v90, vcc
	v_cmp_gt_i32_e32 vcc, s94, v96
	v_add_u32_e32 v96, 32, v96
	s_nop 0
	v_cndmask_b32_e32 v75, v233, v75, vcc
	v_cmp_gt_i32_e32 vcc, s94, v96
	v_add_u32_e32 v96, 0x58, v171
	s_nop 0
	v_cndmask_b32_e32 v91, v233, v91, vcc
	v_cmp_gt_i32_e32 vcc, s94, v96
	v_add_u32_e32 v96, 32, v96
	s_nop 0
	v_cndmask_b32_e32 v76, v233, v76, vcc
	v_cmp_gt_i32_e32 vcc, s94, v96
	v_add_u32_e32 v96, 0x59, v171
	s_nop 0
	v_cndmask_b32_e32 v92, v233, v92, vcc
	v_cmp_gt_i32_e32 vcc, s94, v96
	v_add_u32_e32 v96, 32, v96
	s_nop 0
	v_cndmask_b32_e32 v77, v233, v77, vcc
	v_cmp_gt_i32_e32 vcc, s94, v96
	v_add_u32_e32 v96, 0x5a, v171
	s_nop 0
	v_cndmask_b32_e32 v93, v233, v93, vcc
	v_cmp_gt_i32_e32 vcc, s94, v96
	v_add_u32_e32 v96, 32, v96
	s_nop 0
	v_cndmask_b32_e32 v78, v233, v78, vcc
	v_cmp_gt_i32_e32 vcc, s94, v96
	v_add_u32_e32 v96, 0x5b, v171
	s_nop 0
	v_cndmask_b32_e32 v94, v233, v94, vcc
	v_cmp_gt_i32_e32 vcc, s94, v96
	v_add_u32_e32 v96, 32, v96
	s_nop 0
	v_cndmask_b32_e32 v79, v233, v79, vcc
	v_cmp_gt_i32_e32 vcc, s94, v96
	s_nop 1
	v_cndmask_b32_e32 v95, v233, v95, vcc
.LBB0_371:
	v_mov_b32_e32 v96, v161
	v_ashrrev_i32_e32 v97, 4, v96
	v_and_b32_e32 v99, 0xfffff0, v97
	v_lshlrev_b32_e32 v100, 1, v97
	v_add_u32_e32 v98, 32, v97
	v_and_or_b32 v99, v100, 8, v99
	v_lshrrev_b32_e32 v100, 1, v97
	v_and_b32_e32 v97, 3, v97
	v_and_or_b32 v97, v100, 4, v97
	v_and_b32_e32 v100, 0xfffff0, v98
	v_lshlrev_b32_e32 v98, 1, v98
	v_and_or_b32 v98, v98, 8, v100
	v_lshrrev_b32_e32 v99, 1, v99
	v_bfe_u32 v101, v96, 2, 2
	v_lshrrev_b32_e32 v98, 1, v98
	v_or_b32_e32 v99, v99, v101
	v_lshlrev_b32_e32 v96, 4, v96
	v_or_b32_e32 v98, v98, v101
	v_lshlrev_b32_e32 v99, 9, v99
	v_lshlrev_b32_e32 v97, 6, v97
	v_and_b32_e32 v96, 48, v96
	v_lshlrev_b32_e32 v98, 9, v98
	v_or3_b32 v99, v99, v97, v96
	v_or3_b32 v96, v98, v97, v96
	s_waitcnt vmcnt(0)
	s_barrier
	s_waitcnt vmcnt(0)
	ds_write_b128 v99, v[112:115]
	ds_write_b128 v96, v[116:119]
	v_exp_f32_e32 v64, v64
	v_exp_f32_e32 v66, v66
	v_exp_f32_e32 v68, v68
	v_exp_f32_e32 v70, v70
	v_exp_f32_e32 v72, v72
	v_exp_f32_e32 v74, v74
	v_exp_f32_e32 v76, v76
	v_exp_f32_e32 v78, v78
	v_exp_f32_e32 v65, v65
	v_exp_f32_e32 v67, v67
	v_exp_f32_e32 v69, v69
	v_exp_f32_e32 v71, v71
	v_exp_f32_e32 v73, v73
	v_exp_f32_e32 v75, v75
	v_exp_f32_e32 v77, v77
	v_exp_f32_e32 v79, v79
	s_waitcnt lgkmcnt(0)
	s_barrier
; __device__ __forceinline__ void finishSM(f32x16& p0, f32x16& p1, float& l_reg, bf16x8& pa0, bf16x8& pa1, bf16x8& pa2, bf16x8& pa3) {
; #pragma unroll
;   for (int r = 0; r < 16; ++r) p1[r] = __builtin_amdgcn_exp2f(p1[r]);
;   float ps = 0;
; #pragma unroll
;   for (int r = 0; r < 16; ++r) ps += p0[r];
; #pragma unroll
;   for (int r = 0; r < 16; ++r) ps += p1[r];
;   { auto rr = __builtin_amdgcn_permlane32_swap(__float_as_uint(ps), __float_as_uint(ps), false, false);
;     ps = __uint_as_float(rr[0]) + __uint_as_float(rr[1]); }
;   l_reg += ps;
;     ...
;   PK4(p0, 0, pa0); PK4(p0, 8, pa1); PK4(p1, 0, pa2); PK4(p1, 8, pa3);
;     ...
; }
; template <int DQK, int QL>
; __device__ __forceinline__ void qkt(f32x16& p0, f32x16& p1, const char* Ks, const bf16x8 (&qr)[DQK / 16 - QL], const char* qlds, const int (&kofs)[4], float negM) {
;   constexpr int QR = DQK / 16 - QL;
; #pragma unroll
;   for (int r = 0; r < 16; ++r) { p0[r] = negM; p1[r] = negM; }
; #pragma unroll
;   for (int d0 = 0; d0 < DQK / 16; ++d0) {
;     const char* kp = Ks + kofs[d0 & 3] + (d0 >> 2) * 128;
;     bf16x8 b0 = *reinterpret_cast<const bf16x8*>(kp);
;     bf16x8 b1 = *reinterpret_cast<const bf16x8*>(kp + 32 * DQK * 2);
;     bf16x8 qf;
;     if constexpr (QL > 0) { if (d0 < QR) qf = qr[d0 < QR ? d0 : 0]; else qf = *reinterpret_cast<const bf16x8*>(qlds + (d0 - QR) * 1024); }
;     else qf = qr[d0];
;     p0 = __builtin_amdgcn_mfma_f32_32x32x16_bf16(b0, qf, p0, 0, 0, 0);
;     p1 = __builtin_amdgcn_mfma_f32_32x32x16_bf16(b1, qf, p1, 0, 0, 0);
;   }
	v_add_f32_e32 v96, 0, v64
	v_add_f32_e32 v96, v66, v96
	v_add_f32_e32 v179, v65, v67
	v_add_f32_e32 v96, v68, v96
	v_add_f32_e32 v179, v69, v179
	v_add_f32_e32 v96, v70, v96
	v_add_f32_e32 v179, v71, v179
	v_add_f32_e32 v96, v72, v96
	v_add_f32_e32 v179, v73, v179
	v_add_f32_e32 v96, v74, v96
	v_add_f32_e32 v179, v75, v179
	v_exp_f32_e32 v80, v80
	v_add_f32_e32 v96, v76, v96
	v_exp_f32_e32 v81, v81
	v_add_f32_e32 v179, v77, v179
	v_exp_f32_e32 v82, v82
	v_add_f32_e32 v96, v78, v96
	v_exp_f32_e32 v83, v83
	v_add_f32_e32 v179, v79, v179
	v_exp_f32_e32 v84, v84
	v_add_f32_e32 v96, v80, v96
	v_exp_f32_e32 v85, v85
	v_add_f32_e32 v179, v81, v179
	v_exp_f32_e32 v86, v86
	v_add_f32_e32 v96, v82, v96
	v_exp_f32_e32 v87, v87
	v_add_f32_e32 v179, v83, v179
	v_exp_f32_e32 v88, v88
	v_add_f32_e32 v96, v84, v96
	v_exp_f32_e32 v89, v89
	v_add_f32_e32 v179, v85, v179
	v_exp_f32_e32 v90, v90
	v_add_f32_e32 v96, v86, v96
	v_exp_f32_e32 v91, v91
	v_add_f32_e32 v179, v87, v179
	v_exp_f32_e32 v92, v92
	v_add_f32_e32 v96, v88, v96
	v_exp_f32_e32 v93, v93
	v_add_f32_e32 v179, v89, v179
	v_exp_f32_e32 v94, v94
	v_add_f32_e32 v96, v90, v96
	v_exp_f32_e32 v95, v95
	v_add_f32_e32 v179, v91, v179
	v_add_f32_e32 v96, v92, v96
	v_add_f32_e32 v179, v93, v179
	v_add_f32_e32 v96, v94, v96
	v_add_f32_e32 v179, v95, v179
	v_add_f32_e32 v179, v96, v179
	v_mov_b32_e32 v180, v179
	v_cvt_pk_bf16_f32 v120, v64, v65
	v_cvt_pk_bf16_f32 v121, v66, v67
	v_cvt_pk_bf16_f32 v122, v68, v69
	v_cvt_pk_bf16_f32 v123, v70, v71
	v_cvt_pk_bf16_f32 v124, v72, v73
	v_cvt_pk_bf16_f32 v125, v74, v75
	v_cvt_pk_bf16_f32 v126, v76, v77
	v_cvt_pk_bf16_f32 v127, v78, v79
	v_cvt_pk_bf16_f32 v142, v80, v81
	v_cvt_pk_bf16_f32 v143, v82, v83
	v_cvt_pk_bf16_f32 v144, v84, v85
	v_cvt_pk_bf16_f32 v145, v86, v87
	v_cvt_pk_bf16_f32 v146, v88, v89
	v_cvt_pk_bf16_f32 v147, v90, v91
	v_cvt_pk_bf16_f32 v148, v92, v93
	v_cvt_pk_bf16_f32 v149, v94, v95
	s_nop 1
	v_permlane32_swap_b32_e32 v179, v180
	v_permlane32_swap_b32_e32 v120, v122
	v_permlane32_swap_b32_e32 v121, v123
	v_permlane32_swap_b32_e32 v124, v126
	v_permlane32_swap_b32_e32 v125, v127
	v_permlane32_swap_b32_e32 v142, v144
	v_permlane32_swap_b32_e32 v143, v145
	v_permlane32_swap_b32_e32 v146, v148
	v_permlane32_swap_b32_e32 v147, v149
	ds_read_b128 v[64:67], v152 offset:32768
	ds_read_b128 v[172:175], v152 offset:45056
	v_mov_b64_e32 v[110:111], s[18:19]
	v_mov_b64_e32 v[108:109], s[16:17]
	v_mov_b64_e32 v[106:107], s[14:15]
	v_mov_b64_e32 v[104:105], s[12:13]
	v_mov_b64_e32 v[102:103], s[10:11]
	v_mov_b64_e32 v[100:101], s[8:9]
	v_mov_b64_e32 v[98:99], s[6:7]
	v_mov_b64_e32 v[96:97], s[4:5]
	s_waitcnt lgkmcnt(1)
	s_nop 0
	v_mfma_f32_32x32x16_bf16 v[80:95], v[64:67], v[138:141], v[96:111]
	s_waitcnt lgkmcnt(0)
	v_mfma_f32_32x32x16_bf16 v[64:79], v[172:175], v[138:141], v[96:111]
	s_nop 6
	ds_read_b128 v[96:99], v156 offset:32768
	ds_read_b128 v[100:103], v156 offset:45056
	s_waitcnt lgkmcnt(1)
	v_mfma_f32_32x32x16_bf16 v[80:95], v[96:99], v[134:137], v[80:95]
	s_waitcnt lgkmcnt(0)
	v_mfma_f32_32x32x16_bf16 v[64:79], v[100:103], v[134:137], v[64:79]
	ds_read_b128 v[96:99], v155 offset:32768
	ds_read_b128 v[100:103], v155 offset:45056
	s_waitcnt lgkmcnt(1)
	v_mfma_f32_32x32x16_bf16 v[80:95], v[96:99], v[130:133], v[80:95]
	s_waitcnt lgkmcnt(0)
	v_mfma_f32_32x32x16_bf16 v[64:79], v[100:103], v[130:133], v[64:79]
	ds_read_b128 v[96:99], v153 offset:32768
	ds_read_b128 v[100:103], v153 offset:45056
	ds_read_b128 v[104:107], v167
	s_waitcnt lgkmcnt(0)
	v_mfma_f32_32x32x16_bf16 v[80:95], v[96:99], v[104:107], v[80:95]
	v_mfma_f32_32x32x16_bf16 v[64:79], v[100:103], v[104:107], v[64:79]
	ds_read_b128 v[96:99], v152 offset:32896
	ds_read_b128 v[100:103], v152 offset:45184
	ds_read_b128 v[104:107], v167 offset:1024
	s_waitcnt lgkmcnt(0)
	v_mfma_f32_32x32x16_bf16 v[80:95], v[96:99], v[104:107], v[80:95]
	v_mfma_f32_32x32x16_bf16 v[64:79], v[100:103], v[104:107], v[64:79]
	ds_read_b128 v[96:99], v156 offset:32896
	ds_read_b128 v[100:103], v156 offset:45184
	ds_read_b128 v[104:107], v167 offset:2048
	s_waitcnt lgkmcnt(0)
	v_mfma_f32_32x32x16_bf16 v[80:95], v[96:99], v[104:107], v[80:95]
	v_mfma_f32_32x32x16_bf16 v[64:79], v[100:103], v[104:107], v[64:79]
	ds_read_b128 v[96:99], v155 offset:32896
	ds_read_b128 v[100:103], v155 offset:45184
	ds_read_b128 v[104:107], v167 offset:3072
	s_waitcnt lgkmcnt(0)
	v_mfma_f32_32x32x16_bf16 v[80:95], v[96:99], v[104:107], v[80:95]
	v_mfma_f32_32x32x16_bf16 v[64:79], v[100:103], v[104:107], v[64:79]
	ds_read_b128 v[96:99], v153 offset:32896
	ds_read_b128 v[100:103], v153 offset:45184
	ds_read_b128 v[104:107], v167 offset:4096
	s_waitcnt lgkmcnt(0)
	v_mfma_f32_32x32x16_bf16 v[80:95], v[96:99], v[104:107], v[80:95]
	v_mfma_f32_32x32x16_bf16 v[64:79], v[100:103], v[104:107], v[64:79]
	ds_read_b128 v[96:99], v152 offset:33024
	ds_read_b128 v[100:103], v152 offset:45312
	ds_read_b128 v[104:107], v167 offset:5120
	s_waitcnt lgkmcnt(0)
	v_mfma_f32_32x32x16_bf16 v[80:95], v[96:99], v[104:107], v[80:95]
	v_mfma_f32_32x32x16_bf16 v[64:79], v[100:103], v[104:107], v[64:79]
	ds_read_b128 v[96:99], v156 offset:33024
	ds_read_b128 v[100:103], v156 offset:45312
	ds_read_b128 v[104:107], v167 offset:6144
	s_waitcnt lgkmcnt(0)
	v_mfma_f32_32x32x16_bf16 v[80:95], v[96:99], v[104:107], v[80:95]
	v_mfma_f32_32x32x16_bf16 v[64:79], v[100:103], v[104:107], v[64:79]
	ds_read_b128 v[96:99], v155 offset:33024
	ds_read_b128 v[100:103], v155 offset:45312
	ds_read_b128 v[104:107], v167 offset:7168
	s_waitcnt lgkmcnt(0)
	v_mfma_f32_32x32x16_bf16 v[80:95], v[96:99], v[104:107], v[80:95]
	v_mfma_f32_32x32x16_bf16 v[64:79], v[100:103], v[104:107], v[64:79]
	ds_read_b128 v[96:99], v153 offset:33024
	ds_read_b128 v[100:103], v153 offset:45312
	ds_read_b128 v[104:107], v167 offset:8192
	s_waitcnt lgkmcnt(0)
	v_mfma_f32_32x32x16_bf16 v[80:95], v[96:99], v[104:107], v[80:95]
	v_mfma_f32_32x32x16_bf16 v[64:79], v[100:103], v[104:107], v[64:79]
	s_cmp_lt_u32 s3, s58
	s_cselect_b64 s[22:23], -1, 0
	s_cmp_ge_u32 s3, s58
	s_cselect_b64 s[20:21], -1, 0
	s_and_b64 vcc, exec, s[20:21]
	s_cbranch_vccnz .LBB0_373
	s_add_u32 s100, s72, s48
	s_addc_u32 s101, s73, s49
	v_readfirstlane_b32 s38, v168
	s_mov_b32 m0, s38
	s_nop 0
	global_load_lds_dwordx4 v235, s[100:101]
	s_add_i32 m0, s38, 0x2000
	s_nop 0
	global_load_lds_dwordx4 v236, s[100:101]
	s_add_i32 m0, s38, 0x4000
	s_nop 0
	global_load_lds_dwordx4 v237, s[100:101]
	s_add_u32 s100, s74, 0xd2bc000
	s_addc_u32 s101, s75, 0
	global_load_dwordx4 v[112:115], v232, s[100:101] offset:256
	s_add_u32 s100, s100, 0x8000
	s_addc_u32 s101, s101, 0
	global_load_dwordx4 v[116:119], v232, s[100:101] offset:256

; __device__ __forceinline__ void finishSM(f32x16& p0, f32x16& p1, float& l_reg, bf16x8& pa0, bf16x8& pa1, bf16x8& pa2, bf16x8& pa3) {
; #pragma unroll
;   for (int r = 0; r < 16; ++r) p1[r] = __builtin_amdgcn_exp2f(p1[r]);
;   float ps = 0;
; #pragma unroll
;   for (int r = 0; r < 16; ++r) ps += p0[r];
; #pragma unroll
;   for (int r = 0; r < 16; ++r) ps += p1[r];
;   { auto rr = __builtin_amdgcn_permlane32_swap(__float_as_uint(ps), __float_as_uint(ps), false, false);
;     ps = __uint_as_float(rr[0]) + __uint_as_float(rr[1]); }
;   l_reg += ps;
;     ...
;   PK4(p0, 0, pa0); PK4(p0, 8, pa1); PK4(p1, 0, pa2); PK4(p1, 8, pa3);
;     ...
; }
; template <int DQK, int QL>
; __device__ __forceinline__ void qkt(f32x16& p0, f32x16& p1, const char* Ks, const bf16x8 (&qr)[DQK / 16 - QL], const char* qlds, const int (&kofs)[4], float negM) {
;   constexpr int QR = DQK / 16 - QL;
; #pragma unroll
;   for (int r = 0; r < 16; ++r) { p0[r] = negM; p1[r] = negM; }
; #pragma unroll
;   for (int d0 = 0; d0 < DQK / 16; ++d0) {
;     const char* kp = Ks + kofs[d0 & 3] + (d0 >> 2) * 128;
;     bf16x8 b0 = *reinterpret_cast<const bf16x8*>(kp);
;     bf16x8 b1 = *reinterpret_cast<const bf16x8*>(kp + 32 * DQK * 2);
;     bf16x8 qf;
;     if constexpr (QL > 0) { if (d0 < QR) qf = qr[d0 < QR ? d0 : 0]; else qf = *reinterpret_cast<const bf16x8*>(qlds + (d0 - QR) * 1024); }
;     else qf = qr[d0];
;     p0 = __builtin_amdgcn_mfma_f32_32x32x16_bf16(b0, qf, p0, 0, 0, 0);
;     p1 = __builtin_amdgcn_mfma_f32_32x32x16_bf16(b1, qf, p1, 0, 0, 0);
;   }
; }
; template <int NCB> __device__ __forceinline__ int v_st(int k, int c) {
;   const int kk = (k & ~0xC) | ((k & 4) << 1) | ((k & 8) >> 1);
;   return ((kk >> 3) * NCB + (c >> 5)) * 512 + ((kk & 7) * 32 + (c & 31)) * 2;
; }
; __device__ __forceinline__ int v_rd_base(int lane) { return ((lane & 3) << 3) | (((lane >> 2) & 3) << 6) | (((lane >> 4) & 1) << 5) | (((lane >> 5) & 1) << 8); }
; template <int OFF> __device__ __forceinline__ s16x4 tr_read(int vb) {
;   s16x4 r; asm volatile("ds_read_b64_tr_b16 %0, %1 offset:%2" : "=&v"(r) : "v"(vb), "i"(OFF) : "memory"); return r;
; }
; template <int NCB, int D0> __device__ __forceinline__ void pv_one(f32x16& od, int vb, bf16x8 pa0, bf16x8 pa1, bf16x8 pa2, bf16x8 pa3) {
;   constexpr int KSTEP = NCB * 1024, HALF = NCB * 512, B0 = D0 * 512;
.LBB0_398:
	ds_read_b128 v[96:99], v169 offset:40960
	s_waitcnt vmcnt(0)
	ds_read_b128 v[154:157], v169 offset:45056
	v_mov_b64_e32 v[126:127], s[18:19]
	v_mov_b64_e32 v[124:125], s[16:17]
	v_mov_b64_e32 v[122:123], s[14:15]
	v_mov_b64_e32 v[120:121], s[12:13]
	v_mov_b64_e32 v[118:119], s[10:11]
	v_mov_b64_e32 v[116:117], s[8:9]
	v_mov_b64_e32 v[114:115], s[6:7]
	v_mov_b64_e32 v[112:113], s[4:5]
	v_exp_f32_e32 v100, v68
	v_exp_f32_e32 v101, v69
	s_waitcnt lgkmcnt(1)
	v_mfma_f32_32x32x16_bf16 v[80:95], v[96:99], v[142:145], v[112:127]
	ds_read_b128 v[96:99], v168 offset:40960
	ds_read_b128 v[178:181], v168 offset:45056
	v_exp_f32_e32 v102, v70
	v_exp_f32_e32 v103, v71
	v_exp_f32_e32 v190, v72
	v_exp_f32_e32 v191, v73
	v_exp_f32_e32 v192, v74
	v_exp_f32_e32 v193, v75
	s_waitcnt lgkmcnt(1)
	v_mfma_f32_32x32x16_bf16 v[80:95], v[96:99], v[138:141], v[80:95]
	ds_read_b128 v[96:99], v167 offset:40960
	ds_read_b128 v[182:185], v167 offset:45056
	v_exp_f32_e32 v194, v76
	v_exp_f32_e32 v195, v77
	v_exp_f32_e32 v196, v78
	v_exp_f32_e32 v79, v79
	s_waitcnt lgkmcnt(1)
	v_mfma_f32_32x32x16_bf16 v[80:95], v[96:99], v[134:137], v[80:95]
	ds_read_b128 v[96:99], v166 offset:40960
	ds_read_b128 v[186:189], v166 offset:45056
	s_waitcnt lgkmcnt(1)
	v_mfma_f32_32x32x16_bf16 v[80:95], v[96:99], v[130:133], v[80:95]
	v_exp_f32_e32 v96, v64
	v_add_f32_e32 v64, 0, v152
	v_add_f32_e32 v64, v150, v64
	v_add_f32_e32 v176, v153, v151
	v_add_f32_e32 v64, v148, v64
	v_add_f32_e32 v176, v149, v176
	v_add_f32_e32 v64, v146, v64
	v_add_f32_e32 v176, v147, v176
	v_add_f32_e32 v64, v110, v64
	v_add_f32_e32 v176, v111, v176
	v_add_f32_e32 v64, v108, v64
	v_add_f32_e32 v176, v109, v176
	v_add_f32_e32 v64, v106, v64
	v_exp_f32_e32 v97, v65
	v_add_f32_e32 v176, v107, v176
	v_exp_f32_e32 v98, v66
	v_add_f32_e32 v64, v104, v64
	v_exp_f32_e32 v99, v67
	v_add_f32_e32 v176, v105, v176
	v_add_f32_e32 v64, v96, v64
	v_add_f32_e32 v176, v97, v176
	v_add_f32_e32 v64, v98, v64
	v_add_f32_e32 v176, v99, v176
	v_add_f32_e32 v64, v100, v64
	v_add_f32_e32 v176, v101, v176
	v_add_f32_e32 v64, v102, v64
	v_add_f32_e32 v176, v103, v176
	v_add_f32_e32 v64, v190, v64
	v_add_f32_e32 v176, v191, v176
	v_add_f32_e32 v64, v192, v64
	v_add_f32_e32 v176, v193, v176
	v_add_f32_e32 v64, v194, v64
	v_add_f32_e32 v176, v195, v176
	v_add_f32_e32 v64, v196, v64
	v_add_f32_e32 v176, v79, v176
	v_add_f32_e32 v176, v64, v176
	v_mov_b32_e32 v177, v176
	s_nop 1
	v_permlane32_swap_b32_e32 v176, v177
	v_cvt_pk_bf16_f32 v64, v152, v153
	v_cvt_pk_bf16_f32 v65, v150, v151
	v_cvt_pk_bf16_f32 v66, v148, v149
	v_cvt_pk_bf16_f32 v67, v146, v147
	v_cvt_pk_bf16_f32 v68, v110, v111
	v_cvt_pk_bf16_f32 v69, v108, v109
	v_cvt_pk_bf16_f32 v70, v106, v107
	v_cvt_pk_bf16_f32 v71, v104, v105
	v_cvt_pk_bf16_f32 v72, v96, v97
	v_cvt_pk_bf16_f32 v73, v98, v99
	v_cvt_pk_bf16_f32 v74, v100, v101
	v_cvt_pk_bf16_f32 v75, v102, v103
	v_cvt_pk_bf16_f32 v76, v190, v191
	v_cvt_pk_bf16_f32 v77, v192, v193
	v_cvt_pk_bf16_f32 v78, v194, v195
	v_cvt_pk_bf16_f32 v79, v196, v79
	s_nop 0
	v_permlane32_swap_b32_e32 v64, v66
	v_permlane32_swap_b32_e32 v65, v67
	v_permlane32_swap_b32_e32 v68, v70
	v_permlane32_swap_b32_e32 v69, v71
	v_permlane32_swap_b32_e32 v72, v74
	v_permlane32_swap_b32_e32 v73, v75
	v_permlane32_swap_b32_e32 v76, v78
	v_permlane32_swap_b32_e32 v77, v79
	s_add_i32 s68, s69, 0x80
	v_mfma_f32_32x32x16_bf16 v[96:111], v[154:157], v[142:145], v[112:127]
	s_mul_i32 s39, s68, 0xc00
	s_mul_hi_i32 s38, s68, 0xc00
	s_nop 4
	v_mad_i64_i32 v[112:113], s[20:21], s68, v236, v[162:163]
	s_add_u32 s20, s3, s39
	s_addc_u32 s21, s36, s38
	v_lshl_add_u64 v[116:117], v[160:161], 1, s[20:21]
	v_lshl_add_u64 v[114:115], v[158:159], 1, s[20:21]
	global_load_dwordx4 v[146:149], v[112:113], off offset:1024
	global_load_dwordx4 v[150:153], v[114:115], off offset:2048
	global_load_dwordx4 v[154:157], v[116:117], off offset:2048
	v_mfma_f32_32x32x16_bf16 v[96:111], v[178:181], v[138:141], v[96:111]
	v_mfma_f32_32x32x16_bf16 v[96:111], v[182:185], v[134:137], v[96:111]
	s_waitcnt lgkmcnt(0)
	v_mfma_f32_32x32x16_bf16 v[96:111], v[186:189], v[130:133], v[96:111]
	ds_read_b64_tr_b16 v[112:113], v171 offset:0
	ds_read_b64_tr_b16 v[114:115], v171 offset:0x800
	ds_read_b64_tr_b16 v[116:117], v171 offset:0x1000
	ds_read_b64_tr_b16 v[118:119], v171 offset:0x1800
	ds_read_b64_tr_b16 v[120:121], v171 offset:0x2000
	ds_read_b64_tr_b16 v[122:123], v171 offset:0x2800
	ds_read_b64_tr_b16 v[124:125], v171 offset:0x3000
	ds_read_b64_tr_b16 v[126:127], v171 offset:0x3800
	s_nop 0
	s_waitcnt lgkmcnt(6)
	v_mfma_f32_32x32x16_bf16 v[0:15], v[64:67], v[112:115], v[0:15]
	ds_read_b64_tr_b16 v[112:113], v171 offset:0x200
	ds_read_b64_tr_b16 v[114:115], v171 offset:0xa00
	s_waitcnt lgkmcnt(6)
	v_mfma_f32_32x32x16_bf16 v[0:15], v[68:71], v[116:119], v[0:15]
	ds_read_b64_tr_b16 v[116:117], v171 offset:0x1200
	ds_read_b64_tr_b16 v[118:119], v171 offset:0x1a00
	s_waitcnt lgkmcnt(6)
	v_mfma_f32_32x32x16_bf16 v[0:15], v[72:75], v[120:123], v[0:15]
	ds_read_b64_tr_b16 v[120:121], v171 offset:0x2200
	ds_read_b64_tr_b16 v[122:123], v171 offset:0x2a00
	s_waitcnt lgkmcnt(6)
	v_mfma_f32_32x32x16_bf16 v[0:15], v[76:79], v[124:127], v[0:15]
	ds_read_b64_tr_b16 v[124:125], v171 offset:0x3200
	ds_read_b64_tr_b16 v[126:127], v171 offset:0x3a00
	s_waitcnt lgkmcnt(6)
	v_mfma_f32_32x32x16_bf16 v[48:63], v[64:67], v[112:115], v[48:63]
	ds_read_b64_tr_b16 v[112:113], v171 offset:0x400
	ds_read_b64_tr_b16 v[114:115], v171 offset:0xc00
	s_waitcnt lgkmcnt(6)
	v_mfma_f32_32x32x16_bf16 v[48:63], v[68:71], v[116:119], v[48:63]
	ds_read_b64_tr_b16 v[116:117], v171 offset:0x1400
	ds_read_b64_tr_b16 v[118:119], v171 offset:0x1c00
	s_waitcnt lgkmcnt(6)
; #define WAIT_L0() asm volatile("s_waitcnt lgkmcnt(0)" ::: "memory")
; #define SBAR() __builtin_amdgcn_sched_barrier(0)
; __device__ __forceinline__ int crow(int r, int hi) { return (r & 3) + 8 * (r >> 2) + 4 * hi; }
; template <bool GM>
; __device__ __forceinline__ void partialSM(f32x16& p0, f32x16& p1, bool mask, int kbase, int L, int qpos, int hi) {
;   if (mask) {
; #pragma unroll
;     for (int r = 0; r < 16; ++r) {
;       int k = kbase + crow(r, hi);
;       asm volatile("" : "+v"(k) : "v"(p0[r]));
;       bool ok = k < L;
;       if (GM) ok = ok && (k < 16 || abs(qpos - k) <= 128);
;       p0[r] = ok ? p0[r] : -1e30f;
;       int k2 = k + 32;
;       asm volatile("" : "+v"(k2) : "v"(p1[r]));
;       bool ok2 = k2 < L;
;       if (GM) ok2 = ok2 && (k2 < 16 || abs(qpos - k2) <= 128);
;       p1[r] = ok2 ? p1[r] : -1e30f;
;     }
;   }
; template <int NCB, int D0> __device__ __forceinline__ void pv_one(f32x16& od, int vb, bf16x8 pa0, bf16x8 pa1, bf16x8 pa2, bf16x8 pa3) {
;   constexpr int KSTEP = NCB * 1024, HALF = NCB * 512, B0 = D0 * 512;
;   const s16x4 l0 = tr_read<B0>(vb), h0 = tr_read<B0 + HALF>(vb), l1 = tr_read<B0 + KSTEP>(vb), h1 = tr_read<B0 + KSTEP + HALF>(vb);
;   const s16x4 l2 = tr_read<B0 + 2 * KSTEP>(vb), h2 = tr_read<B0 + 2 * KSTEP + HALF>(vb), l3 = tr_read<B0 + 3 * KSTEP>(vb), h3 = tr_read<B0 + 3 * KSTEP + HALF>(vb);
;   WAIT_L0(); SBAR();
;     ...
;   od = __builtin_amdgcn_mfma_f32_32x32x16_bf16(pa0, PK(l0, h0), od, 0, 0, 0);
;   od = __builtin_amdgcn_mfma_f32_32x32x16_bf16(pa1, PK(l1, h1), od, 0, 0, 0);
;   od = __builtin_amdgcn_mfma_f32_32x32x16_bf16(pa2, PK(l2, h2), od, 0, 0, 0);
;   od = __builtin_amdgcn_mfma_f32_32x32x16_bf16(pa3, PK(l3, h3), od, 0, 0, 0);
;     ...
; }
; template <int NCB> __device__ __forceinline__ void pv_all(f32x16 (&o)[NCB], int vb, bf16x8 pa0, bf16x8 pa1, bf16x8 pa2, bf16x8 pa3) {
;   pv_one<NCB, 0>(o[0], vb, pa0, pa1, pa2, pa3); pv_one<NCB, 1>(o[1], vb, pa0, pa1, pa2, pa3);
;   if constexpr (NCB == 4) { pv_one<NCB, 2>(o[2], vb, pa0, pa1, pa2, pa3); pv_one<NCB, 3>(o[3], vb, pa0, pa1, pa2, pa3); }
	v_mfma_f32_32x32x16_bf16 v[48:63], v[72:75], v[120:123], v[48:63]
	ds_read_b64_tr_b16 v[120:121], v171 offset:0x2400
	ds_read_b64_tr_b16 v[122:123], v171 offset:0x2c00
	s_waitcnt lgkmcnt(6)
	v_mfma_f32_32x32x16_bf16 v[48:63], v[76:79], v[124:127], v[48:63]
	ds_read_b64_tr_b16 v[124:125], v171 offset:0x3400
	ds_read_b64_tr_b16 v[126:127], v171 offset:0x3c00
	s_waitcnt lgkmcnt(6)
	v_mfma_f32_32x32x16_bf16 v[32:47], v[64:67], v[112:115], v[32:47]
	ds_read_b64_tr_b16 v[112:113], v171 offset:0x600
	ds_read_b64_tr_b16 v[114:115], v171 offset:0xe00
	s_waitcnt lgkmcnt(6)
	v_mfma_f32_32x32x16_bf16 v[32:47], v[68:71], v[116:119], v[32:47]
	ds_read_b64_tr_b16 v[116:117], v171 offset:0x1600
	ds_read_b64_tr_b16 v[118:119], v171 offset:0x1e00
	s_waitcnt lgkmcnt(6)
	v_mfma_f32_32x32x16_bf16 v[32:47], v[72:75], v[120:123], v[32:47]
	ds_read_b64_tr_b16 v[120:121], v171 offset:0x2600
	ds_read_b64_tr_b16 v[122:123], v171 offset:0x2e00
	s_waitcnt lgkmcnt(6)
	v_mfma_f32_32x32x16_bf16 v[32:47], v[76:79], v[124:127], v[32:47]
	ds_read_b64_tr_b16 v[124:125], v171 offset:0x3600
	ds_read_b64_tr_b16 v[126:127], v171 offset:0x3e00
	s_waitcnt lgkmcnt(6)
	v_mfma_f32_32x32x16_bf16 v[16:31], v[64:67], v[112:115], v[16:31]
	s_add_i32 s20, s69, 64
	s_cmp_le_i32 s20, s59
	v_add_u32_e32 v178, s69, v175
	s_waitcnt lgkmcnt(4)
	v_mfma_f32_32x32x16_bf16 v[16:31], v[68:71], v[116:119], v[16:31]
	s_waitcnt lgkmcnt(2)
	v_mfma_f32_32x32x16_bf16 v[16:31], v[72:75], v[120:123], v[16:31]
	s_waitcnt lgkmcnt(0)
	v_mfma_f32_32x32x16_bf16 v[16:31], v[76:79], v[124:127], v[16:31]
	s_cbranch_scc1 .LBB0_400
	v_add_u32_e32 v64, 64, v178
	s_nop 0
	v_cmp_gt_i32_e32 vcc, s94, v64
	v_add_u32_e32 v64, 32, v64
	s_nop 0
	v_cndmask_b32_e32 v80, v233, v80, vcc
	v_cmp_gt_i32_e32 vcc, s94, v64
	v_add_u32_e32 v64, 0x41, v178
	s_nop 0
	v_cndmask_b32_e32 v96, v233, v96, vcc
	v_cmp_gt_i32_e32 vcc, s94, v64
	v_add_u32_e32 v64, 32, v64
	s_nop 0
	v_cndmask_b32_e32 v81, v233, v81, vcc
	v_cmp_gt_i32_e32 vcc, s94, v64
	v_add_u32_e32 v64, 0x42, v178
	s_nop 0
	v_cndmask_b32_e32 v97, v233, v97, vcc
	v_cmp_gt_i32_e32 vcc, s94, v64
	v_add_u32_e32 v64, 32, v64
	s_nop 0
	v_cndmask_b32_e32 v82, v233, v82, vcc
	v_cmp_gt_i32_e32 vcc, s94, v64
	v_add_u32_e32 v64, 0x43, v178
	s_nop 0
	v_cndmask_b32_e32 v98, v233, v98, vcc
	v_cmp_gt_i32_e32 vcc, s94, v64
	v_add_u32_e32 v64, 32, v64
	s_nop 0
	v_cndmask_b32_e32 v83, v233, v83, vcc
	v_cmp_gt_i32_e32 vcc, s94, v64
	v_add_u32_e32 v64, 0x48, v178
	s_nop 0
	v_cndmask_b32_e32 v99, v233, v99, vcc
	v_cmp_gt_i32_e32 vcc, s94, v64
	v_add_u32_e32 v64, 32, v64
	s_nop 0
	v_cndmask_b32_e32 v84, v233, v84, vcc
	v_cmp_gt_i32_e32 vcc, s94, v64
	v_add_u32_e32 v64, 0x49, v178
	s_nop 0
	v_cndmask_b32_e32 v100, v233, v100, vcc
	v_cmp_gt_i32_e32 vcc, s94, v64
	v_add_u32_e32 v64, 32, v64
	s_nop 0
	v_cndmask_b32_e32 v85, v233, v85, vcc
	v_cmp_gt_i32_e32 vcc, s94, v64
	v_add_u32_e32 v64, 0x4a, v178
	s_nop 0
	v_cndmask_b32_e32 v101, v233, v101, vcc
	v_cmp_gt_i32_e32 vcc, s94, v64
	v_add_u32_e32 v64, 32, v64
	s_nop 0
	v_cndmask_b32_e32 v86, v233, v86, vcc
	v_cmp_gt_i32_e32 vcc, s94, v64
	v_add_u32_e32 v64, 0x4b, v178
	s_nop 0
	v_cndmask_b32_e32 v102, v233, v102, vcc
	v_cmp_gt_i32_e32 vcc, s94, v64
	v_add_u32_e32 v64, 32, v64
	s_nop 0
	v_cndmask_b32_e32 v87, v233, v87, vcc
	v_cmp_gt_i32_e32 vcc, s94, v64
	v_add_u32_e32 v64, 0x50, v178
	s_nop 0
	v_cndmask_b32_e32 v103, v233, v103, vcc
	v_cmp_gt_i32_e32 vcc, s94, v64
	v_add_u32_e32 v64, 32, v64
	s_nop 0
	v_cndmask_b32_e32 v88, v233, v88, vcc
	v_cmp_gt_i32_e32 vcc, s94, v64
	v_add_u32_e32 v64, 0x51, v178
	s_nop 0
	v_cndmask_b32_e32 v104, v233, v104, vcc
	v_cmp_gt_i32_e32 vcc, s94, v64
	v_add_u32_e32 v64, 32, v64
	s_nop 0
	v_cndmask_b32_e32 v89, v233, v89, vcc
	v_cmp_gt_i32_e32 vcc, s94, v64
	v_add_u32_e32 v64, 0x52, v178
	s_nop 0
	v_cndmask_b32_e32 v105, v233, v105, vcc
	v_cmp_gt_i32_e32 vcc, s94, v64
	v_add_u32_e32 v64, 32, v64
	s_nop 0
	v_cndmask_b32_e32 v90, v233, v90, vcc
	v_cmp_gt_i32_e32 vcc, s94, v64
	v_add_u32_e32 v64, 0x53, v178
	s_nop 0
	v_cndmask_b32_e32 v106, v233, v106, vcc
	v_cmp_gt_i32_e32 vcc, s94, v64
	v_add_u32_e32 v64, 32, v64
	s_nop 0
	v_cndmask_b32_e32 v91, v233, v91, vcc
	v_cmp_gt_i32_e32 vcc, s94, v64
	v_add_u32_e32 v64, 0x58, v178
	s_nop 0
	v_cndmask_b32_e32 v107, v233, v107, vcc
	v_cmp_gt_i32_e32 vcc, s94, v64
	v_add_u32_e32 v64, 32, v64
	s_nop 0
	v_cndmask_b32_e32 v92, v233, v92, vcc
	v_cmp_gt_i32_e32 vcc, s94, v64
	v_add_u32_e32 v64, 0x59, v178
	s_nop 0
	v_cndmask_b32_e32 v108, v233, v108, vcc
	v_cmp_gt_i32_e32 vcc, s94, v64
	v_add_u32_e32 v64, 32, v64
	s_nop 0
	v_cndmask_b32_e32 v93, v233, v93, vcc
	v_cmp_gt_i32_e32 vcc, s94, v64
	v_add_u32_e32 v64, 0x5a, v178
	s_nop 0
	v_cndmask_b32_e32 v109, v233, v109, vcc
	v_cmp_gt_i32_e32 vcc, s94, v64
	v_add_u32_e32 v64, 32, v64
	s_nop 0
	v_cndmask_b32_e32 v94, v233, v94, vcc
	v_cmp_gt_i32_e32 vcc, s94, v64
	v_add_u32_e32 v64, 0x5b, v178
	s_nop 0
	v_cndmask_b32_e32 v110, v233, v110, vcc
	v_cmp_gt_i32_e32 vcc, s94, v64
	v_add_u32_e32 v64, 32, v64
	s_nop 0
	v_cndmask_b32_e32 v95, v233, v95, vcc
	v_cmp_gt_i32_e32 vcc, s94, v64
	s_nop 1
	v_cndmask_b32_e32 v111, v233, v111, vcc
; #define WAIT_V0() asm volatile("s_waitcnt vmcnt(0)" ::: "memory")
; #define SBAR() __builtin_amdgcn_sched_barrier(0)
; #define SWRITE(b) do { FRESH_COORDS(); \
;     if constexpr (!KDMA) { _Pragma("unroll") for (int i = 0; i < KC; ++i) *reinterpret_cast<bf16x8*>(shm + (b) * SHM_K + klo[i]) = ks[i]; } \
;     _Pragma("unroll") for (int i = 0; i < VC; ++i) *reinterpret_cast<bf16x8*>(shm + (b) * SHM_V + vlo[i]) = vs[i]; } while (0)
; #define QKT(P0, P1, BUF) qkt<DQK, QL>(P0, P1, shm + K_OFF + (BUF) * SHM_K, qr, qlds, kofs, negM)
; __device__ __forceinline__ void finishSM(f32x16& p0, f32x16& p1, float& l_reg, bf16x8& pa0, bf16x8& pa1, bf16x8& pa2, bf16x8& pa3) {
; #pragma unroll
;   for (int r = 0; r < 16; ++r) p1[r] = __builtin_amdgcn_exp2f(p1[r]);
;   float ps = 0;
; #pragma unroll
;   for (int r = 0; r < 16; ++r) ps += p0[r];
; #pragma unroll
;   for (int r = 0; r < 16; ++r) ps += p1[r];
;   { auto rr = __builtin_amdgcn_permlane32_swap(__float_as_uint(ps), __float_as_uint(ps), false, false);
;     ps = __uint_as_float(rr[0]) + __uint_as_float(rr[1]); }
;   l_reg += ps;
;     ...
;   PK4(p0, 0, pa0); PK4(p0, 8, pa1); PK4(p1, 0, pa2); PK4(p1, 8, pa3);
;     ...
; }
; template <int DQK, int QL>
; __device__ __forceinline__ void qkt(f32x16& p0, f32x16& p1, const char* Ks, const bf16x8 (&qr)[DQK / 16 - QL], const char* qlds, const int (&kofs)[4], float negM) {
;   constexpr int QR = DQK / 16 - QL;
; #pragma unroll
;   for (int r = 0; r < 16; ++r) { p0[r] = negM; p1[r] = negM; }
; #pragma unroll
;   for (int d0 = 0; d0 < DQK / 16; ++d0) {
;     const char* kp = Ks + kofs[d0 & 3] + (d0 >> 2) * 128;
;     bf16x8 b0 = *reinterpret_cast<const bf16x8*>(kp);
;     bf16x8 b1 = *reinterpret_cast<const bf16x8*>(kp + 32 * DQK * 2);
;     bf16x8 qf;
;     if constexpr (QL > 0) { if (d0 < QR) qf = qr[d0 < QR ? d0 : 0]; else qf = *reinterpret_cast<const bf16x8*>(qlds + (d0 - QR) * 1024); }
;     else qf = qr[d0];
;     p0 = __builtin_amdgcn_mfma_f32_32x32x16_bf16(b0, qf, p0, 0, 0, 0);
;     p1 = __builtin_amdgcn_mfma_f32_32x32x16_bf16(b1, qf, p1, 0, 0, 0);
;   }
;     ...
;     __syncthreads(); WAIT_V0(); SWRITE(0);
;     __syncthreads();
;     SBAR();
;     if constexpr (ONEP) { finishSM(pB0, pB1, l_reg, pa0, pa1, pa2, pa3); SBAR(); QKT(pA0, pA1, 0); }
;     else { QKT(pA0, pA1, 0); finishSM(pB0, pB1, l_reg, pa0, pa1, pa2, pa3); }
;     SBAR();
;     if (j + 2 < NT) SLOAD(TKEY(j + 2), 1);
.LBB0_400:
	s_barrier
	s_waitcnt vmcnt(0)
	s_waitcnt vmcnt(2)
	ds_write_b128 v174, v[146:149] offset:32768
	s_waitcnt vmcnt(1)
	ds_write_b128 v172, v[150:153]
	s_waitcnt vmcnt(0)
	ds_write_b128 v173, v[154:157]
	v_exp_f32_e32 v179, v80
	v_exp_f32_e32 v184, v81
	v_exp_f32_e32 v185, v82
	v_exp_f32_e32 v186, v83
	v_exp_f32_e32 v187, v84
	v_exp_f32_e32 v188, v85
	v_exp_f32_e32 v189, v86
	v_exp_f32_e32 v190, v87
	v_exp_f32_e32 v191, v88
	v_exp_f32_e32 v192, v89
	v_exp_f32_e32 v193, v90
	v_exp_f32_e32 v194, v91
	v_exp_f32_e32 v195, v92
	v_exp_f32_e32 v196, v93
	v_exp_f32_e32 v197, v94
	v_exp_f32_e32 v198, v95
	s_waitcnt lgkmcnt(0)
	s_barrier
	ds_read_b128 v[64:67], v169 offset:32768
	ds_read_b128 v[180:183], v169 offset:36864
	v_mov_b64_e32 v[126:127], s[18:19]
	v_mov_b64_e32 v[124:125], s[16:17]
	v_mov_b64_e32 v[122:123], s[14:15]
	v_mov_b64_e32 v[120:121], s[12:13]
	v_mov_b64_e32 v[118:119], s[10:11]
	v_mov_b64_e32 v[116:117], s[8:9]
	v_mov_b64_e32 v[114:115], s[6:7]
	v_mov_b64_e32 v[112:113], s[4:5]
	v_exp_f32_e32 v111, v111
	s_waitcnt lgkmcnt(1)
	v_mfma_f32_32x32x16_bf16 v[80:95], v[64:67], v[142:145], v[112:127]
	s_waitcnt lgkmcnt(0)
	v_mfma_f32_32x32x16_bf16 v[64:79], v[180:183], v[142:145], v[112:127]
	s_nop 6
	ds_read_b128 v[112:115], v168 offset:32768
	ds_read_b128 v[116:119], v168 offset:36864
	v_exp_f32_e32 v120, v102
	v_exp_f32_e32 v121, v103
	v_exp_f32_e32 v122, v104
	v_exp_f32_e32 v123, v105
	v_exp_f32_e32 v124, v106
	v_exp_f32_e32 v125, v107
	s_waitcnt lgkmcnt(1)
	v_mfma_f32_32x32x16_bf16 v[80:95], v[112:115], v[138:141], v[80:95]
	v_exp_f32_e32 v126, v108
	v_exp_f32_e32 v127, v109
	v_exp_f32_e32 v180, v110
	s_waitcnt lgkmcnt(0)
	v_mfma_f32_32x32x16_bf16 v[64:79], v[116:119], v[138:141], v[64:79]
	ds_read_b128 v[112:115], v167 offset:32768
	ds_read_b128 v[116:119], v167 offset:36864
	s_waitcnt lgkmcnt(1)
	v_mfma_f32_32x32x16_bf16 v[80:95], v[112:115], v[134:137], v[80:95]
	s_waitcnt lgkmcnt(0)
	v_mfma_f32_32x32x16_bf16 v[64:79], v[116:119], v[134:137], v[64:79]
	ds_read_b128 v[112:115], v166 offset:32768
	ds_read_b128 v[116:119], v166 offset:36864
	s_waitcnt lgkmcnt(1)
	v_mfma_f32_32x32x16_bf16 v[80:95], v[112:115], v[130:133], v[80:95]
	v_exp_f32_e32 v114, v96
	v_add_f32_e32 v96, 0, v179
	v_add_f32_e32 v96, v185, v96
	v_add_f32_e32 v112, v184, v186
	v_add_f32_e32 v96, v187, v96
	v_add_f32_e32 v112, v188, v112
	v_add_f32_e32 v96, v189, v96
	v_add_f32_e32 v112, v190, v112
	v_add_f32_e32 v96, v191, v96
	v_add_f32_e32 v112, v192, v112
	v_add_f32_e32 v96, v193, v96
	v_add_f32_e32 v112, v194, v112
	v_add_f32_e32 v96, v195, v96
	v_exp_f32_e32 v115, v97
	v_add_f32_e32 v112, v196, v112
	s_waitcnt lgkmcnt(0)
	v_mfma_f32_32x32x16_bf16 v[64:79], v[116:119], v[130:133], v[64:79]
	v_exp_f32_e32 v116, v98
	v_add_f32_e32 v96, v197, v96
	v_exp_f32_e32 v117, v99
	v_add_f32_e32 v112, v198, v112
	v_exp_f32_e32 v118, v100
	v_add_f32_e32 v96, v114, v96
	v_exp_f32_e32 v119, v101
	v_add_f32_e32 v112, v115, v112
	v_add_f32_e32 v96, v116, v96
	v_add_f32_e32 v112, v117, v112
	v_add_f32_e32 v96, v118, v96
	v_add_f32_e32 v112, v119, v112
	v_add_f32_e32 v96, v120, v96
	v_add_f32_e32 v112, v121, v112
	v_add_f32_e32 v96, v122, v96
	v_add_f32_e32 v112, v123, v112
	v_add_f32_e32 v96, v124, v96
	v_add_f32_e32 v112, v125, v112
	v_add_f32_e32 v96, v126, v96
	v_add_f32_e32 v112, v127, v112
	v_add_f32_e32 v96, v180, v96
	v_add_f32_e32 v112, v111, v112
	v_add_f32_e32 v112, v96, v112
	v_mov_b32_e32 v113, v112
	v_cvt_pk_bf16_f32 v96, v179, v184
	v_cvt_pk_bf16_f32 v97, v185, v186
	v_cvt_pk_bf16_f32 v98, v187, v188
	v_cvt_pk_bf16_f32 v99, v189, v190
	v_cvt_pk_bf16_f32 v100, v191, v192
	v_cvt_pk_bf16_f32 v101, v193, v194
	v_cvt_pk_bf16_f32 v102, v195, v196
	v_cvt_pk_bf16_f32 v103, v197, v198
	v_cvt_pk_bf16_f32 v104, v114, v115
	v_cvt_pk_bf16_f32 v105, v116, v117
	v_cvt_pk_bf16_f32 v106, v118, v119
	v_cvt_pk_bf16_f32 v107, v120, v121
	v_cvt_pk_bf16_f32 v108, v122, v123
	v_cvt_pk_bf16_f32 v109, v124, v125
	v_cvt_pk_bf16_f32 v110, v126, v127
	v_cvt_pk_bf16_f32 v111, v180, v111
	s_nop 1
	v_permlane32_swap_b32_e32 v112, v113
	v_permlane32_swap_b32_e32 v96, v98
	v_permlane32_swap_b32_e32 v97, v99
	v_permlane32_swap_b32_e32 v100, v102
	v_permlane32_swap_b32_e32 v101, v103
	v_permlane32_swap_b32_e32 v104, v106
	v_permlane32_swap_b32_e32 v105, v107
	v_permlane32_swap_b32_e32 v108, v110
	v_permlane32_swap_b32_e32 v109, v111
	s_cmp_lt_i32 s54, s55
	s_cselect_b64 s[20:21], -1, 0
	s_cmp_ge_i32 s54, s55
	s_cbranch_scc1 .LBB0_402
	s_add_i32 s38, s69, 0xc0
	s_mul_i32 s69, s38, 0xc00
	v_mad_i64_i32 v[114:115], s[80:81], s38, v236, v[162:163]
	s_mul_hi_i32 s39, s38, 0xc00
	s_add_u32 s80, s3, s69
	s_addc_u32 s81, s36, s39
	v_lshl_add_u64 v[116:117], v[158:159], 1, s[80:81]
	global_load_dwordx4 v[146:149], v[114:115], off offset:1024
	global_load_dwordx4 v[150:153], v[116:117], off offset:2048
	v_lshl_add_u64 v[114:115], v[160:161], 1, s[80:81]
	global_load_dwordx4 v[154:157], v[114:115], off offset:2048

; __device__ __forceinline__ void finishSM(f32x16& p0, f32x16& p1, float& l_reg, bf16x8& pa0, bf16x8& pa1, bf16x8& pa2, bf16x8& pa3) {
; #pragma unroll
;   for (int r = 0; r < 16; ++r) p1[r] = __builtin_amdgcn_exp2f(p1[r]);
;   float ps = 0;
; #pragma unroll
;   for (int r = 0; r < 16; ++r) ps += p0[r];
; #pragma unroll
;   for (int r = 0; r < 16; ++r) ps += p1[r];
;   { auto rr = __builtin_amdgcn_permlane32_swap(__float_as_uint(ps), __float_as_uint(ps), false, false);
;     ps = __uint_as_float(rr[0]) + __uint_as_float(rr[1]); }
;   l_reg += ps;
;     ...
;   PK4(p0, 0, pa0); PK4(p0, 8, pa1); PK4(p1, 0, pa2); PK4(p1, 8, pa3);
;     ...
; }
; template <int DQK, int QL>
; __device__ __forceinline__ void qkt(f32x16& p0, f32x16& p1, const char* Ks, const bf16x8 (&qr)[DQK / 16 - QL], const char* qlds, const int (&kofs)[4], float negM) {
;   constexpr int QR = DQK / 16 - QL;
; #pragma unroll
;   for (int r = 0; r < 16; ++r) { p0[r] = negM; p1[r] = negM; }
; #pragma unroll
;   for (int d0 = 0; d0 < DQK / 16; ++d0) {
;     const char* kp = Ks + kofs[d0 & 3] + (d0 >> 2) * 128;
;     bf16x8 b0 = *reinterpret_cast<const bf16x8*>(kp);
;     bf16x8 b1 = *reinterpret_cast<const bf16x8*>(kp + 32 * DQK * 2);
;     bf16x8 qf;
;     if constexpr (QL > 0) { if (d0 < QR) qf = qr[d0 < QR ? d0 : 0]; else qf = *reinterpret_cast<const bf16x8*>(qlds + (d0 - QR) * 1024); }
;     else qf = qr[d0];
;     p0 = __builtin_amdgcn_mfma_f32_32x32x16_bf16(b0, qf, p0, 0, 0, 0);
;     p1 = __builtin_amdgcn_mfma_f32_32x32x16_bf16(b1, qf, p1, 0, 0, 0);
;   }
.LBB0_430:
	v_add_f32_e32 v80, 0, v132
	v_add_f32_e32 v80, v130, v80
	v_add_f32_e32 v168, v133, v131
	v_add_f32_e32 v80, v126, v80
	v_add_f32_e32 v168, v127, v168
	v_add_f32_e32 v80, v124, v80
	v_add_f32_e32 v168, v125, v168
	v_add_f32_e32 v80, v110, v80
	v_add_f32_e32 v168, v111, v168
	v_add_f32_e32 v80, v108, v80
	v_add_f32_e32 v168, v109, v168
	v_exp_f32_e32 v64, v64
	v_add_f32_e32 v80, v106, v80
	v_exp_f32_e32 v65, v65
	v_add_f32_e32 v168, v107, v168
	v_exp_f32_e32 v66, v66
	v_add_f32_e32 v80, v104, v80
	v_exp_f32_e32 v67, v67
	v_add_f32_e32 v168, v105, v168
	v_exp_f32_e32 v68, v68
	v_add_f32_e32 v80, v64, v80
	v_exp_f32_e32 v69, v69
	v_add_f32_e32 v168, v65, v168
	v_exp_f32_e32 v70, v70
	v_add_f32_e32 v80, v66, v80
	v_exp_f32_e32 v71, v71
	v_add_f32_e32 v168, v67, v168
	v_exp_f32_e32 v72, v72
	v_add_f32_e32 v80, v68, v80
	v_exp_f32_e32 v73, v73
	v_add_f32_e32 v168, v69, v168
	v_exp_f32_e32 v74, v74
	v_add_f32_e32 v80, v70, v80
	v_exp_f32_e32 v75, v75
	v_add_f32_e32 v168, v71, v168
	v_exp_f32_e32 v76, v76
	v_add_f32_e32 v80, v72, v80
	v_exp_f32_e32 v77, v77
	v_add_f32_e32 v168, v73, v168
	v_exp_f32_e32 v78, v78
	v_add_f32_e32 v80, v74, v80
	v_exp_f32_e32 v79, v79
	v_add_f32_e32 v168, v75, v168
	v_add_f32_e32 v80, v76, v80
	v_add_f32_e32 v168, v77, v168
	v_add_f32_e32 v80, v78, v80
	v_add_f32_e32 v168, v79, v168
	v_add_f32_e32 v168, v80, v168
	v_mov_b32_e32 v169, v168
	s_nop 1
	v_permlane32_swap_b32_e32 v168, v169
	v_cvt_pk_bf16_f32 v134, v132, v133
	v_cvt_pk_bf16_f32 v135, v130, v131
	v_cvt_pk_bf16_f32 v136, v126, v127
	v_cvt_pk_bf16_f32 v137, v124, v125
	v_cvt_pk_bf16_f32 v138, v110, v111
	v_cvt_pk_bf16_f32 v139, v108, v109
	v_cvt_pk_bf16_f32 v140, v106, v107
	v_cvt_pk_bf16_f32 v141, v104, v105
	v_cvt_pk_bf16_f32 v146, v64, v65
	v_cvt_pk_bf16_f32 v147, v66, v67
	v_cvt_pk_bf16_f32 v148, v68, v69
	v_cvt_pk_bf16_f32 v149, v70, v71
	v_cvt_pk_bf16_f32 v142, v72, v73
	v_cvt_pk_bf16_f32 v143, v74, v75
	v_cvt_pk_bf16_f32 v144, v76, v77
	v_cvt_pk_bf16_f32 v145, v78, v79
	s_nop 0
	v_permlane32_swap_b32_e32 v134, v136
	v_permlane32_swap_b32_e32 v135, v137
	v_permlane32_swap_b32_e32 v138, v140
	v_permlane32_swap_b32_e32 v139, v141
	v_permlane32_swap_b32_e32 v146, v148
	v_permlane32_swap_b32_e32 v147, v149
	v_permlane32_swap_b32_e32 v142, v144
	v_permlane32_swap_b32_e32 v143, v145
	ds_read_b128 v[80:83], v153 offset:57344
	ds_read_b128 v[84:87], v153 offset:57472
	v_mov_b64_e32 v[110:111], s[18:19]
	v_mov_b64_e32 v[108:109], s[16:17]
	v_mov_b64_e32 v[106:107], s[14:15]
	v_mov_b64_e32 v[104:105], s[12:13]
	v_mov_b64_e32 v[102:103], s[10:11]
	v_mov_b64_e32 v[100:101], s[8:9]
	v_mov_b64_e32 v[98:99], s[6:7]
	v_mov_b64_e32 v[96:97], s[4:5]
	v_add_u32_e32 v171, v155, v154
	s_waitcnt lgkmcnt(1)
	v_mfma_f32_32x32x16_bf16 v[64:79], v[80:83], v[120:123], v[96:111]
	ds_read_b128 v[80:83], v152 offset:57344
	ds_read_b128 v[88:91], v153 offset:57600
	s_waitcnt lgkmcnt(1)
	v_mfma_f32_32x32x16_bf16 v[64:79], v[80:83], v[116:119], v[64:79]
	ds_read_b128 v[80:83], v151 offset:57344
	ds_read_b128 v[92:95], v151 offset:57472
	s_waitcnt lgkmcnt(1)
	v_mfma_f32_32x32x16_bf16 v[64:79], v[80:83], v[112:115], v[64:79]
	ds_read_b128 v[80:83], v150 offset:57344
	ds_read_b128 v[124:127], v171
	ds_read_b128 v[130:133], v151 offset:57600
	ds_read_b128 v[172:175], v171 offset:1024
	s_waitcnt lgkmcnt(2)
	v_mfma_f32_32x32x16_bf16 v[64:79], v[80:83], v[124:127], v[64:79]
	s_waitcnt lgkmcnt(0)
	v_mfma_f32_32x32x16_bf16 v[64:79], v[84:87], v[172:175], v[64:79]
	ds_read_b128 v[80:83], v152 offset:57472
	ds_read_b128 v[176:179], v171 offset:2048
	ds_read_b128 v[84:87], v152 offset:57600
	ds_read_b128 v[180:183], v171 offset:3072
	s_waitcnt lgkmcnt(2)
	v_mfma_f32_32x32x16_bf16 v[64:79], v[80:83], v[176:179], v[64:79]
	s_waitcnt lgkmcnt(0)
	v_mfma_f32_32x32x16_bf16 v[64:79], v[92:95], v[180:183], v[64:79]
	ds_read_b128 v[80:83], v150 offset:57472
	ds_read_b128 v[184:187], v171 offset:4096
	ds_read_b128 v[188:191], v171 offset:5120
	ds_read_b128 v[92:95], v150 offset:57600
	ds_read_b128 v[192:195], v171 offset:6144
	ds_read_b128 v[196:199], v171 offset:7168
	ds_read_b128 v[200:203], v165 offset:12288
	ds_read_b128 v[204:207], v165 offset:12416
	ds_read_b128 v[208:211], v163 offset:12288
	ds_read_b128 v[212:215], v163 offset:12416
	ds_read_b128 v[216:219], v166 offset:12416
	ds_read_b128 v[220:223], v166 offset:12544
	s_waitcnt lgkmcnt(10)
	v_mfma_f32_32x32x16_bf16 v[64:79], v[80:83], v[184:187], v[64:79]
	s_waitcnt lgkmcnt(9)
	v_mfma_f32_32x32x16_bf16 v[64:79], v[88:91], v[188:191], v[64:79]
	s_waitcnt lgkmcnt(7)
	v_mfma_f32_32x32x16_bf16 v[64:79], v[84:87], v[192:195], v[64:79]
	s_waitcnt lgkmcnt(6)
	v_mfma_f32_32x32x16_bf16 v[64:79], v[130:133], v[196:199], v[64:79]
	ds_read_b128 v[130:133], v166 offset:12288
	ds_read_b128 v[224:227], v171 offset:8192
	ds_read_b128 v[228:231], v164 offset:12288
	ds_read_b128 v[238:241], v165 offset:12544
	ds_read_b128 v[242:245], v164 offset:12416
	ds_read_b128 v[246:249], v164 offset:12544
	ds_read_b128 v[250:253], v163 offset:12544
	s_waitcnt lgkmcnt(5)
; #define SBAR() __builtin_amdgcn_sched_barrier(0)
; template <int DQK, int QL>
; __device__ __forceinline__ void qkt(f32x16& p0, f32x16& p1, const char* Ks, const bf16x8 (&qr)[DQK / 16 - QL], const char* qlds, const int (&kofs)[4], float negM) {
;   constexpr int QR = DQK / 16 - QL;
; #pragma unroll
;   for (int r = 0; r < 16; ++r) { p0[r] = negM; p1[r] = negM; }
; #pragma unroll
;   for (int d0 = 0; d0 < DQK / 16; ++d0) {
;     const char* kp = Ks + kofs[d0 & 3] + (d0 >> 2) * 128;
;     bf16x8 b0 = *reinterpret_cast<const bf16x8*>(kp);
;     bf16x8 b1 = *reinterpret_cast<const bf16x8*>(kp + 32 * DQK * 2);
;     bf16x8 qf;
;     if constexpr (QL > 0) { if (d0 < QR) qf = qr[d0 < QR ? d0 : 0]; else qf = *reinterpret_cast<const bf16x8*>(qlds + (d0 - QR) * 1024); }
;     else qf = qr[d0];
;     p0 = __builtin_amdgcn_mfma_f32_32x32x16_bf16(b0, qf, p0, 0, 0, 0);
;     p1 = __builtin_amdgcn_mfma_f32_32x32x16_bf16(b1, qf, p1, 0, 0, 0);
;   }
; }
; template <int NCB> __device__ __forceinline__ int v_st(int k, int c) {
;   const int kk = (k & ~0xC) | ((k & 4) << 1) | ((k & 8) >> 1);
;   return ((kk >> 3) * NCB + (c >> 5)) * 512 + ((kk & 7) * 32 + (c & 31)) * 2;
; }
; __device__ __forceinline__ int v_rd_base(int lane) { return ((lane & 3) << 3) | (((lane >> 2) & 3) << 6) | (((lane >> 4) & 1) << 5) | (((lane >> 5) & 1) << 8); }
; template <int OFF> __device__ __forceinline__ s16x4 tr_read(int vb) {
;   s16x4 r; asm volatile("ds_read_b64_tr_b16 %0, %1 offset:%2" : "=&v"(r) : "v"(vb), "i"(OFF) : "memory"); return r;
; }
; template <int NCB, int D0> __device__ __forceinline__ void pv_one(f32x16& od, int vb, bf16x8 pa0, bf16x8 pa1, bf16x8 pa2, bf16x8 pa3) {
;   constexpr int KSTEP = NCB * 1024, HALF = NCB * 512, B0 = D0 * 512;
;   const s16x4 l0 = tr_read<B0>(vb), h0 = tr_read<B0 + HALF>(vb), l1 = tr_read<B0 + KSTEP>(vb), h1 = tr_read<B0 + KSTEP + HALF>(vb);
;   const s16x4 l2 = tr_read<B0 + 2 * KSTEP>(vb), h2 = tr_read<B0 + 2 * KSTEP + HALF>(vb), l3 = tr_read<B0 + 3 * KSTEP>(vb), h3 = tr_read<B0 + 3 * KSTEP + HALF>(vb);
;   WAIT_L0(); SBAR();
;     ...
;   od = __builtin_amdgcn_mfma_f32_32x32x16_bf16(pa0, PK(l0, h0), od, 0, 0, 0);
;   od = __builtin_amdgcn_mfma_f32_32x32x16_bf16(pa1, PK(l1, h1), od, 0, 0, 0);
;   od = __builtin_amdgcn_mfma_f32_32x32x16_bf16(pa2, PK(l2, h2), od, 0, 0, 0);
;   od = __builtin_amdgcn_mfma_f32_32x32x16_bf16(pa3, PK(l3, h3), od, 0, 0, 0);
;     ...
; }
	v_mfma_f32_32x32x16_bf16 v[64:79], v[92:95], v[224:227], v[64:79]
	v_mfma_f32_32x32x16_bf16 v[80:95], v[130:133], v[120:123], v[96:111]
	s_add_i32 s68, s23, 0x80
	s_ashr_i32 s69, s68, 31
	s_mul_i32 s20, s68, 0x600
	s_mul_hi_i32 s21, s68, 0x600
	s_add_u32 s20, s3, s20
	s_nop 1
	v_mov_b32_e32 v97, v157
	v_mfma_f32_32x32x16_bf16 v[80:95], v[200:203], v[116:119], v[80:95]
	v_mul_hi_i32 v99, v97, s82
	v_lshrrev_b32_e32 v100, 31, v99
	v_ashrrev_i32_e32 v99, 2, v99
	v_add_u32_e32 v99, v99, v100
	v_lshrrev_b32_e32 v101, 3, v99
	v_mul_lo_u32 v100, v99, 24
	v_bitop3_b32 v99, v101, v99, 1 bitop3:0x6c
	v_add_u32_e32 v101, 0x200, v97
	v_mul_hi_i32 v102, v101, s82
	v_sub_u32_e32 v100, v97, v100
	v_lshrrev_b32_e32 v103, 31, v102
	v_ashrrev_i32_e32 v102, 2, v102
	v_bitop3_b32 v100, v99, v100, 7 bitop3:0x6c
	v_mul_lo_u32 v99, v99, s85
	v_add_u32_e32 v102, v102, v103
	v_lshl_add_u32 v100, v100, 3, v99
	v_mul_lo_u32 v99, v102, 24
	v_lshlrev_b32_e32 v96, 3, v97
	v_lshlrev_b32_e32 v98, 5, v97
	v_sub_u32_e32 v99, v101, v99
	v_lshrrev_b32_e32 v101, 3, v102
	v_add_u32_e32 v97, 0x400, v97
	v_bitop3_b32 v101, v101, v102, 1 bitop3:0x6c
	v_mul_hi_i32 v102, v97, s82
	v_lshrrev_b32_e32 v103, 31, v102
	v_ashrrev_i32_e32 v102, 2, v102
	v_add_u32_e32 v103, v102, v103
	v_bitop3_b32 v99, v101, v99, 7 bitop3:0x6c
	v_mul_lo_u32 v101, v101, s85
	v_mul_lo_u32 v102, v103, 24
	v_sub_u32_e32 v97, v97, v102
	v_lshl_add_u32 v102, v99, 3, v101
	v_lshrrev_b32_e32 v99, 3, v103
	s_waitcnt lgkmcnt(4)
	v_mfma_f32_32x32x16_bf16 v[80:95], v[228:231], v[112:115], v[80:95]
	v_bitop3_b32 v99, v99, v103, 1 bitop3:0x6c
	v_bitop3_b32 v97, v99, v97, 7 bitop3:0x6c
	v_mul_lo_u32 v99, v99, s85
	s_addc_u32 s21, s36, s21
	v_ashrrev_i32_e32 v101, 31, v100
	v_readfirstlane_b32 s38, v160
	v_lshl_add_u32 v104, v97, 3, v99
	v_lshl_add_u64 v[100:101], v[100:101], 1, s[20:21]
	s_mov_b32 m0, s38
	v_ashrrev_i32_e32 v103, 31, v102
	v_readfirstlane_b32 s38, v161
	global_load_lds_dwordx4 v[100:101], off
	v_lshl_add_u64 v[100:101], v[102:103], 1, s[20:21]
	s_mov_b32 m0, s38
	v_ashrrev_i32_e32 v105, 31, v104
	v_and_b32_e32 v96, 0x78, v96
	global_load_lds_dwordx4 v[100:101], off
	v_lshl_add_u64 v[100:101], v[104:105], 1, s[20:21]
	s_lshl_b64 s[20:21], s[68:69], 10
	v_and_or_b32 v96, v98, s24, v96
	v_readfirstlane_b32 s38, v162
	s_add_u32 s20, s83, s20
	v_add_u32_e32 v98, 0x4000, v96
	s_mov_b32 m0, s38
	s_addc_u32 s21, s93, s21
	v_ashrrev_i32_e32 v97, 31, v96
	global_load_lds_dwordx4 v[100:101], off
	v_lshl_add_u64 v[96:97], v[96:97], 1, s[20:21]
	v_ashrrev_i32_e32 v99, 31, v98
	v_mfma_f32_32x32x16_bf16 v[80:95], v[208:211], v[124:127], v[80:95]
	v_lshl_add_u64 v[98:99], v[98:99], 1, s[20:21]
	global_load_dwordx4 v[130:133], v[96:97], off
	global_load_dwordx4 v[124:127], v[98:99], off
	v_mfma_f32_32x32x16_bf16 v[80:95], v[216:219], v[172:175], v[80:95]
	v_mfma_f32_32x32x16_bf16 v[80:95], v[204:207], v[176:179], v[80:95]
	s_waitcnt lgkmcnt(0)
	v_mfma_f32_32x32x16_bf16 v[80:95], v[242:245], v[180:183], v[80:95]
	v_mfma_f32_32x32x16_bf16 v[80:95], v[212:215], v[184:187], v[80:95]
	v_mfma_f32_32x32x16_bf16 v[80:95], v[220:223], v[188:191], v[80:95]
	v_mfma_f32_32x32x16_bf16 v[80:95], v[238:241], v[192:195], v[80:95]
	v_mfma_f32_32x32x16_bf16 v[80:95], v[246:249], v[196:199], v[80:95]
	v_mfma_f32_32x32x16_bf16 v[80:95], v[250:253], v[224:227], v[80:95]
	ds_read_b64_tr_b16 v[96:97], v159 offset:0
	ds_read_b64_tr_b16 v[98:99], v159 offset:0x800
	ds_read_b64_tr_b16 v[100:101], v159 offset:0x1000
	ds_read_b64_tr_b16 v[102:103], v159 offset:0x1800
	ds_read_b64_tr_b16 v[104:105], v159 offset:0x2000
	ds_read_b64_tr_b16 v[106:107], v159 offset:0x2800
	ds_read_b64_tr_b16 v[108:109], v159 offset:0x3000
	ds_read_b64_tr_b16 v[110:111], v159 offset:0x3800
	s_nop 0
	s_waitcnt lgkmcnt(6)
	v_mfma_f32_32x32x16_bf16 v[0:15], v[134:137], v[96:99], v[0:15]
	ds_read_b64_tr_b16 v[96:97], v159 offset:0x200
	ds_read_b64_tr_b16 v[98:99], v159 offset:0xa00
	s_waitcnt lgkmcnt(6)
	v_mfma_f32_32x32x16_bf16 v[0:15], v[138:141], v[100:103], v[0:15]
	ds_read_b64_tr_b16 v[100:101], v159 offset:0x1200
	ds_read_b64_tr_b16 v[102:103], v159 offset:0x1a00
	s_waitcnt lgkmcnt(6)
	v_mfma_f32_32x32x16_bf16 v[0:15], v[146:149], v[104:107], v[0:15]
	ds_read_b64_tr_b16 v[104:105], v159 offset:0x2200
	ds_read_b64_tr_b16 v[106:107], v159 offset:0x2a00
	s_waitcnt lgkmcnt(6)
	v_mfma_f32_32x32x16_bf16 v[0:15], v[142:145], v[108:111], v[0:15]
	ds_read_b64_tr_b16 v[108:109], v159 offset:0x3200
	ds_read_b64_tr_b16 v[110:111], v159 offset:0x3a00
	s_waitcnt lgkmcnt(6)
	v_mfma_f32_32x32x16_bf16 v[48:63], v[134:137], v[96:99], v[48:63]
	ds_read_b64_tr_b16 v[96:97], v159 offset:0x400
	ds_read_b64_tr_b16 v[98:99], v159 offset:0xc00
	s_waitcnt lgkmcnt(6)
	v_mfma_f32_32x32x16_bf16 v[48:63], v[138:141], v[100:103], v[48:63]
	ds_read_b64_tr_b16 v[100:101], v159 offset:0x1400
	ds_read_b64_tr_b16 v[102:103], v159 offset:0x1c00
	s_waitcnt lgkmcnt(6)
	v_mfma_f32_32x32x16_bf16 v[48:63], v[146:149], v[104:107], v[48:63]
	ds_read_b64_tr_b16 v[104:105], v159 offset:0x2400
	ds_read_b64_tr_b16 v[106:107], v159 offset:0x2c00
	s_waitcnt lgkmcnt(6)
	v_mfma_f32_32x32x16_bf16 v[48:63], v[142:145], v[108:111], v[48:63]
	ds_read_b64_tr_b16 v[108:109], v159 offset:0x3400
	ds_read_b64_tr_b16 v[110:111], v159 offset:0x3c00
	s_waitcnt lgkmcnt(6)
	v_mfma_f32_32x32x16_bf16 v[32:47], v[134:137], v[96:99], v[32:47]
	ds_read_b64_tr_b16 v[96:97], v159 offset:0x600
	ds_read_b64_tr_b16 v[98:99], v159 offset:0xe00
	s_waitcnt lgkmcnt(6)
	v_mfma_f32_32x32x16_bf16 v[32:47], v[138:141], v[100:103], v[32:47]
	ds_read_b64_tr_b16 v[100:101], v159 offset:0x1600
	ds_read_b64_tr_b16 v[102:103], v159 offset:0x1e00
	s_waitcnt lgkmcnt(6)
	v_mfma_f32_32x32x16_bf16 v[32:47], v[146:149], v[104:107], v[32:47]
	ds_read_b64_tr_b16 v[104:105], v159 offset:0x2600
	ds_read_b64_tr_b16 v[106:107], v159 offset:0x2e00
	s_waitcnt lgkmcnt(6)
	v_mfma_f32_32x32x16_bf16 v[32:47], v[142:145], v[108:111], v[32:47]
	ds_read_b64_tr_b16 v[108:109], v159 offset:0x3600
	ds_read_b64_tr_b16 v[110:111], v159 offset:0x3e00
	s_waitcnt lgkmcnt(6)
	v_mfma_f32_32x32x16_bf16 v[16:31], v[134:137], v[96:99], v[16:31]
	s_add_i32 s20, s23, 64
	v_lshlrev_b32_e32 v96, 2, v128
	s_cmp_le_i32 s20, s59
	v_add_u32_e32 v170, s23, v96
	s_waitcnt lgkmcnt(4)
	v_mfma_f32_32x32x16_bf16 v[16:31], v[138:141], v[100:103], v[16:31]
	s_waitcnt lgkmcnt(2)
	v_mfma_f32_32x32x16_bf16 v[16:31], v[146:149], v[104:107], v[16:31]
	s_waitcnt lgkmcnt(0)
	v_mfma_f32_32x32x16_bf16 v[16:31], v[142:145], v[108:111], v[16:31]
	s_cbranch_scc1 .LBB0_432
; #define WAIT_V0() asm volatile("s_waitcnt vmcnt(0)" ::: "memory")
; __device__ __forceinline__ int crow(int r, int hi) { return (r & 3) + 8 * (r >> 2) + 4 * hi; }
; #define SWRITE(b) do { FRESH_COORDS(); \
;     if constexpr (!KDMA) { _Pragma("unroll") for (int i = 0; i < KC; ++i) *reinterpret_cast<bf16x8*>(shm + (b) * SHM_K + klo[i]) = ks[i]; } \
;     _Pragma("unroll") for (int i = 0; i < VC; ++i) *reinterpret_cast<bf16x8*>(shm + (b) * SHM_V + vlo[i]) = vs[i]; } while (0)
; template <bool GM>
; __device__ __forceinline__ void partialSM(f32x16& p0, f32x16& p1, bool mask, int kbase, int L, int qpos, int hi) {
;   if (mask) {
; #pragma unroll
;     for (int r = 0; r < 16; ++r) {
;       int k = kbase + crow(r, hi);
;       asm volatile("" : "+v"(k) : "v"(p0[r]));
;       bool ok = k < L;
;       if (GM) ok = ok && (k < 16 || abs(qpos - k) <= 128);
;       p0[r] = ok ? p0[r] : -1e30f;
;       int k2 = k + 32;
;       asm volatile("" : "+v"(k2) : "v"(p1[r]));
;       bool ok2 = k2 < L;
;       if (GM) ok2 = ok2 && (k2 < 16 || abs(qpos - k2) <= 128);
;       p1[r] = ok2 ? p1[r] : -1e30f;
;     }
;   }
; #pragma unroll
;   for (int r = 0; r < 16; ++r) p0[r] = __builtin_amdgcn_exp2f(p0[r]);
; }
;     ...
;     partialSM<GM>(pB0, pB1, NEEDMASK(kb), kb, L, qpos, hi);
;     __syncthreads(); WAIT_V0(); SWRITE(0);
;     __syncthreads();
	v_add_u32_e32 v96, 64, v170
	s_nop 0
	v_cmp_gt_i32_e32 vcc, s94, v96
	v_add_u32_e32 v96, 32, v96
	s_nop 0
	v_cndmask_b32_e32 v64, v233, v64, vcc
	v_cmp_gt_i32_e32 vcc, s94, v96
	v_add_u32_e32 v96, 0x41, v170
	s_nop 0
	v_cndmask_b32_e32 v80, v233, v80, vcc
	v_cmp_gt_i32_e32 vcc, s94, v96
	v_add_u32_e32 v96, 32, v96
	s_nop 0
	v_cndmask_b32_e32 v65, v233, v65, vcc
	v_cmp_gt_i32_e32 vcc, s94, v96
	v_add_u32_e32 v96, 0x42, v170
	s_nop 0
	v_cndmask_b32_e32 v81, v233, v81, vcc
	v_cmp_gt_i32_e32 vcc, s94, v96
	v_add_u32_e32 v96, 32, v96
	s_nop 0
	v_cndmask_b32_e32 v66, v233, v66, vcc
	v_cmp_gt_i32_e32 vcc, s94, v96
	v_add_u32_e32 v96, 0x43, v170
	s_nop 0
	v_cndmask_b32_e32 v82, v233, v82, vcc
	v_cmp_gt_i32_e32 vcc, s94, v96
	v_add_u32_e32 v96, 32, v96
	s_nop 0
	v_cndmask_b32_e32 v67, v233, v67, vcc
	v_cmp_gt_i32_e32 vcc, s94, v96
	v_add_u32_e32 v96, 0x48, v170
	s_nop 0
	v_cndmask_b32_e32 v83, v233, v83, vcc
	v_cmp_gt_i32_e32 vcc, s94, v96
	v_add_u32_e32 v96, 32, v96
	s_nop 0
	v_cndmask_b32_e32 v68, v233, v68, vcc
	v_cmp_gt_i32_e32 vcc, s94, v96
	v_add_u32_e32 v96, 0x49, v170
	s_nop 0
	v_cndmask_b32_e32 v84, v233, v84, vcc
	v_cmp_gt_i32_e32 vcc, s94, v96
	v_add_u32_e32 v96, 32, v96
	s_nop 0
	v_cndmask_b32_e32 v69, v233, v69, vcc
	v_cmp_gt_i32_e32 vcc, s94, v96
	v_add_u32_e32 v96, 0x4a, v170
	s_nop 0
	v_cndmask_b32_e32 v85, v233, v85, vcc
	v_cmp_gt_i32_e32 vcc, s94, v96
	v_add_u32_e32 v96, 32, v96
	s_nop 0
	v_cndmask_b32_e32 v70, v233, v70, vcc
	v_cmp_gt_i32_e32 vcc, s94, v96
	v_add_u32_e32 v96, 0x4b, v170
	s_nop 0
	v_cndmask_b32_e32 v86, v233, v86, vcc
	v_cmp_gt_i32_e32 vcc, s94, v96
	v_add_u32_e32 v96, 32, v96
	s_nop 0
	v_cndmask_b32_e32 v71, v233, v71, vcc
	v_cmp_gt_i32_e32 vcc, s94, v96
	v_add_u32_e32 v96, 0x50, v170
	s_nop 0
	v_cndmask_b32_e32 v87, v233, v87, vcc
	v_cmp_gt_i32_e32 vcc, s94, v96
	v_add_u32_e32 v96, 32, v96
	s_nop 0
	v_cndmask_b32_e32 v72, v233, v72, vcc
	v_cmp_gt_i32_e32 vcc, s94, v96
	v_add_u32_e32 v96, 0x51, v170
	s_nop 0
	v_cndmask_b32_e32 v88, v233, v88, vcc
	v_cmp_gt_i32_e32 vcc, s94, v96
	v_add_u32_e32 v96, 32, v96
	s_nop 0
	v_cndmask_b32_e32 v73, v233, v73, vcc
	v_cmp_gt_i32_e32 vcc, s94, v96
	v_add_u32_e32 v96, 0x52, v170
	s_nop 0
	v_cndmask_b32_e32 v89, v233, v89, vcc
	v_cmp_gt_i32_e32 vcc, s94, v96
	v_add_u32_e32 v96, 32, v96
	s_nop 0
	v_cndmask_b32_e32 v74, v233, v74, vcc
	v_cmp_gt_i32_e32 vcc, s94, v96
	v_add_u32_e32 v96, 0x53, v170
	s_nop 0
	v_cndmask_b32_e32 v90, v233, v90, vcc
	v_cmp_gt_i32_e32 vcc, s94, v96
	v_add_u32_e32 v96, 32, v96
	s_nop 0
	v_cndmask_b32_e32 v75, v233, v75, vcc
	v_cmp_gt_i32_e32 vcc, s94, v96
	v_add_u32_e32 v96, 0x58, v170
	s_nop 0
	v_cndmask_b32_e32 v91, v233, v91, vcc
	v_cmp_gt_i32_e32 vcc, s94, v96
	v_add_u32_e32 v96, 32, v96
	s_nop 0
	v_cndmask_b32_e32 v76, v233, v76, vcc
	v_cmp_gt_i32_e32 vcc, s94, v96
	v_add_u32_e32 v96, 0x59, v170
	s_nop 0
	v_cndmask_b32_e32 v92, v233, v92, vcc
	v_cmp_gt_i32_e32 vcc, s94, v96
	v_add_u32_e32 v96, 32, v96
	s_nop 0
	v_cndmask_b32_e32 v77, v233, v77, vcc
	v_cmp_gt_i32_e32 vcc, s94, v96
	v_add_u32_e32 v96, 0x5a, v170
	s_nop 0
	v_cndmask_b32_e32 v93, v233, v93, vcc
	v_cmp_gt_i32_e32 vcc, s94, v96
	v_add_u32_e32 v96, 32, v96
	s_nop 0
	v_cndmask_b32_e32 v78, v233, v78, vcc
	v_cmp_gt_i32_e32 vcc, s94, v96
	v_add_u32_e32 v96, 0x5b, v170
	s_nop 0
	v_cndmask_b32_e32 v94, v233, v94, vcc
	v_cmp_gt_i32_e32 vcc, s94, v96
	v_add_u32_e32 v96, 32, v96
	s_nop 0
	v_cndmask_b32_e32 v79, v233, v79, vcc
	v_cmp_gt_i32_e32 vcc, s94, v96
	s_nop 1
	v_cndmask_b32_e32 v95, v233, v95, vcc
.LBB0_432:
	v_mov_b32_e32 v96, v157
	v_ashrrev_i32_e32 v97, 4, v96
	v_and_b32_e32 v99, 0xfffff0, v97
	v_lshlrev_b32_e32 v100, 1, v97
	v_add_u32_e32 v98, 32, v97
	v_and_or_b32 v99, v100, 8, v99
	v_lshrrev_b32_e32 v100, 1, v97
	v_and_b32_e32 v97, 3, v97
	v_and_or_b32 v97, v100, 4, v97
	v_and_b32_e32 v100, 0xfffff0, v98
	v_lshlrev_b32_e32 v98, 1, v98
	v_and_or_b32 v98, v98, 8, v100
	v_lshrrev_b32_e32 v99, 1, v99
	v_bfe_u32 v101, v96, 2, 2
	v_lshrrev_b32_e32 v98, 1, v98
	v_or_b32_e32 v99, v99, v101
	v_lshlrev_b32_e32 v96, 4, v96
	v_or_b32_e32 v98, v98, v101
	v_lshlrev_b32_e32 v99, 9, v99
	v_lshlrev_b32_e32 v97, 6, v97
	v_and_b32_e32 v96, 48, v96
	v_lshlrev_b32_e32 v98, 9, v98
	v_or3_b32 v99, v99, v97, v96
	v_or3_b32 v96, v98, v97, v96
	s_waitcnt vmcnt(0)
	s_barrier
	s_waitcnt vmcnt(0)
	ds_write_b128 v99, v[130:133]
	ds_write_b128 v96, v[124:127]
	v_exp_f32_e32 v64, v64
	v_exp_f32_e32 v66, v66
	v_exp_f32_e32 v68, v68
	v_exp_f32_e32 v70, v70
	v_exp_f32_e32 v72, v72
	v_exp_f32_e32 v74, v74
	v_exp_f32_e32 v76, v76
	v_exp_f32_e32 v78, v78
	v_exp_f32_e32 v65, v65
	v_exp_f32_e32 v67, v67
	v_exp_f32_e32 v69, v69
	v_exp_f32_e32 v71, v71
	v_exp_f32_e32 v73, v73
	v_exp_f32_e32 v75, v75
	v_exp_f32_e32 v77, v77
	v_exp_f32_e32 v79, v79
	s_waitcnt lgkmcnt(0)
	s_barrier
; __device__ __forceinline__ void finishSM(f32x16& p0, f32x16& p1, float& l_reg, bf16x8& pa0, bf16x8& pa1, bf16x8& pa2, bf16x8& pa3) {
; #pragma unroll
;   for (int r = 0; r < 16; ++r) p1[r] = __builtin_amdgcn_exp2f(p1[r]);
;   float ps = 0;
; #pragma unroll
;   for (int r = 0; r < 16; ++r) ps += p0[r];
; #pragma unroll
;   for (int r = 0; r < 16; ++r) ps += p1[r];
;   { auto rr = __builtin_amdgcn_permlane32_swap(__float_as_uint(ps), __float_as_uint(ps), false, false);
;     ps = __uint_as_float(rr[0]) + __uint_as_float(rr[1]); }
;   l_reg += ps;
;     ...
;   PK4(p0, 0, pa0); PK4(p0, 8, pa1); PK4(p1, 0, pa2); PK4(p1, 8, pa3);
;     ...
; }
; template <int DQK, int QL>
; __device__ __forceinline__ void qkt(f32x16& p0, f32x16& p1, const char* Ks, const bf16x8 (&qr)[DQK / 16 - QL], const char* qlds, const int (&kofs)[4], float negM) {
;   constexpr int QR = DQK / 16 - QL;
; #pragma unroll
;   for (int r = 0; r < 16; ++r) { p0[r] = negM; p1[r] = negM; }
; #pragma unroll
;   for (int d0 = 0; d0 < DQK / 16; ++d0) {
;     const char* kp = Ks + kofs[d0 & 3] + (d0 >> 2) * 128;
;     bf16x8 b0 = *reinterpret_cast<const bf16x8*>(kp);
;     bf16x8 b1 = *reinterpret_cast<const bf16x8*>(kp + 32 * DQK * 2);
;     bf16x8 qf;
;     if constexpr (QL > 0) { if (d0 < QR) qf = qr[d0 < QR ? d0 : 0]; else qf = *reinterpret_cast<const bf16x8*>(qlds + (d0 - QR) * 1024); }
;     else qf = qr[d0];
;     p0 = __builtin_amdgcn_mfma_f32_32x32x16_bf16(b0, qf, p0, 0, 0, 0);
;     p1 = __builtin_amdgcn_mfma_f32_32x32x16_bf16(b1, qf, p1, 0, 0, 0);
;   }
	v_add_f32_e32 v96, 0, v64
	v_add_f32_e32 v96, v66, v96
	v_add_f32_e32 v172, v65, v67
	v_add_f32_e32 v96, v68, v96
	v_add_f32_e32 v172, v69, v172
	v_add_f32_e32 v96, v70, v96
	v_add_f32_e32 v172, v71, v172
	v_add_f32_e32 v96, v72, v96
	v_add_f32_e32 v172, v73, v172
	v_add_f32_e32 v96, v74, v96
	v_add_f32_e32 v172, v75, v172
	v_exp_f32_e32 v80, v80
	v_add_f32_e32 v96, v76, v96
	v_exp_f32_e32 v81, v81
	v_add_f32_e32 v172, v77, v172
	v_exp_f32_e32 v82, v82
	v_add_f32_e32 v96, v78, v96
	v_exp_f32_e32 v83, v83
	v_add_f32_e32 v172, v79, v172
	v_exp_f32_e32 v84, v84
	v_add_f32_e32 v96, v80, v96
	v_exp_f32_e32 v85, v85
	v_add_f32_e32 v172, v81, v172
	v_exp_f32_e32 v86, v86
	v_add_f32_e32 v96, v82, v96
	v_exp_f32_e32 v87, v87
	v_add_f32_e32 v172, v83, v172
	v_exp_f32_e32 v88, v88
	v_add_f32_e32 v96, v84, v96
	v_exp_f32_e32 v89, v89
	v_add_f32_e32 v172, v85, v172
	v_exp_f32_e32 v90, v90
	v_add_f32_e32 v96, v86, v96
	v_exp_f32_e32 v91, v91
	v_add_f32_e32 v172, v87, v172
	v_exp_f32_e32 v92, v92
	v_add_f32_e32 v96, v88, v96
	v_exp_f32_e32 v93, v93
	v_add_f32_e32 v172, v89, v172
	v_exp_f32_e32 v94, v94
	v_add_f32_e32 v96, v90, v96
	v_exp_f32_e32 v95, v95
	v_add_f32_e32 v172, v91, v172
	v_add_f32_e32 v96, v92, v96
	v_add_f32_e32 v172, v93, v172
	v_add_f32_e32 v96, v94, v96
	v_add_f32_e32 v172, v95, v172
	v_add_f32_e32 v172, v96, v172
	v_mov_b32_e32 v173, v172
	v_cvt_pk_bf16_f32 v134, v64, v65
	v_cvt_pk_bf16_f32 v135, v66, v67
	v_cvt_pk_bf16_f32 v136, v68, v69
	v_cvt_pk_bf16_f32 v137, v70, v71
	v_cvt_pk_bf16_f32 v138, v72, v73
	v_cvt_pk_bf16_f32 v139, v74, v75
	v_cvt_pk_bf16_f32 v140, v76, v77
	v_cvt_pk_bf16_f32 v141, v78, v79
	v_cvt_pk_bf16_f32 v142, v80, v81
	v_cvt_pk_bf16_f32 v143, v82, v83
	v_cvt_pk_bf16_f32 v144, v84, v85
	v_cvt_pk_bf16_f32 v145, v86, v87
	v_cvt_pk_bf16_f32 v146, v88, v89
	v_cvt_pk_bf16_f32 v147, v90, v91
	v_cvt_pk_bf16_f32 v148, v92, v93
	v_cvt_pk_bf16_f32 v149, v94, v95
	s_nop 1
	v_permlane32_swap_b32_e32 v172, v173
	v_permlane32_swap_b32_e32 v134, v136
	v_permlane32_swap_b32_e32 v135, v137
	v_permlane32_swap_b32_e32 v138, v140
	v_permlane32_swap_b32_e32 v139, v141
	v_permlane32_swap_b32_e32 v142, v144
	v_permlane32_swap_b32_e32 v143, v145
	v_permlane32_swap_b32_e32 v146, v148
	v_permlane32_swap_b32_e32 v147, v149
	ds_read_b128 v[64:67], v153 offset:32768
	ds_read_b128 v[174:177], v153 offset:45056
	v_mov_b64_e32 v[110:111], s[18:19]
	v_mov_b64_e32 v[108:109], s[16:17]
	v_mov_b64_e32 v[106:107], s[14:15]
	v_mov_b64_e32 v[104:105], s[12:13]
	v_mov_b64_e32 v[102:103], s[10:11]
	v_mov_b64_e32 v[100:101], s[8:9]
	v_mov_b64_e32 v[98:99], s[6:7]
	v_mov_b64_e32 v[96:97], s[4:5]
	s_waitcnt lgkmcnt(1)
	s_nop 0
	v_mfma_f32_32x32x16_bf16 v[80:95], v[64:67], v[120:123], v[96:111]
	s_waitcnt lgkmcnt(0)
	v_mfma_f32_32x32x16_bf16 v[64:79], v[174:177], v[120:123], v[96:111]
	s_nop 6
	ds_read_b128 v[96:99], v152 offset:32768
	ds_read_b128 v[100:103], v152 offset:45056
	s_waitcnt lgkmcnt(1)
	v_mfma_f32_32x32x16_bf16 v[80:95], v[96:99], v[116:119], v[80:95]
	s_waitcnt lgkmcnt(0)
	v_mfma_f32_32x32x16_bf16 v[64:79], v[100:103], v[116:119], v[64:79]
	ds_read_b128 v[96:99], v151 offset:32768
	ds_read_b128 v[100:103], v151 offset:45056
	s_waitcnt lgkmcnt(1)
	v_mfma_f32_32x32x16_bf16 v[80:95], v[96:99], v[112:115], v[80:95]
	s_waitcnt lgkmcnt(0)
	v_mfma_f32_32x32x16_bf16 v[64:79], v[100:103], v[112:115], v[64:79]
	ds_read_b128 v[96:99], v150 offset:32768
	ds_read_b128 v[100:103], v150 offset:45056
	ds_read_b128 v[104:107], v171
	s_waitcnt lgkmcnt(0)
	v_mfma_f32_32x32x16_bf16 v[80:95], v[96:99], v[104:107], v[80:95]
	v_mfma_f32_32x32x16_bf16 v[64:79], v[100:103], v[104:107], v[64:79]
	ds_read_b128 v[96:99], v153 offset:32896
	ds_read_b128 v[100:103], v153 offset:45184
	ds_read_b128 v[104:107], v171 offset:1024
	s_waitcnt lgkmcnt(0)
	v_mfma_f32_32x32x16_bf16 v[80:95], v[96:99], v[104:107], v[80:95]
	v_mfma_f32_32x32x16_bf16 v[64:79], v[100:103], v[104:107], v[64:79]
	ds_read_b128 v[96:99], v152 offset:32896
	ds_read_b128 v[100:103], v152 offset:45184
	ds_read_b128 v[104:107], v171 offset:2048
	s_waitcnt lgkmcnt(0)
	v_mfma_f32_32x32x16_bf16 v[80:95], v[96:99], v[104:107], v[80:95]
	v_mfma_f32_32x32x16_bf16 v[64:79], v[100:103], v[104:107], v[64:79]
	ds_read_b128 v[96:99], v151 offset:32896
	ds_read_b128 v[100:103], v151 offset:45184
	ds_read_b128 v[104:107], v171 offset:3072
	s_waitcnt lgkmcnt(0)
	v_mfma_f32_32x32x16_bf16 v[80:95], v[96:99], v[104:107], v[80:95]
	v_mfma_f32_32x32x16_bf16 v[64:79], v[100:103], v[104:107], v[64:79]
	ds_read_b128 v[96:99], v150 offset:32896
	ds_read_b128 v[100:103], v150 offset:45184
	ds_read_b128 v[104:107], v171 offset:4096
	s_waitcnt lgkmcnt(0)
	v_mfma_f32_32x32x16_bf16 v[80:95], v[96:99], v[104:107], v[80:95]
	v_mfma_f32_32x32x16_bf16 v[64:79], v[100:103], v[104:107], v[64:79]
	ds_read_b128 v[96:99], v153 offset:33024
	ds_read_b128 v[100:103], v153 offset:45312
	ds_read_b128 v[104:107], v171 offset:5120
	s_waitcnt lgkmcnt(0)
	v_mfma_f32_32x32x16_bf16 v[80:95], v[96:99], v[104:107], v[80:95]
	v_mfma_f32_32x32x16_bf16 v[64:79], v[100:103], v[104:107], v[64:79]
	ds_read_b128 v[96:99], v152 offset:33024
	ds_read_b128 v[100:103], v152 offset:45312
	ds_read_b128 v[104:107], v171 offset:6144
	s_waitcnt lgkmcnt(0)
	v_mfma_f32_32x32x16_bf16 v[80:95], v[96:99], v[104:107], v[80:95]
	v_mfma_f32_32x32x16_bf16 v[64:79], v[100:103], v[104:107], v[64:79]
	ds_read_b128 v[96:99], v151 offset:33024
	ds_read_b128 v[100:103], v151 offset:45312
	ds_read_b128 v[104:107], v171 offset:7168
	s_waitcnt lgkmcnt(0)
	v_mfma_f32_32x32x16_bf16 v[80:95], v[96:99], v[104:107], v[80:95]
	v_mfma_f32_32x32x16_bf16 v[64:79], v[100:103], v[104:107], v[64:79]
	ds_read_b128 v[96:99], v150 offset:33024
	ds_read_b128 v[100:103], v150 offset:45312
	ds_read_b128 v[104:107], v171 offset:8192
	s_waitcnt lgkmcnt(0)
	v_mfma_f32_32x32x16_bf16 v[80:95], v[96:99], v[104:107], v[80:95]
	v_mfma_f32_32x32x16_bf16 v[64:79], v[100:103], v[104:107], v[64:79]
	s_cmp_lt_i32 s22, s54
	s_cselect_b64 s[20:21], -1, 0
	s_cmp_ge_i32 s22, s54
	s_cbranch_scc1 .LBB0_434
; __device__ __forceinline__ int v_rd_base(int lane) { return ((lane & 3) << 3) | (((lane >> 2) & 3) << 6) | (((lane >> 4) & 1) << 5) | (((lane >> 5) & 1) << 8); }
; #define V_COORDS(T) do { if constexpr (VC == 2) { const int sr = (T) >> 4, sc = ((T) & 15) * 8; vgo[0] = sr * LDV + sc; vgo[VC - 1] = (32 + sr) * LDV + sc; vlo[0] = v_st<NCB>(sr, sc); vlo[VC - 1] = v_st<NCB>(32 + sr, sc); } \
;     else { const int sr = (T) >> 3, sc = ((T) & 7) * 8; vgo[0] = sr * LDV + sc; vlo[0] = v_st<NCB>(sr, sc); } } while (0)
;     ...
;   if constexpr (KDMA) {
;   } else {
; #pragma unroll
;     for (int i = 0; i < KC; ++i) { const int c = tid + i * 512, row = c / CPR, cc = c % CPR; kgo[i] = row * LDK + cc * 8; klo[i] = K_OFF + KSWZ(KRS, row, cc * 16); }
;     V_COORDS(tid);
;   }
;   const int vb0 = (int)(uintptr_t)shm + v_rd_base(lane);
;   int kofs[4];
; #pragma unroll
;   for (int b = 0; b < 4; ++b) kofs[b] = (r32 ^ ((r32 >> 3) & 1)) * KRS + ((b * 32 + hi * 16) ^ ((r32 & 7) << 4));
;   bf16x8 ks[KC], vs[VC];
	v_mov_b32_e32 v97, v157
	s_add_i32 vcc_lo, s23, 0xc0
	v_mul_hi_i32 v99, v97, s82
	v_lshrrev_b32_e32 v100, 31, v99
	v_ashrrev_i32_e32 v99, 2, v99
	v_add_u32_e32 v99, v99, v100
	v_mul_lo_u32 v100, v99, 24
	v_lshrrev_b32_e32 v101, 3, v99
	v_sub_u32_e32 v100, v97, v100
	v_bitop3_b32 v99, v101, v99, 1 bitop3:0x6c
	v_bitop3_b32 v100, v99, v100, 7 bitop3:0x6c
	v_mul_lo_u32 v99, v99, s85
	v_lshl_add_u32 v100, v100, 3, v99
	v_add_u32_e32 v99, 0x200, v97
	v_mul_hi_i32 v101, v99, s82
	v_lshrrev_b32_e32 v102, 31, v101
	v_ashrrev_i32_e32 v101, 2, v101
	v_add_u32_e32 v101, v101, v102
	v_mul_lo_u32 v102, v101, 24
	v_sub_u32_e32 v99, v99, v102
	v_lshrrev_b32_e32 v102, 3, v101
	v_bitop3_b32 v101, v102, v101, 1 bitop3:0x6c
	v_lshlrev_b32_e32 v96, 3, v97
	v_lshlrev_b32_e32 v98, 5, v97
	v_bitop3_b32 v99, v101, v99, 7 bitop3:0x6c
	v_mul_lo_u32 v101, v101, s85
	v_add_u32_e32 v97, 0x400, v97
	v_lshl_add_u32 v102, v99, 3, v101
	v_mul_hi_i32 v99, v97, s82
	v_lshrrev_b32_e32 v101, 31, v99
	v_ashrrev_i32_e32 v99, 2, v99
	v_add_u32_e32 v99, v99, v101
	v_mul_lo_u32 v101, v99, 24
	v_sub_u32_e32 v97, v97, v101
	v_lshrrev_b32_e32 v101, 3, v99
	v_bitop3_b32 v99, v101, v99, 1 bitop3:0x6c
	s_ashr_i32 vcc_hi, vcc_lo, 31
	s_mul_i32 s38, vcc_lo, 0x600
	v_bitop3_b32 v97, v99, v97, 7 bitop3:0x6c
	v_mul_lo_u32 v99, v99, s85
	s_mul_hi_i32 s23, vcc_lo, 0x600
	s_add_u32 s38, s3, s38
	v_lshl_add_u32 v104, v97, 3, v99
	s_addc_u32 s39, s36, s23
	v_ashrrev_i32_e32 v101, 31, v100
	v_readfirstlane_b32 s23, v167
	v_add_u32_e32 v97, 0x2000, v167
	v_lshl_add_u64 v[100:101], v[100:101], 1, s[38:39]
	s_mov_b32 m0, s23
	v_ashrrev_i32_e32 v103, 31, v102
	v_readfirstlane_b32 s23, v97
	global_load_lds_dwordx4 v[100:101], off
	v_lshl_add_u64 v[100:101], v[102:103], 1, s[38:39]
	s_mov_b32 m0, s23
	v_ashrrev_i32_e32 v105, 31, v104
	v_and_b32_e32 v96, 0x78, v96
	global_load_lds_dwordx4 v[100:101], off
	v_lshl_add_u64 v[100:101], v[104:105], 1, s[38:39]
	v_add_u32_e32 v97, 0x4000, v167
	s_lshl_b64 s[38:39], vcc, 10
	v_and_or_b32 v96, v98, s24, v96
	v_readfirstlane_b32 s23, v97
	s_add_u32 s38, s83, s38
	v_add_u32_e32 v98, 0x4000, v96
	s_mov_b32 m0, s23
	s_addc_u32 s39, s93, s39
	v_ashrrev_i32_e32 v97, 31, v96
	global_load_lds_dwordx4 v[100:101], off
	v_lshl_add_u64 v[96:97], v[96:97], 1, s[38:39]
	v_ashrrev_i32_e32 v99, 31, v98
	v_lshl_add_u64 v[98:99], v[98:99], 1, s[38:39]
	global_load_dwordx4 v[130:133], v[96:97], off
	global_load_dwordx4 v[124:127], v[98:99], off

; __device__ __forceinline__ void finishSM(f32x16& p0, f32x16& p1, float& l_reg, bf16x8& pa0, bf16x8& pa1, bf16x8& pa2, bf16x8& pa3) {
; #pragma unroll
;   for (int r = 0; r < 16; ++r) p1[r] = __builtin_amdgcn_exp2f(p1[r]);
;   float ps = 0;
; #pragma unroll
;   for (int r = 0; r < 16; ++r) ps += p0[r];
; #pragma unroll
;   for (int r = 0; r < 16; ++r) ps += p1[r];
;   { auto rr = __builtin_amdgcn_permlane32_swap(__float_as_uint(ps), __float_as_uint(ps), false, false);
;     ps = __uint_as_float(rr[0]) + __uint_as_float(rr[1]); }
;   l_reg += ps;
;     ...
;   PK4(p0, 0, pa0); PK4(p0, 8, pa1); PK4(p1, 0, pa2); PK4(p1, 8, pa3);
;     ...
; }
; template <int DQK, int QL>
; __device__ __forceinline__ void qkt(f32x16& p0, f32x16& p1, const char* Ks, const bf16x8 (&qr)[DQK / 16 - QL], const char* qlds, const int (&kofs)[4], float negM) {
;   constexpr int QR = DQK / 16 - QL;
; #pragma unroll
;   for (int r = 0; r < 16; ++r) { p0[r] = negM; p1[r] = negM; }
; #pragma unroll
;   for (int d0 = 0; d0 < DQK / 16; ++d0) {
;     const char* kp = Ks + kofs[d0 & 3] + (d0 >> 2) * 128;
;     bf16x8 b0 = *reinterpret_cast<const bf16x8*>(kp);
;     bf16x8 b1 = *reinterpret_cast<const bf16x8*>(kp + 32 * DQK * 2);
;     bf16x8 qf;
;     if constexpr (QL > 0) { if (d0 < QR) qf = qr[d0 < QR ? d0 : 0]; else qf = *reinterpret_cast<const bf16x8*>(qlds + (d0 - QR) * 1024); }
;     else qf = qr[d0];
;     p0 = __builtin_amdgcn_mfma_f32_32x32x16_bf16(b0, qf, p0, 0, 0, 0);
;     p1 = __builtin_amdgcn_mfma_f32_32x32x16_bf16(b1, qf, p1, 0, 0, 0);
;   }
; }
; template <int NCB> __device__ __forceinline__ int v_st(int k, int c) {
;   const int kk = (k & ~0xC) | ((k & 4) << 1) | ((k & 8) >> 1);
;   return ((kk >> 3) * NCB + (c >> 5)) * 512 + ((kk & 7) * 32 + (c & 31)) * 2;
; }
; __device__ __forceinline__ int v_rd_base(int lane) { return ((lane & 3) << 3) | (((lane >> 2) & 3) << 6) | (((lane >> 4) & 1) << 5) | (((lane >> 5) & 1) << 8); }
; template <int OFF> __device__ __forceinline__ s16x4 tr_read(int vb) {
;   s16x4 r; asm volatile("ds_read_b64_tr_b16 %0, %1 offset:%2" : "=&v"(r) : "v"(vb), "i"(OFF) : "memory"); return r;
; }
; template <int NCB, int D0> __device__ __forceinline__ void pv_one(f32x16& od, int vb, bf16x8 pa0, bf16x8 pa1, bf16x8 pa2, bf16x8 pa3) {
;   constexpr int KSTEP = NCB * 1024, HALF = NCB * 512, B0 = D0 * 512;
.LBB0_650:
	ds_read_b128 v[40:43], v150 offset:40960
	ds_read_b128 v[158:161], v150 offset:45056
	s_waitcnt vmcnt(0)
	v_mov_b64_e32 v[110:111], s[18:19]
	v_mov_b64_e32 v[108:109], s[16:17]
	v_mov_b64_e32 v[106:107], s[14:15]
	v_mov_b64_e32 v[104:105], s[12:13]
	v_mov_b64_e32 v[102:103], s[10:11]
	v_mov_b64_e32 v[100:101], s[8:9]
	v_mov_b64_e32 v[98:99], s[6:7]
	v_mov_b64_e32 v[96:97], s[4:5]
	s_waitcnt lgkmcnt(1)
	s_nop 0
	v_mfma_f32_32x32x16_bf16 v[56:71], v[40:43], v[124:127], v[96:111]
	s_waitcnt lgkmcnt(0)
	v_mfma_f32_32x32x16_bf16 v[40:55], v[158:161], v[124:127], v[96:111]
	s_nop 6
	ds_read_b128 v[96:99], v148 offset:40960
	ds_read_b128 v[100:103], v148 offset:45056
	s_waitcnt lgkmcnt(1)
	v_mfma_f32_32x32x16_bf16 v[56:71], v[96:99], v[120:123], v[56:71]
	s_waitcnt lgkmcnt(0)
	v_mfma_f32_32x32x16_bf16 v[40:55], v[100:103], v[120:123], v[40:55]
	ds_read_b128 v[96:99], v147 offset:40960
	ds_read_b128 v[100:103], v147 offset:45056
	s_waitcnt lgkmcnt(1)
	v_mfma_f32_32x32x16_bf16 v[56:71], v[96:99], v[116:119], v[56:71]
	s_waitcnt lgkmcnt(0)
	v_mfma_f32_32x32x16_bf16 v[40:55], v[100:103], v[116:119], v[40:55]
	ds_read_b128 v[96:99], v146 offset:40960
	ds_read_b128 v[100:103], v146 offset:45056
	s_waitcnt lgkmcnt(1)
	v_mfma_f32_32x32x16_bf16 v[56:71], v[96:99], v[112:115], v[56:71]
	v_exp_f32_e32 v96, v32
	v_add_f32_e32 v32, 0, v90
	v_add_f32_e32 v32, v88, v32
	v_add_f32_e32 v104, v91, v87
	v_add_f32_e32 v32, v86, v32
	v_add_f32_e32 v104, v85, v104
	v_add_f32_e32 v32, v82, v32
	v_add_f32_e32 v104, v81, v104
	v_add_f32_e32 v32, v74, v32
	v_add_f32_e32 v104, v75, v104
	v_add_f32_e32 v32, v76, v32
	v_add_f32_e32 v104, v77, v104
	v_add_f32_e32 v32, v78, v32
	v_exp_f32_e32 v97, v33
	v_add_f32_e32 v104, v79, v104
	v_exp_f32_e32 v98, v34
	v_add_f32_e32 v32, v80, v32
	v_exp_f32_e32 v99, v35
	v_add_f32_e32 v104, v83, v104
	s_waitcnt lgkmcnt(0)
	v_mfma_f32_32x32x16_bf16 v[40:55], v[100:103], v[112:115], v[40:55]
	v_exp_f32_e32 v100, v36
	v_add_f32_e32 v32, v96, v32
	v_exp_f32_e32 v101, v37
	v_add_f32_e32 v104, v97, v104
	v_exp_f32_e32 v102, v38
	v_add_f32_e32 v32, v98, v32
	v_exp_f32_e32 v103, v39
	v_add_f32_e32 v104, v99, v104
	v_exp_f32_e32 v36, v72
	v_add_f32_e32 v32, v100, v32
	v_exp_f32_e32 v37, v73
	v_add_f32_e32 v104, v101, v104
	v_exp_f32_e32 v38, v84
	v_add_f32_e32 v32, v102, v32
	v_exp_f32_e32 v39, v89
	v_add_f32_e32 v104, v103, v104
	v_exp_f32_e32 v72, v92
	v_add_f32_e32 v32, v36, v32
	v_exp_f32_e32 v73, v93
	v_add_f32_e32 v104, v37, v104
	v_exp_f32_e32 v84, v94
	v_add_f32_e32 v32, v38, v32
	v_exp_f32_e32 v89, v95
	v_add_f32_e32 v104, v39, v104
	v_add_f32_e32 v32, v72, v32
	v_add_f32_e32 v104, v73, v104
	v_add_f32_e32 v32, v84, v32
	v_add_f32_e32 v104, v89, v104
	v_add_f32_e32 v104, v32, v104
	v_mov_b32_e32 v105, v104
	v_cvt_pk_bf16_f32 v32, v90, v91
	v_cvt_pk_bf16_f32 v33, v88, v87
	v_cvt_pk_bf16_f32 v34, v86, v85
	v_cvt_pk_bf16_f32 v35, v82, v81
	s_nop 1
	v_permlane32_swap_b32_e32 v104, v105
	v_permlane32_swap_b32_e32 v32, v34
	v_permlane32_swap_b32_e32 v33, v35
	v_cvt_pk_bf16_f32 v74, v74, v75
	v_cvt_pk_bf16_f32 v75, v76, v77
	v_cvt_pk_bf16_f32 v76, v78, v79
	v_cvt_pk_bf16_f32 v77, v80, v83
	v_cvt_pk_bf16_f32 v78, v96, v97
	v_cvt_pk_bf16_f32 v79, v98, v99
	v_cvt_pk_bf16_f32 v80, v100, v101
	v_cvt_pk_bf16_f32 v81, v102, v103
	v_cvt_pk_bf16_f32 v36, v36, v37
	v_cvt_pk_bf16_f32 v37, v38, v39
	v_cvt_pk_bf16_f32 v38, v72, v73
	v_cvt_pk_bf16_f32 v39, v84, v89
	s_nop 0
	v_permlane32_swap_b32_e32 v74, v76
	v_permlane32_swap_b32_e32 v75, v77
	v_permlane32_swap_b32_e32 v78, v80
	v_permlane32_swap_b32_e32 v79, v81
	v_permlane32_swap_b32_e32 v36, v38
	v_permlane32_swap_b32_e32 v37, v39
	v_mad_i64_i32 v[72:73], s[20:21], s97, v237, v[134:135]
	v_mad_i64_i32 v[82:83], s[20:21], s97, v237, v[136:137]
	global_load_dwordx4 v[96:99], v[72:73], off offset:1024
	global_load_dwordx4 v[100:103], v[82:83], off offset:1280
	ds_read_b64_tr_b16 v[82:83], v156 offset:0
	ds_read_b64_tr_b16 v[84:85], v156 offset:0x400
	ds_read_b64_tr_b16 v[86:87], v156 offset:0x800
	ds_read_b64_tr_b16 v[88:89], v156 offset:0xc00
	ds_read_b64_tr_b16 v[90:91], v156 offset:0x1000
	ds_read_b64_tr_b16 v[92:93], v156 offset:0x1400
	ds_read_b64_tr_b16 v[106:107], v156 offset:0x1800
	ds_read_b64_tr_b16 v[108:109], v156 offset:0x1c00
	s_nop 0
	s_waitcnt lgkmcnt(6)
	v_mfma_f32_32x32x16_bf16 v[0:15], v[32:35], v[82:85], v[0:15]
	ds_read_b64_tr_b16 v[82:83], v156 offset:0x200
	ds_read_b64_tr_b16 v[84:85], v156 offset:0x600
	s_waitcnt lgkmcnt(6)
	v_mfma_f32_32x32x16_bf16 v[0:15], v[74:77], v[86:89], v[0:15]
	ds_read_b64_tr_b16 v[86:87], v156 offset:0xa00
	ds_read_b64_tr_b16 v[88:89], v156 offset:0xe00
	s_waitcnt lgkmcnt(6)
	v_mfma_f32_32x32x16_bf16 v[0:15], v[78:81], v[90:93], v[0:15]
	ds_read_b64_tr_b16 v[90:91], v156 offset:0x1200
	ds_read_b64_tr_b16 v[92:93], v156 offset:0x1600
	s_waitcnt lgkmcnt(6)
	v_mfma_f32_32x32x16_bf16 v[0:15], v[36:39], v[106:109], v[0:15]
	ds_read_b64_tr_b16 v[106:107], v156 offset:0x1a00
	ds_read_b64_tr_b16 v[108:109], v156 offset:0x1e00
	s_waitcnt lgkmcnt(6)
	v_mfma_f32_32x32x16_bf16 v[16:31], v[32:35], v[82:85], v[16:31]
	v_add_u32_e32 v82, s97, v151
	v_subrev_u32_e32 v34, 64, v82
	v_mov_b32_e32 v32, 0xf149f2ca
	v_cmp_gt_i32_e32 vcc, s94, v34
	v_mov_b32_e32 v33, 0xf149f2ca
	s_waitcnt lgkmcnt(4)
	v_mfma_f32_32x32x16_bf16 v[16:31], v[74:77], v[86:89], v[16:31]
	s_waitcnt lgkmcnt(2)
	v_mfma_f32_32x32x16_bf16 v[16:31], v[78:81], v[90:93], v[16:31]
	s_waitcnt lgkmcnt(0)
	v_mfma_f32_32x32x16_bf16 v[16:31], v[36:39], v[106:109], v[16:31]
	v_readfirstlane_b32 s100, v34
	v_readfirstlane_b32 s101, v145
	s_nop 0
	s_add_i32 s98, s100, 0x61
	s_cmp_ge_i32 s98, s101
	s_cbranch_scc0 .Lgq_slow_1
	s_add_i32 s98, s101, 0x41
	s_cmp_le_i32 s100, s98
	s_cbranch_scc0 .Lgq_slow_1
	s_add_i32 s98, s100, 64
	s_cmp_le_i32 s98, s94
	s_cbranch_scc0 .Lgq_slow_1
	v_mov_b32_e32 v33, v56
	v_mov_b32_e32 v32, v40
	v_mov_b32_e32 v34, v57
	v_mov_b32_e32 v83, v41
	v_mov_b32_e32 v35, v58
	v_mov_b32_e32 v84, v42
	v_mov_b32_e32 v36, v59
	v_mov_b32_e32 v85, v43
	v_mov_b32_e32 v37, v60
	v_mov_b32_e32 v86, v44
	v_mov_b32_e32 v38, v61
	v_mov_b32_e32 v87, v45
	v_mov_b32_e32 v39, v62
	v_mov_b32_e32 v88, v46
	v_mov_b32_e32 v40, v63
	v_mov_b32_e32 v89, v47
	v_mov_b32_e32 v41, v64
	v_mov_b32_e32 v90, v48
	v_mov_b32_e32 v42, v65
	v_mov_b32_e32 v91, v49
	v_mov_b32_e32 v43, v66
	v_mov_b32_e32 v92, v50
	v_mov_b32_e32 v44, v67
	v_mov_b32_e32 v93, v51
	v_mov_b32_e32 v45, v68
	v_mov_b32_e32 v94, v52
	v_mov_b32_e32 v46, v69
	v_mov_b32_e32 v95, v53
	v_mov_b32_e32 v47, v70
	v_mov_b32_e32 v106, v54
	v_mov_b32_e32 v48, v71
	v_mov_b32_e32 v107, v55
	s_branch .Lgq_end_1
